# lever 4, one static priority raise: the trailing wave group (wr==1) runs every GEMM phase at s_setprio 1, all per-segment s_setprio toggling in the five K-loops and the epilogue prio-3 raise removed
# speedup vs baseline: 1.0064x; 1.0064x over previous
; #define PG8_STAGE(bufoff, gbase, voff) do { _Pragma("unroll") for (int _i = 0; _i < 2; ++_i) \
;         __builtin_amdgcn_global_load_lds((const __attribute__((address_space(1))) unsigned*)((const char*)(gbase) + (voff)[_i]), (LAS unsigned*)(lds + (bufoff) + ldsw + _i * 8192), 16, 0, 0); } while (0)
; #define PG8_WAIT_V(n) asm volatile("s_waitcnt vmcnt(" #n ")" ::: "memory")
; #define PG8_BAR __builtin_amdgcn_s_barrier()
; template <class Epi, class SchedT, bool ALIGN_EPI, bool SP2>
; __device__ __forceinline__ void gemm_phase(LAS unsigned char* lds, const int ldk, const int nt, const SchedT& S, const Epi& E) {
;     ...
;     for (int i = 0; i < 2; ++i) { int R, C; stage_rc(tid * 16 + i * 8192, R, C); const int Rb = 2 * (R & ~31) + perm32(R & 31);
;         voffA[i] = (unsigned)(R * K + C) * 2u; voffB[i] = (unsigned)(Rb * K + C) * 2u; }
;     const size_t kstep = (size_t)(BK * 2);
;     const size_t hstep = (size_t)HALF * K * 2;
;     const size_t hstepB = (size_t)32 * K * 2;
;     const unsigned ldsw = (unsigned)wid * 1024u;
;     const int aoff = lds_byte(wr * 64 + fr, fq * 8), boff = lds_byte(wc * 32 + fr, fq * 8);
;     ...
;     if constexpr (SP2) {
;         PG8_STAGE(PG8_SB(0, 0), cB, voffB); PG8_STAGE(PG8_SB(0, 1), cB + hstepB, voffB); PG8_STAGE(PG8_SA(0, 0), cA, voffA); PG8_STAGE(PG8_SA(0, 1), cA + hstep, voffA);
;         if (wr == 1) PG8_BAR;
;         PG8_WAIT_V(2); PG8_BAR;
.LBB0_112:
	s_mul_i32 s12, s16, 0x7500000
	v_writelane_b32 v163, s12, 36
	s_lshl_b32 s12, s16, 19
	s_mov_b32 s13, s23
	v_writelane_b32 v163, s12, 37
	s_mov_b32 s17, s23
	s_and_b64 vcc, exec, s[0:1]
	v_writelane_b32 v163, s13, 38
	v_writelane_b32 v163, s16, 39
	s_lshl_b64 s[0:1], s[16:17], 17
	s_nop 0
	v_writelane_b32 v163, s17, 40
	v_writelane_b32 v163, s0, 41
	s_nop 1
	v_writelane_b32 v163, s1, 42
	s_cbranch_vccnz .LBB0_358
	v_ashrrev_i32_e32 v3, 31, v0
	v_lshrrev_b32_e32 v3, 26, v3
	v_add_u32_e32 v3, v0, v3
	v_ashrrev_i32_e32 v10, 6, v3
	v_bfe_i32 v3, v0, 27, 1
	v_lshlrev_b32_e32 v2, 4, v0
	v_lshrrev_b32_e32 v3, 22, v3
	v_add_u32_e32 v3, v2, v3
	v_and_b32_e32 v3, 0xfffffc00, v3
	v_sub_u32_e32 v3, v2, v3
	v_lshrrev_b32_e32 v4, 4, v3
	v_bitop3_b32 v3, v4, v3, 32 bitop3:0x6c
	v_ashrrev_i32_e32 v5, 31, v3
	v_lshrrev_b32_e32 v5, 26, v5
	v_add_u32_e32 v5, v3, v5
	v_lshlrev_b32_e32 v4, 3, v10
	v_ashrrev_i32_e32 v11, 6, v5
	v_and_b32_e32 v5, 0xc0, v5
	v_and_b32_e32 v4, -16, v4
	v_sub_u32_e32 v3, v3, v5
	v_add_u32_e32 v4, v11, v4
	v_ashrrev_i16_sdwa v3, v244, sext(v3) dst_sel:DWORD dst_unused:UNUSED_PAD src0_sel:DWORD src1_sel:BYTE_0
	v_readlane_b32 s0, v163, 39
	v_lshlrev_b32_e32 v6, 5, v10
	v_bfe_i32 v12, v3, 0, 16
	v_lshlrev_b32_e32 v3, 1, v4
	v_lshrrev_b32_e32 v5, 2, v4
	s_mul_i32 s0, s0, 0x7500000
	v_and_b32_e32 v6, 32, v6
	v_and_b32_e32 v5, 4, v5
	v_and_b32_e32 v7, 3, v11
	v_and_b32_e32 v3, 0xfffd8, v3
	v_readlane_b32 s1, v163, 40
	s_add_u32 s0, s44, s0
	v_or3_b32 v3, v7, v5, v3
	v_add_lshl_u32 v5, v6, v12, 1
	v_add_u32_e32 v2, 0x2000, v2
	s_addc_u32 s1, s45, 0
	v_lshl_add_u32 v158, v3, 12, v5
	v_ashrrev_i32_e32 v3, 31, v2
	s_add_u32 s22, s0, 0x200000
	v_lshrrev_b32_e32 v3, 22, v3
	s_addc_u32 s84, s1, 0
	v_add_u32_e32 v3, v2, v3
	s_add_u32 s85, s44, 0xec00000
	v_ashrrev_i32_e32 v13, 10, v3
	s_addc_u32 s86, s45, 0
	s_ashr_i32 s0, s18, 6
	v_mul_i32_i24_e32 v3, 0x400, v13
	v_sub_u32_e32 v2, v2, v3
	s_ashr_i32 s94, s18, 8
	s_lshl_b32 s87, s0, 10
	v_lshrrev_b32_e32 v3, 4, v2
	s_cmp_eq_u32 s20, 0
	v_bitop3_b32 v2, v3, v2, 32 bitop3:0x6c
	s_cselect_b32 s12, s82, s51
	v_lshl_add_u32 v156, v4, 12, v5
	v_ashrrev_i32_e32 v4, 31, v2
	s_cselect_b32 s1, s86, s84
	s_cselect_b32 s17, s85, s22
	s_cselect_b32 s16, s51, s82
	s_cselect_b32 s19, s84, s86
	s_cselect_b32 s21, s22, s85
	s_ashr_i32 s13, s12, 31
	v_lshrrev_b32_e32 v4, 26, v4
	s_lshl_b64 s[12:13], s[12:13], 20
	v_add_u32_e32 v4, v2, v4
	s_add_u32 s12, s17, s12
	v_lshlrev_b32_e32 v3, 3, v13
	v_ashrrev_i32_e32 v14, 6, v4
	v_and_b32_e32 v4, 0xc0, v4
	s_addc_u32 s13, s1, s13
	s_ashr_i32 s17, s16, 31
	v_and_b32_e32 v3, -16, v3
	v_sub_u32_e32 v2, v2, v4
	s_lshl_b64 s[16:17], s[16:17], 20
	v_add_u32_e32 v3, v14, v3
	v_ashrrev_i16_sdwa v2, v244, sext(v2) dst_sel:DWORD dst_unused:UNUSED_PAD src0_sel:DWORD src1_sel:BYTE_0
	s_add_u32 s16, s21, s16
	v_lshlrev_b32_e32 v5, 5, v13
	v_bfe_i32 v15, v2, 0, 16
	v_lshlrev_b32_e32 v2, 1, v3
	v_lshrrev_b32_e32 v4, 2, v3
	s_addc_u32 s17, s19, s17
	s_add_i32 s88, s87, 0
	v_and_b32_e32 v5, 32, v5
	v_and_b32_e32 v4, 4, v4
	v_and_b32_e32 v6, 3, v14
	v_and_b32_e32 v2, 0xfffd8, v2
	s_add_i32 m0, s88, 0x10000
	v_or3_b32 v2, v6, v4, v2
	v_add_lshl_u32 v4, v5, v15, 1
	global_load_lds_dwordx4 v158, s[16:17]
	s_add_i32 m0, s88, 0x12000
	v_lshl_add_u32 v174, v2, 12, v4
	s_add_u32 s30, s16, 0x20000
	global_load_lds_dwordx4 v174, s[16:17]
	s_addc_u32 s31, s17, 0
	s_add_i32 m0, s88, 0x14000
	s_add_i32 s89, s88, 0x2000
	global_load_lds_dwordx4 v158, s[30:31]
	s_add_i32 m0, s88, 0x16000
	v_lshl_add_u32 v160, v3, 12, v4
	global_load_lds_dwordx4 v174, s[30:31]
	s_mov_b32 m0, s88
	s_add_u32 s30, s12, 0x80000
	global_load_lds_dwordx4 v156, s[12:13]
	s_mov_b32 m0, s89
	s_addc_u32 s31, s13, 0
	s_add_i32 s90, s88, 0x4000
	global_load_lds_dwordx4 v160, s[12:13]
	s_mov_b32 m0, s90
	s_add_i32 s91, s88, 0x6000
	global_load_lds_dwordx4 v156, s[30:31]
	s_mov_b32 m0, s91
	v_mov_b32_e32 v159, v1
	global_load_lds_dwordx4 v160, s[30:31]
	v_mov_b32_e32 v175, v1
	v_mov_b32_e32 v157, v1
	v_mov_b32_e32 v161, v1
	s_cmp_eq_u32 s94, 1
	v_lshl_add_u64 v[8:9], s[16:17], 0, v[158:159]
	v_lshl_add_u64 v[6:7], s[16:17], 0, v[174:175]
	v_lshl_add_u64 v[2:3], s[12:13], 0, v[156:157]
	s_cselect_b64 s[46:47], -1, 0
	s_cmp_lg_u32 s94, 1
	v_lshl_add_u64 v[4:5], s[12:13], 0, v[160:161]
	s_cbranch_scc1 .LBB0_115
	s_barrier
	s_setprio 1

; #define PG8_STAGE(bufoff, gbase, voff) do { _Pragma("unroll") for (int _i = 0; _i < 2; ++_i) \
;         __builtin_amdgcn_global_load_lds((const __attribute__((address_space(1))) unsigned*)((const char*)(gbase) + (voff)[_i]), (LAS unsigned*)(lds + (bufoff) + ldsw + _i * 8192), 16, 0, 0); } while (0)
; #define PG8_LDA(dst, b, h) do { _Pragma("unroll") for (int m = 0; m < 4; ++m) _Pragma("unroll") for (int k = 0; k < 2; ++k) dst[m][k] = *(const LAS bf16x8*)(lds + PG8_SA(b, h) + aoff + m * 2048 + k * 1024); } while (0)
; #define PG8_LDB(dst, b, h) do { _Pragma("unroll") for (int n = 0; n < 2; ++n) _Pragma("unroll") for (int k = 0; k < 2; ++k) dst[n][k] = *(const LAS bf16x8*)(lds + PG8_SB(b, h) + boff + n * 2048 + k * 1024); } while (0)
; #define PG8_MMA(ai, bj, At, Bt) do { __builtin_amdgcn_s_setprio(1); _Pragma("unroll") for (int m = 0; m < 4; ++m) _Pragma("unroll") for (int n = 0; n < 2; ++n) _Pragma("unroll") for (int k = 0; k < 2; ++k) \
;         acc[ai][bj][m][n] = __builtin_amdgcn_mfma_f32_16x16x32_bf16(Bt[n][k], At[m][k], acc[ai][bj][m][n], 0, 0, 0); __builtin_amdgcn_s_setprio(0); } while (0)
; #define PG8_WAIT_V(n) asm volatile("s_waitcnt vmcnt(" #n ")" ::: "memory")
; #define PG8_WAIT_L(n) asm volatile("s_waitcnt lgkmcnt(" #n ")" ::: "memory")
; #define PG8_BAR __builtin_amdgcn_s_barrier()
; #define PG8_SCHED __builtin_amdgcn_sched_barrier(0)
; template <class Epi, class SchedT, bool ALIGN_EPI, bool SP2>
; __device__ __forceinline__ void gemm_phase(LAS unsigned char* lds, const int ldk, const int nt, const SchedT& S, const Epi& E) {
;     ...
;             PG8_LDB(B0, 0, 0); PG8_LDB(B1, 0, 1); PG8_SCHED; PG8_LDA(At, 0, 0); PG8_STAGE(PG8_SA(1, 1), a1 + hstep, voffA);
;             PG8_WAIT_V(8); PG8_WAIT_L(0); PG8_BAR; PG8_MMA(0, 0, At, B0); PG8_MMA(0, 1, At, B1); PG8_BAR; PG8_SCHED;
;             PG8_LDA(At, 0, 1); PG8_STAGE(PG8_SB(0, 0), b2, voffB); PG8_STAGE(PG8_SB(0, 1), b2 + hstepB, voffB); PG8_STAGE(PG8_SA(0, 0), a2, voffA);
;             PG8_WAIT_V(8); PG8_WAIT_L(0); PG8_BAR; PG8_MMA(1, 0, At, B0); PG8_MMA(1, 1, At, B1); PG8_BAR; PG8_SCHED;
.LBB0_123:
	s_add_u32 s12, s0, 0xfff80080
	s_addc_u32 s13, s1, -1
	s_add_i32 s34, 0, 0x10000
	s_cmp_eq_u32 s21, 28
	s_cselect_b32 s17, s61, s13
	s_cselect_b32 s16, s60, s12
	v_add_u32_e32 v0, s34, v212
	s_cselect_b32 s13, s31, s19
	s_cselect_b32 s12, s30, s18
	s_add_i32 s38, 0, 0x14000
	s_waitcnt lgkmcnt(0)
	ds_read_b128 v[132:135], v0
	ds_read_b128 v[136:139], v0 offset:1024
	ds_read_b128 v[140:143], v0 offset:2048
	ds_read_b128 v[144:147], v0 offset:3072
	v_add_u32_e32 v0, s38, v212
	ds_read_b128 v[148:151], v0
	ds_read_b128 v[152:155], v0 offset:1024
	ds_read_b128 v[184:187], v0 offset:2048
	ds_read_b128 v[188:191], v0 offset:3072
	v_lshl_add_u64 v[2:3], s[0:1], 0, v[180:181]
	s_add_i32 m0, s88, 0xc000
	ds_read_b128 v[192:195], v216
	ds_read_b128 v[196:199], v216 offset:1024
	ds_read_b128 v[200:203], v216 offset:2048
	ds_read_b128 v[204:207], v216 offset:3072
	ds_read_b128 v[218:221], v216 offset:4096
	ds_read_b128 v[222:225], v216 offset:5120
	ds_read_b128 v[226:229], v216 offset:6144
	ds_read_b128 v[230:233], v216 offset:7168
	global_load_lds_dwordx4 v[2:3], off
	v_lshl_add_u64 v[2:3], s[0:1], 0, v[182:183]
	s_add_i32 m0, s88, 0xe000
	s_nop 0
	global_load_lds_dwordx4 v[2:3], off
	s_waitcnt vmcnt(8)
	s_waitcnt lgkmcnt(0)
	s_barrier
	s_waitcnt lgkmcnt(0)
	v_mfma_f32_16x16x32_bf16 v[128:131], v[132:135], v[192:195], v[128:131]
	v_mfma_f32_16x16x32_bf16 v[124:127], v[140:143], v[192:195], v[124:127]
	v_mfma_f32_16x16x32_bf16 v[112:115], v[132:135], v[200:203], v[112:115]
	v_mfma_f32_16x16x32_bf16 v[108:111], v[140:143], v[200:203], v[108:111]
	v_mfma_f32_16x16x32_bf16 v[96:99], v[132:135], v[218:221], v[96:99]
	v_mfma_f32_16x16x32_bf16 v[92:95], v[140:143], v[218:221], v[92:95]
	v_mfma_f32_16x16x32_bf16 v[80:83], v[132:135], v[226:229], v[80:83]
	v_mfma_f32_16x16x32_bf16 v[76:79], v[140:143], v[226:229], v[76:79]
	v_mfma_f32_16x16x32_bf16 v[128:131], v[136:139], v[196:199], v[128:131]
	v_mfma_f32_16x16x32_bf16 v[124:127], v[144:147], v[196:199], v[124:127]
	v_mfma_f32_16x16x32_bf16 v[112:115], v[136:139], v[204:207], v[112:115]
	v_mfma_f32_16x16x32_bf16 v[108:111], v[144:147], v[204:207], v[108:111]
	v_mfma_f32_16x16x32_bf16 v[96:99], v[136:139], v[222:225], v[96:99]
	v_mfma_f32_16x16x32_bf16 v[92:95], v[144:147], v[222:225], v[92:95]
	v_mfma_f32_16x16x32_bf16 v[80:83], v[136:139], v[230:233], v[80:83]
	v_mfma_f32_16x16x32_bf16 v[76:79], v[144:147], v[230:233], v[76:79]
	v_mfma_f32_16x16x32_bf16 v[120:123], v[148:151], v[192:195], v[120:123]
	v_mfma_f32_16x16x32_bf16 v[116:119], v[184:187], v[192:195], v[116:119]
	v_mfma_f32_16x16x32_bf16 v[104:107], v[148:151], v[200:203], v[104:107]
	v_mfma_f32_16x16x32_bf16 v[100:103], v[184:187], v[200:203], v[100:103]
	v_mfma_f32_16x16x32_bf16 v[88:91], v[148:151], v[218:221], v[88:91]
	v_mfma_f32_16x16x32_bf16 v[84:87], v[184:187], v[218:221], v[84:87]
	v_mfma_f32_16x16x32_bf16 v[72:75], v[148:151], v[226:229], v[72:75]
	v_mfma_f32_16x16x32_bf16 v[68:71], v[184:187], v[226:229], v[68:71]
	v_mfma_f32_16x16x32_bf16 v[120:123], v[152:155], v[196:199], v[120:123]
	v_mfma_f32_16x16x32_bf16 v[116:119], v[188:191], v[196:199], v[116:119]
	v_mfma_f32_16x16x32_bf16 v[104:107], v[152:155], v[204:207], v[104:107]
	v_mfma_f32_16x16x32_bf16 v[100:103], v[188:191], v[204:207], v[100:103]
	v_mfma_f32_16x16x32_bf16 v[88:91], v[152:155], v[222:225], v[88:91]
	v_mfma_f32_16x16x32_bf16 v[84:87], v[188:191], v[222:225], v[84:87]
	v_mfma_f32_16x16x32_bf16 v[72:75], v[152:155], v[230:233], v[72:75]
	v_mfma_f32_16x16x32_bf16 v[68:71], v[188:191], v[230:233], v[68:71]
	s_barrier
	s_add_i32 s34, s34, s87
	v_lshl_add_u64 v[208:209], s[12:13], 0, v[158:159]
	s_mov_b32 m0, s34
	ds_read_b128 v[192:195], v216 offset:16384
	ds_read_b128 v[196:199], v216 offset:17408
	ds_read_b128 v[200:203], v216 offset:18432
	ds_read_b128 v[204:207], v216 offset:19456
	ds_read_b128 v[218:221], v216 offset:20480
	ds_read_b128 v[222:225], v216 offset:21504
	ds_read_b128 v[226:229], v216 offset:22528
	ds_read_b128 v[230:233], v216 offset:23552
	global_load_lds_dwordx4 v[208:209], off
	s_add_i32 m0, s34, 0x2000
	s_add_u32 s34, s12, 0x20000
	v_lshl_add_u64 v[234:235], s[12:13], 0, v[174:175]
	s_addc_u32 s35, s13, 0
	s_add_i32 s38, s38, s87
	global_load_lds_dwordx4 v[234:235], off
	v_lshl_add_u64 v[2:3], s[34:35], 0, v[158:159]
	s_mov_b32 m0, s38
	v_lshl_add_u64 v[236:237], s[16:17], 0, v[156:157]
	global_load_lds_dwordx4 v[2:3], off
	v_lshl_add_u64 v[2:3], s[34:35], 0, v[174:175]
	s_add_i32 m0, s38, 0x2000
	v_lshl_add_u64 v[238:239], s[16:17], 0, v[160:161]
	global_load_lds_dwordx4 v[2:3], off
	s_mov_b32 m0, s88
	s_nop 0
	global_load_lds_dwordx4 v[236:237], off
	s_mov_b32 m0, s89
	s_nop 0
	global_load_lds_dwordx4 v[238:239], off
	s_waitcnt vmcnt(8)
	s_waitcnt lgkmcnt(0)
	s_barrier
; #define PG8_STAGE(bufoff, gbase, voff) do { _Pragma("unroll") for (int _i = 0; _i < 2; ++_i) \
;         __builtin_amdgcn_global_load_lds((const __attribute__((address_space(1))) unsigned*)((const char*)(gbase) + (voff)[_i]), (LAS unsigned*)(lds + (bufoff) + ldsw + _i * 8192), 16, 0, 0); } while (0)
; #define PG8_LDA(dst, b, h) do { _Pragma("unroll") for (int m = 0; m < 4; ++m) _Pragma("unroll") for (int k = 0; k < 2; ++k) dst[m][k] = *(const LAS bf16x8*)(lds + PG8_SA(b, h) + aoff + m * 2048 + k * 1024); } while (0)
; #define PG8_LDB(dst, b, h) do { _Pragma("unroll") for (int n = 0; n < 2; ++n) _Pragma("unroll") for (int k = 0; k < 2; ++k) dst[n][k] = *(const LAS bf16x8*)(lds + PG8_SB(b, h) + boff + n * 2048 + k * 1024); } while (0)
; #define PG8_MMA(ai, bj, At, Bt) do { __builtin_amdgcn_s_setprio(1); _Pragma("unroll") for (int m = 0; m < 4; ++m) _Pragma("unroll") for (int n = 0; n < 2; ++n) _Pragma("unroll") for (int k = 0; k < 2; ++k) \
;         acc[ai][bj][m][n] = __builtin_amdgcn_mfma_f32_16x16x32_bf16(Bt[n][k], At[m][k], acc[ai][bj][m][n], 0, 0, 0); __builtin_amdgcn_s_setprio(0); } while (0)
; #define PG8_WAIT_V(n) asm volatile("s_waitcnt vmcnt(" #n ")" ::: "memory")
; #define PG8_WAIT_L(n) asm volatile("s_waitcnt lgkmcnt(" #n ")" ::: "memory")
; #define PG8_BAR __builtin_amdgcn_s_barrier()
; #define PG8_SCHED __builtin_amdgcn_sched_barrier(0)
; template <class Epi, class SchedT, bool ALIGN_EPI, bool SP2>
; __device__ __forceinline__ void gemm_phase(LAS unsigned char* lds, const int ldk, const int nt, const SchedT& S, const Epi& E) {
;     ...
;             PG8_WAIT_V(8); PG8_WAIT_L(0); PG8_BAR; PG8_MMA(1, 0, At, B0); PG8_MMA(1, 1, At, B1); PG8_BAR; PG8_SCHED;
;             PG8_LDB(B0, 1, 0); PG8_LDB(B1, 1, 1); PG8_SCHED; PG8_LDA(At, 1, 0); PG8_STAGE(PG8_SA(0, 1), a2 + hstep, voffA);
;             PG8_WAIT_V(8); PG8_WAIT_L(0); PG8_BAR; PG8_MMA(0, 0, At, B0); PG8_MMA(0, 1, At, B1); PG8_BAR; PG8_SCHED;
	s_waitcnt lgkmcnt(0)
	v_mfma_f32_16x16x32_bf16 v[64:67], v[132:135], v[192:195], v[64:67]
	v_mfma_f32_16x16x32_bf16 v[60:63], v[140:143], v[192:195], v[60:63]
	v_mfma_f32_16x16x32_bf16 v[48:51], v[132:135], v[200:203], v[48:51]
	v_mfma_f32_16x16x32_bf16 v[44:47], v[140:143], v[200:203], v[44:47]
	v_mfma_f32_16x16x32_bf16 v[32:35], v[132:135], v[218:221], v[32:35]
	v_mfma_f32_16x16x32_bf16 v[28:31], v[140:143], v[218:221], v[28:31]
	v_mfma_f32_16x16x32_bf16 v[16:19], v[132:135], v[226:229], v[16:19]
	v_mfma_f32_16x16x32_bf16 v[12:15], v[140:143], v[226:229], v[12:15]
	v_mfma_f32_16x16x32_bf16 v[64:67], v[136:139], v[196:199], v[64:67]
	v_mfma_f32_16x16x32_bf16 v[60:63], v[144:147], v[196:199], v[60:63]
	v_mfma_f32_16x16x32_bf16 v[48:51], v[136:139], v[204:207], v[48:51]
	v_mfma_f32_16x16x32_bf16 v[44:47], v[144:147], v[204:207], v[44:47]
	v_mfma_f32_16x16x32_bf16 v[32:35], v[136:139], v[222:225], v[32:35]
	v_mfma_f32_16x16x32_bf16 v[28:31], v[144:147], v[222:225], v[28:31]
	v_mfma_f32_16x16x32_bf16 v[16:19], v[136:139], v[230:233], v[16:19]
	v_mfma_f32_16x16x32_bf16 v[12:15], v[144:147], v[230:233], v[12:15]
	v_mfma_f32_16x16x32_bf16 v[56:59], v[148:151], v[192:195], v[56:59]
	v_mfma_f32_16x16x32_bf16 v[52:55], v[184:187], v[192:195], v[52:55]
	v_mfma_f32_16x16x32_bf16 v[40:43], v[148:151], v[200:203], v[40:43]
	v_mfma_f32_16x16x32_bf16 v[36:39], v[184:187], v[200:203], v[36:39]
	v_mfma_f32_16x16x32_bf16 v[24:27], v[148:151], v[218:221], v[24:27]
	v_mfma_f32_16x16x32_bf16 v[20:23], v[184:187], v[218:221], v[20:23]
	v_mfma_f32_16x16x32_bf16 v[8:11], v[148:151], v[226:229], v[8:11]
	v_mfma_f32_16x16x32_bf16 v[2:5], v[184:187], v[226:229], v[4:7]
	v_mfma_f32_16x16x32_bf16 v[56:59], v[152:155], v[196:199], v[56:59]
	v_mfma_f32_16x16x32_bf16 v[52:55], v[188:191], v[196:199], v[52:55]
	v_mfma_f32_16x16x32_bf16 v[40:43], v[152:155], v[204:207], v[40:43]
	v_mfma_f32_16x16x32_bf16 v[36:39], v[188:191], v[204:207], v[36:39]
	v_mfma_f32_16x16x32_bf16 v[24:27], v[152:155], v[222:225], v[24:27]
	v_mfma_f32_16x16x32_bf16 v[20:23], v[188:191], v[222:225], v[20:23]
	v_mfma_f32_16x16x32_bf16 v[8:11], v[152:155], v[230:233], v[8:11]
	v_mfma_f32_16x16x32_bf16 v[2:5], v[188:191], v[230:233], v[2:5]
	s_barrier
	s_add_i32 s34, 0, 0x18000
	v_add_u32_e32 v0, s34, v212
	s_add_i32 s35, 0, 0x1c000
	ds_read_b128 v[132:135], v0
	ds_read_b128 v[136:139], v0 offset:1024
	ds_read_b128 v[140:143], v0 offset:2048
	ds_read_b128 v[144:147], v0 offset:3072
	v_add_u32_e32 v0, s35, v212
	ds_read_b128 v[148:151], v0
	ds_read_b128 v[152:155], v0 offset:1024
	ds_read_b128 v[184:187], v0 offset:2048
	ds_read_b128 v[188:191], v0 offset:3072
	s_add_u32 s16, s16, 0x80000
	s_addc_u32 s17, s17, 0
	s_mov_b32 m0, s90
	v_lshl_add_u64 v[6:7], s[16:17], 0, v[156:157]
	ds_read_b128 v[192:195], v216 offset:32768
	ds_read_b128 v[196:199], v216 offset:33792
	ds_read_b128 v[200:203], v216 offset:34816
	ds_read_b128 v[204:207], v216 offset:35840
	ds_read_b128 v[218:221], v216 offset:36864
	ds_read_b128 v[222:225], v216 offset:37888
	ds_read_b128 v[226:229], v216 offset:38912
	ds_read_b128 v[230:233], v216 offset:39936
	global_load_lds_dwordx4 v[6:7], off
	v_lshl_add_u64 v[6:7], s[16:17], 0, v[160:161]
	s_mov_b32 m0, s91
	s_nop 0
	global_load_lds_dwordx4 v[6:7], off
	s_waitcnt vmcnt(8)
	s_waitcnt lgkmcnt(0)
	s_barrier
	s_waitcnt lgkmcnt(0)
	v_mfma_f32_16x16x32_bf16 v[128:131], v[132:135], v[192:195], v[128:131]
	v_mfma_f32_16x16x32_bf16 v[124:127], v[140:143], v[192:195], v[124:127]
	v_mfma_f32_16x16x32_bf16 v[112:115], v[132:135], v[200:203], v[112:115]
	v_mfma_f32_16x16x32_bf16 v[108:111], v[140:143], v[200:203], v[108:111]
	v_mfma_f32_16x16x32_bf16 v[96:99], v[132:135], v[218:221], v[96:99]
	v_mfma_f32_16x16x32_bf16 v[92:95], v[140:143], v[218:221], v[92:95]
	v_mfma_f32_16x16x32_bf16 v[80:83], v[132:135], v[226:229], v[80:83]
	v_mfma_f32_16x16x32_bf16 v[76:79], v[140:143], v[226:229], v[76:79]
	v_mfma_f32_16x16x32_bf16 v[128:131], v[136:139], v[196:199], v[128:131]
	v_mfma_f32_16x16x32_bf16 v[124:127], v[144:147], v[196:199], v[124:127]
	v_mfma_f32_16x16x32_bf16 v[112:115], v[136:139], v[204:207], v[112:115]
	v_mfma_f32_16x16x32_bf16 v[108:111], v[144:147], v[204:207], v[108:111]
	v_mfma_f32_16x16x32_bf16 v[96:99], v[136:139], v[222:225], v[96:99]
	v_mfma_f32_16x16x32_bf16 v[92:95], v[144:147], v[222:225], v[92:95]
	v_mfma_f32_16x16x32_bf16 v[80:83], v[136:139], v[230:233], v[80:83]
	v_mfma_f32_16x16x32_bf16 v[76:79], v[144:147], v[230:233], v[76:79]
	v_mfma_f32_16x16x32_bf16 v[120:123], v[148:151], v[192:195], v[120:123]
	v_mfma_f32_16x16x32_bf16 v[116:119], v[184:187], v[192:195], v[116:119]
	v_mfma_f32_16x16x32_bf16 v[104:107], v[148:151], v[200:203], v[104:107]
	v_mfma_f32_16x16x32_bf16 v[100:103], v[184:187], v[200:203], v[100:103]
	v_mfma_f32_16x16x32_bf16 v[88:91], v[148:151], v[218:221], v[88:91]
	v_mfma_f32_16x16x32_bf16 v[84:87], v[184:187], v[218:221], v[84:87]
	v_mfma_f32_16x16x32_bf16 v[72:75], v[148:151], v[226:229], v[72:75]
	v_mfma_f32_16x16x32_bf16 v[68:71], v[184:187], v[226:229], v[68:71]
	v_mfma_f32_16x16x32_bf16 v[120:123], v[152:155], v[196:199], v[120:123]
	v_mfma_f32_16x16x32_bf16 v[116:119], v[188:191], v[196:199], v[116:119]
	v_mfma_f32_16x16x32_bf16 v[104:107], v[152:155], v[204:207], v[104:107]
	v_mfma_f32_16x16x32_bf16 v[100:103], v[188:191], v[204:207], v[100:103]
	v_mfma_f32_16x16x32_bf16 v[88:91], v[152:155], v[222:225], v[88:91]
	v_mfma_f32_16x16x32_bf16 v[84:87], v[188:191], v[222:225], v[84:87]
	v_mfma_f32_16x16x32_bf16 v[72:75], v[152:155], v[230:233], v[72:75]
	v_mfma_f32_16x16x32_bf16 v[68:71], v[188:191], v[230:233], v[68:71]
	s_barrier
; #define PG8_STAGE(bufoff, gbase, voff) do { _Pragma("unroll") for (int _i = 0; _i < 2; ++_i) \
;         __builtin_amdgcn_global_load_lds((const __attribute__((address_space(1))) unsigned*)((const char*)(gbase) + (voff)[_i]), (LAS unsigned*)(lds + (bufoff) + ldsw + _i * 8192), 16, 0, 0); } while (0)
; #define PG8_LDA(dst, b, h) do { _Pragma("unroll") for (int m = 0; m < 4; ++m) _Pragma("unroll") for (int k = 0; k < 2; ++k) dst[m][k] = *(const LAS bf16x8*)(lds + PG8_SA(b, h) + aoff + m * 2048 + k * 1024); } while (0)
; #define PG8_MMA(ai, bj, At, Bt) do { __builtin_amdgcn_s_setprio(1); _Pragma("unroll") for (int m = 0; m < 4; ++m) _Pragma("unroll") for (int n = 0; n < 2; ++n) _Pragma("unroll") for (int k = 0; k < 2; ++k) \
;         acc[ai][bj][m][n] = __builtin_amdgcn_mfma_f32_16x16x32_bf16(Bt[n][k], At[m][k], acc[ai][bj][m][n], 0, 0, 0); __builtin_amdgcn_s_setprio(0); } while (0)
; #define PG8_WAIT_V(n) asm volatile("s_waitcnt vmcnt(" #n ")" ::: "memory")
; #define PG8_WAIT_L(n) asm volatile("s_waitcnt lgkmcnt(" #n ")" ::: "memory")
; #define PG8_BAR __builtin_amdgcn_s_barrier()
; #define PG8_SCHED __builtin_amdgcn_sched_barrier(0)
; template <class Epi, class SchedT, bool ALIGN_EPI, bool SP2>
; __device__ __forceinline__ void gemm_phase(LAS unsigned char* lds, const int ldk, const int nt, const SchedT& S, const Epi& E) {
;     ...
;             PG8_LDA(At, 1, 1); PG8_STAGE(PG8_SB(1, 0), b3, voffB); PG8_STAGE(PG8_SB(1, 1), b3 + hstepB, voffB); PG8_STAGE(PG8_SA(1, 0), a3, voffA);
;             PG8_WAIT_V(8); PG8_WAIT_L(0); PG8_BAR; PG8_MMA(1, 0, At, B0); PG8_MMA(1, 1, At, B1); PG8_BAR; PG8_SCHED;
;     ...
;         if constexpr (ALIGN_EPI) { if (wr == 0) PG8_BAR; }
	s_add_i32 s16, s34, s87
	v_lshl_add_u64 v[6:7], v[208:209], 0, s[24:25]
	s_mov_b32 m0, s16
	ds_read_b128 v[192:195], v216 offset:49152
	ds_read_b128 v[196:199], v216 offset:50176
	ds_read_b128 v[200:203], v216 offset:51200
	ds_read_b128 v[204:207], v216 offset:52224
	ds_read_b128 v[218:221], v216 offset:53248
	ds_read_b128 v[222:225], v216 offset:54272
	ds_read_b128 v[226:229], v216 offset:55296
	ds_read_b128 v[230:233], v216 offset:56320
	global_load_lds_dwordx4 v[6:7], off
	s_add_i32 m0, s16, 0x2000
	s_add_u32 s12, s12, 0x20080
	v_lshl_add_u64 v[6:7], v[234:235], 0, s[24:25]
	s_addc_u32 s13, s13, 0
	s_add_i32 s16, s35, s87
	global_load_lds_dwordx4 v[6:7], off
	v_lshl_add_u64 v[6:7], s[12:13], 0, v[158:159]
	s_mov_b32 m0, s16
	s_nop 0
	global_load_lds_dwordx4 v[6:7], off
	v_lshl_add_u64 v[6:7], s[12:13], 0, v[174:175]
	s_add_i32 m0, s16, 0x2000
	s_nop 0
	global_load_lds_dwordx4 v[6:7], off
	v_lshl_add_u64 v[6:7], v[236:237], 0, s[24:25]
	s_mov_b32 m0, s92
	s_nop 0
	global_load_lds_dwordx4 v[6:7], off
	v_lshl_add_u64 v[6:7], v[238:239], 0, s[24:25]
	s_mov_b32 m0, s93
	s_nop 0
	global_load_lds_dwordx4 v[6:7], off
	s_waitcnt vmcnt(8)
	s_waitcnt lgkmcnt(0)
	s_barrier
	s_waitcnt lgkmcnt(0)
	v_mfma_f32_16x16x32_bf16 v[64:67], v[132:135], v[192:195], v[64:67]
	v_mfma_f32_16x16x32_bf16 v[60:63], v[140:143], v[192:195], v[60:63]
	v_mfma_f32_16x16x32_bf16 v[48:51], v[132:135], v[200:203], v[48:51]
	v_mfma_f32_16x16x32_bf16 v[44:47], v[140:143], v[200:203], v[44:47]
	v_mfma_f32_16x16x32_bf16 v[32:35], v[132:135], v[218:221], v[32:35]
	v_mfma_f32_16x16x32_bf16 v[28:31], v[140:143], v[218:221], v[28:31]
	v_mfma_f32_16x16x32_bf16 v[16:19], v[132:135], v[226:229], v[16:19]
	v_mfma_f32_16x16x32_bf16 v[12:15], v[140:143], v[226:229], v[12:15]
	v_mfma_f32_16x16x32_bf16 v[64:67], v[136:139], v[196:199], v[64:67]
	v_mfma_f32_16x16x32_bf16 v[60:63], v[144:147], v[196:199], v[60:63]
	v_mfma_f32_16x16x32_bf16 v[48:51], v[136:139], v[204:207], v[48:51]
	v_mfma_f32_16x16x32_bf16 v[44:47], v[144:147], v[204:207], v[44:47]
	v_mfma_f32_16x16x32_bf16 v[32:35], v[136:139], v[222:225], v[32:35]
	v_mfma_f32_16x16x32_bf16 v[28:31], v[144:147], v[222:225], v[28:31]
	v_mfma_f32_16x16x32_bf16 v[16:19], v[136:139], v[230:233], v[16:19]
	v_mfma_f32_16x16x32_bf16 v[12:15], v[144:147], v[230:233], v[12:15]
	v_mfma_f32_16x16x32_bf16 v[56:59], v[148:151], v[192:195], v[56:59]
	v_mfma_f32_16x16x32_bf16 v[52:55], v[184:187], v[192:195], v[52:55]
	v_mfma_f32_16x16x32_bf16 v[40:43], v[148:151], v[200:203], v[40:43]
	v_mfma_f32_16x16x32_bf16 v[36:39], v[184:187], v[200:203], v[36:39]
	v_mfma_f32_16x16x32_bf16 v[24:27], v[148:151], v[218:221], v[24:27]
	v_mfma_f32_16x16x32_bf16 v[20:23], v[184:187], v[218:221], v[20:23]
	v_mfma_f32_16x16x32_bf16 v[6:9], v[148:151], v[226:229], v[8:11]
	v_mfma_f32_16x16x32_bf16 v[2:5], v[184:187], v[226:229], v[2:5]
	v_mfma_f32_16x16x32_bf16 v[56:59], v[152:155], v[196:199], v[56:59]
	v_mfma_f32_16x16x32_bf16 v[52:55], v[188:191], v[196:199], v[52:55]
	v_mfma_f32_16x16x32_bf16 v[40:43], v[152:155], v[204:207], v[40:43]
	v_mfma_f32_16x16x32_bf16 v[36:39], v[188:191], v[204:207], v[36:39]
	v_mfma_f32_16x16x32_bf16 v[24:27], v[152:155], v[222:225], v[24:27]
	v_mfma_f32_16x16x32_bf16 v[20:23], v[188:191], v[222:225], v[20:23]
	v_mfma_f32_16x16x32_bf16 v[8:11], v[152:155], v[230:233], v[6:9]
	v_mfma_f32_16x16x32_bf16 v[4:7], v[188:191], v[230:233], v[2:5]
	s_barrier
	s_add_i32 s21, s21, 2
	s_add_u32 s0, s0, 0x100
	s_addc_u32 s1, s1, 0
	s_add_u32 s18, s18, 0x100
	s_addc_u32 s19, s19, 0
	s_cmp_gt_u32 s21, 29
	s_cbranch_scc0 .LBB0_123
	s_and_b64 vcc, exec, s[58:59]
	s_cbranch_vccz .LBB0_126
	s_barrier

; #define PG8_STAGE(bufoff, gbase, voff) do { _Pragma("unroll") for (int _i = 0; _i < 2; ++_i) \
;         __builtin_amdgcn_global_load_lds((const __attribute__((address_space(1))) unsigned*)((const char*)(gbase) + (voff)[_i]), (LAS unsigned*)(lds + (bufoff) + ldsw + _i * 8192), 16, 0, 0); } while (0)
; #define PG8_BAR __builtin_amdgcn_s_barrier()
; template <class Epi, class SchedT, bool ALIGN_EPI, bool SP2>
; __device__ __forceinline__ void gemm_phase(LAS unsigned char* lds, const int ldk, const int nt, const SchedT& S, const Epi& E) {
;     ...
;     for (int i = 0; i < 2; ++i) { int R, C; stage_rc(tid * 16 + i * 8192, R, C); const int Rb = 2 * (R & ~31) + perm32(R & 31);
;         voffA[i] = (unsigned)(R * K + C) * 2u; voffB[i] = (unsigned)(Rb * K + C) * 2u; }
;     ...
;         PG8_STAGE(PG8_SB(0, 0), cB, voffB); PG8_STAGE(PG8_SB(0, 1), cB + hstepB, voffB); PG8_STAGE(PG8_SA(0, 0), cA, voffA); PG8_STAGE(PG8_SA(0, 1), cA + hstep, voffA);
;         if (wr == 1) PG8_BAR;
.LBB0_523:
	v_readlane_b32 s18, v163, 43
	v_readlane_b32 s19, v163, 44
	s_and_b64 vcc, exec, s[18:19]
	s_cbranch_vccnz .LBB0_607
	v_ashrrev_i32_e32 v3, 31, v0
	v_lshrrev_b32_e32 v3, 26, v3
	v_add_u32_e32 v3, v0, v3
	v_ashrrev_i32_e32 v10, 6, v3
	v_bfe_i32 v3, v0, 27, 1
	v_lshlrev_b32_e32 v2, 4, v0
	v_lshrrev_b32_e32 v3, 22, v3
	v_add_u32_e32 v3, v2, v3
	v_and_b32_e32 v3, 0xfffffc00, v3
	v_sub_u32_e32 v3, v2, v3
	v_lshrrev_b32_e32 v4, 4, v3
	v_bitop3_b32 v3, v4, v3, 32 bitop3:0x6c
	v_ashrrev_i32_e32 v5, 31, v3
	v_lshrrev_b32_e32 v5, 26, v5
	v_add_u32_e32 v5, v3, v5
	v_lshlrev_b32_e32 v4, 3, v10
	v_ashrrev_i32_e32 v11, 6, v5
	v_and_b32_e32 v5, 0xc0, v5
	v_and_b32_e32 v4, -16, v4
	v_sub_u32_e32 v3, v3, v5
	v_add_u32_e32 v4, v11, v4
	v_ashrrev_i16_sdwa v3, v244, sext(v3) dst_sel:DWORD dst_unused:UNUSED_PAD src0_sel:DWORD src1_sel:BYTE_0
	v_lshlrev_b32_e32 v6, 5, v10
	v_bfe_i32 v12, v3, 0, 16
	v_lshlrev_b32_e32 v3, 1, v4
	v_lshrrev_b32_e32 v5, 2, v4
	v_and_b32_e32 v6, 32, v6
	v_and_b32_e32 v5, 4, v5
	v_and_b32_e32 v7, 3, v11
	v_and_b32_e32 v3, 0xfffd8, v3
	v_or3_b32 v3, v7, v5, v3
	v_add_lshl_u32 v5, v6, v12, 1
	v_add_u32_e32 v2, 0x2000, v2
	v_lshl_add_u32 v134, v3, 12, v5
	v_ashrrev_i32_e32 v3, 31, v2
	v_lshrrev_b32_e32 v3, 22, v3
	v_add_u32_e32 v3, v2, v3
	v_ashrrev_i32_e32 v13, 10, v3
	v_readlane_b32 s18, v163, 39
	v_mul_i32_i24_e32 v3, 0x400, v13
	s_mul_i32 s13, s18, 0x7500000
	v_sub_u32_e32 v2, v2, v3
	s_add_u32 s13, s0, s13
	v_lshrrev_b32_e32 v3, 4, v2
	s_addc_u32 s17, s1, 0
	v_bitop3_b32 v2, v3, v2, 32 bitop3:0x6c
	s_add_u32 s21, s0, 0x1fc00000
	v_lshl_add_u32 v132, v4, 12, v5
	v_ashrrev_i32_e32 v4, 31, v2
	s_addc_u32 s22, s1, 0
	v_lshrrev_b32_e32 v4, 26, v4
	s_add_u32 s54, s13, 0x2600000
	v_add_u32_e32 v4, v2, v4
	v_readlane_b32 s19, v163, 40
	s_addc_u32 s55, s17, 0
	s_ashr_i32 s38, s20, 6
	v_lshlrev_b32_e32 v3, 3, v13
	v_ashrrev_i32_e32 v14, 6, v4
	v_and_b32_e32 v4, 0xc0, v4
	s_ashr_i32 s17, s16, 31
	s_ashr_i32 s13, s12, 31
	v_and_b32_e32 v3, -16, v3
	v_sub_u32_e32 v2, v2, v4
	s_ashr_i32 s39, s20, 8
	s_lshl_b32 s56, s38, 10
	s_lshl_b64 s[18:19], s[16:17], 20
	s_lshl_b64 s[30:31], s[12:13], 20
	v_add_u32_e32 v3, v14, v3
	v_ashrrev_i16_sdwa v2, v244, sext(v2) dst_sel:DWORD dst_unused:UNUSED_PAD src0_sel:DWORD src1_sel:BYTE_0
	s_add_u32 s36, s54, s30
	v_lshlrev_b32_e32 v5, 5, v13
	v_bfe_i32 v15, v2, 0, 16
	v_lshlrev_b32_e32 v2, 1, v3
	v_lshrrev_b32_e32 v4, 2, v3
	s_addc_u32 s37, s55, s31
	s_add_i32 s57, s56, 0
	v_and_b32_e32 v5, 32, v5
	v_and_b32_e32 v4, 4, v4
	v_and_b32_e32 v6, 3, v14
	v_and_b32_e32 v2, 0xfffd8, v2
	s_add_i32 m0, s57, 0x10000
	v_or3_b32 v2, v6, v4, v2
	v_add_lshl_u32 v4, v5, v15, 1
	global_load_lds_dwordx4 v134, s[36:37]
	s_add_i32 m0, s57, 0x12000
	v_lshl_add_u32 v138, v2, 12, v4
	s_add_u32 s30, s36, 0x20000
	global_load_lds_dwordx4 v138, s[36:37]
	s_addc_u32 s31, s37, 0
	s_add_i32 m0, s57, 0x14000
	v_lshl_add_u32 v136, v3, 12, v4
	global_load_lds_dwordx4 v134, s[30:31]
	s_add_i32 m0, s57, 0x16000
	s_add_u32 s34, s21, s18
	s_addc_u32 s35, s22, s19
	s_add_i32 s58, s57, 0x2000
	global_load_lds_dwordx4 v138, s[30:31]
	s_mov_b32 m0, s57
	s_add_u32 s18, s34, 0x80000
	global_load_lds_dwordx4 v132, s[34:35]
	s_mov_b32 m0, s58
	s_addc_u32 s19, s35, 0
	s_add_i32 s59, s57, 0x4000
	global_load_lds_dwordx4 v136, s[34:35]
	s_mov_b32 m0, s59
	s_add_i32 s60, s57, 0x6000
	global_load_lds_dwordx4 v132, s[18:19]
	s_mov_b32 m0, s60
	v_mov_b32_e32 v135, v1
	global_load_lds_dwordx4 v136, s[18:19]
	v_mov_b32_e32 v139, v1
	v_mov_b32_e32 v133, v1
	v_mov_b32_e32 v137, v1
	s_cmp_eq_u32 s39, 1
	v_lshl_add_u64 v[8:9], s[36:37], 0, v[134:135]
	v_lshl_add_u64 v[6:7], s[36:37], 0, v[138:139]
	v_lshl_add_u64 v[2:3], s[34:35], 0, v[132:133]
	s_cselect_b64 s[18:19], -1, 0
	s_cmp_lg_u32 s39, 1
	v_lshl_add_u64 v[4:5], s[34:35], 0, v[136:137]
	s_cbranch_scc1 .LBB0_526
	s_barrier
	s_setprio 1

; #define PG8_STAGE(bufoff, gbase, voff) do { _Pragma("unroll") for (int _i = 0; _i < 2; ++_i) \
;         __builtin_amdgcn_global_load_lds((const __attribute__((address_space(1))) unsigned*)((const char*)(gbase) + (voff)[_i]), (LAS unsigned*)(lds + (bufoff) + ldsw + _i * 8192), 16, 0, 0); } while (0)
; #define PG8_LDA(dst, b, h) do { _Pragma("unroll") for (int m = 0; m < 4; ++m) _Pragma("unroll") for (int k = 0; k < 2; ++k) dst[m][k] = *(const LAS bf16x8*)(lds + PG8_SA(b, h) + aoff + m * 2048 + k * 1024); } while (0)
; #define PG8_LDB(dst, b, h) do { _Pragma("unroll") for (int n = 0; n < 2; ++n) _Pragma("unroll") for (int k = 0; k < 2; ++k) dst[n][k] = *(const LAS bf16x8*)(lds + PG8_SB(b, h) + boff + n * 2048 + k * 1024); } while (0)
; #define PG8_MMA(ai, bj, At, Bt) do { __builtin_amdgcn_s_setprio(1); _Pragma("unroll") for (int m = 0; m < 4; ++m) _Pragma("unroll") for (int n = 0; n < 2; ++n) _Pragma("unroll") for (int k = 0; k < 2; ++k) \
;         acc[ai][bj][m][n] = __builtin_amdgcn_mfma_f32_16x16x32_bf16(Bt[n][k], At[m][k], acc[ai][bj][m][n], 0, 0, 0); __builtin_amdgcn_s_setprio(0); } while (0)
; #define PG8_WAIT_V(n) asm volatile("s_waitcnt vmcnt(" #n ")" ::: "memory")
; #define PG8_WAIT_L(n) asm volatile("s_waitcnt lgkmcnt(" #n ")" ::: "memory")
; #define PG8_BAR __builtin_amdgcn_s_barrier()
; #define PG8_SCHED __builtin_amdgcn_sched_barrier(0)
; template <class Epi, class SchedT, bool ALIGN_EPI, bool SP2>
; __device__ __forceinline__ void gemm_phase(LAS unsigned char* lds, const int ldk, const int nt, const SchedT& S, const Epi& E) {
;     ...
;             PG8_LDB(B0, 0, 0); PG8_LDB(B1, 0, 1); PG8_SCHED; PG8_LDA(At, 0, 0); PG8_STAGE(PG8_SA(1, 1), a1 + hstep, voffA);
;             PG8_WAIT_V(8); PG8_WAIT_L(0); PG8_BAR; PG8_MMA(0, 0, At, B0); PG8_MMA(0, 1, At, B1); PG8_BAR; PG8_SCHED;
;             PG8_LDA(At, 0, 1); PG8_STAGE(PG8_SB(0, 0), b2, voffB); PG8_STAGE(PG8_SB(0, 1), b2 + hstepB, voffB); PG8_STAGE(PG8_SA(0, 0), a2, voffA);
.LBB0_534:
	s_add_u32 s36, s34, 0xfff80080
	s_addc_u32 s37, s35, -1
	s_add_i32 s49, 0, 0x10000
	s_cmp_eq_u32 s47, 12
	s_cselect_b32 s41, s1, s37
	s_cselect_b32 s40, s0, s36
	v_add_u32_e32 v0, s49, v159
	s_cselect_b32 s37, s53, s20
	s_cselect_b32 s36, s52, s17
	s_add_i32 s51, 0, 0x14000
	ds_read_b128 v[144:147], v0
	ds_read_b128 v[148:151], v0 offset:1024
	ds_read_b128 v[152:155], v0 offset:2048
	ds_read_b128 v[174:177], v0 offset:3072
	v_add_u32_e32 v0, s51, v159
	ds_read_b128 v[178:181], v0
	ds_read_b128 v[182:185], v0 offset:1024
	ds_read_b128 v[186:189], v0 offset:2048
	ds_read_b128 v[190:193], v0 offset:3072
	v_lshl_add_u64 v[2:3], s[34:35], 0, v[140:141]
	s_add_i32 m0, s57, 0xc000
	ds_read_b128 v[194:197], v161
	ds_read_b128 v[198:201], v161 offset:1024
	ds_read_b128 v[202:205], v161 offset:2048
	ds_read_b128 v[206:209], v161 offset:3072
	ds_read_b128 v[210:213], v161 offset:4096
	ds_read_b128 v[214:217], v161 offset:5120
	ds_read_b128 v[218:221], v161 offset:6144
	ds_read_b128 v[222:225], v161 offset:7168
	global_load_lds_dwordx4 v[2:3], off
	v_lshl_add_u64 v[2:3], s[34:35], 0, v[142:143]
	s_add_i32 m0, s57, 0xe000
	s_nop 0
	global_load_lds_dwordx4 v[2:3], off
	s_waitcnt vmcnt(8)
	s_waitcnt lgkmcnt(0)
	s_barrier
	s_waitcnt lgkmcnt(0)
	v_mfma_f32_16x16x32_bf16 v[128:131], v[144:147], v[194:197], v[128:131]
	v_mfma_f32_16x16x32_bf16 v[124:127], v[152:155], v[194:197], v[124:127]
	v_mfma_f32_16x16x32_bf16 v[120:123], v[144:147], v[202:205], v[120:123]
	v_mfma_f32_16x16x32_bf16 v[116:119], v[152:155], v[202:205], v[116:119]
	v_mfma_f32_16x16x32_bf16 v[112:115], v[144:147], v[210:213], v[112:115]
	v_mfma_f32_16x16x32_bf16 v[108:111], v[152:155], v[210:213], v[108:111]
	v_mfma_f32_16x16x32_bf16 v[104:107], v[144:147], v[218:221], v[104:107]
	v_mfma_f32_16x16x32_bf16 v[100:103], v[152:155], v[218:221], v[100:103]
	v_mfma_f32_16x16x32_bf16 v[128:131], v[148:151], v[198:201], v[128:131]
	v_mfma_f32_16x16x32_bf16 v[124:127], v[174:177], v[198:201], v[124:127]
	v_mfma_f32_16x16x32_bf16 v[120:123], v[148:151], v[206:209], v[120:123]
	v_mfma_f32_16x16x32_bf16 v[116:119], v[174:177], v[206:209], v[116:119]
	v_mfma_f32_16x16x32_bf16 v[112:115], v[148:151], v[214:217], v[112:115]
	v_mfma_f32_16x16x32_bf16 v[108:111], v[174:177], v[214:217], v[108:111]
	v_mfma_f32_16x16x32_bf16 v[104:107], v[148:151], v[222:225], v[104:107]
	v_mfma_f32_16x16x32_bf16 v[100:103], v[174:177], v[222:225], v[100:103]
	v_mfma_f32_16x16x32_bf16 v[96:99], v[178:181], v[194:197], v[96:99]
	v_mfma_f32_16x16x32_bf16 v[92:95], v[186:189], v[194:197], v[92:95]
	v_mfma_f32_16x16x32_bf16 v[88:91], v[178:181], v[202:205], v[88:91]
	v_mfma_f32_16x16x32_bf16 v[84:87], v[186:189], v[202:205], v[84:87]
	v_mfma_f32_16x16x32_bf16 v[80:83], v[178:181], v[210:213], v[80:83]
	v_mfma_f32_16x16x32_bf16 v[76:79], v[186:189], v[210:213], v[76:79]
	v_mfma_f32_16x16x32_bf16 v[72:75], v[178:181], v[218:221], v[72:75]
	v_mfma_f32_16x16x32_bf16 v[68:71], v[186:189], v[218:221], v[68:71]
	v_mfma_f32_16x16x32_bf16 v[96:99], v[182:185], v[198:201], v[96:99]
	v_mfma_f32_16x16x32_bf16 v[92:95], v[190:193], v[198:201], v[92:95]
	v_mfma_f32_16x16x32_bf16 v[88:91], v[182:185], v[206:209], v[88:91]
	v_mfma_f32_16x16x32_bf16 v[84:87], v[190:193], v[206:209], v[84:87]
	v_mfma_f32_16x16x32_bf16 v[80:83], v[182:185], v[214:217], v[80:83]
	v_mfma_f32_16x16x32_bf16 v[76:79], v[190:193], v[214:217], v[76:79]
	v_mfma_f32_16x16x32_bf16 v[72:75], v[182:185], v[222:225], v[72:75]
	v_mfma_f32_16x16x32_bf16 v[68:71], v[190:193], v[222:225], v[68:71]
	s_barrier
	s_add_i32 s49, s49, s56
	v_lshl_add_u64 v[156:157], s[36:37], 0, v[134:135]
	s_mov_b32 m0, s49
	ds_read_b128 v[194:197], v161 offset:16384
	ds_read_b128 v[198:201], v161 offset:17408
	ds_read_b128 v[202:205], v161 offset:18432
	ds_read_b128 v[206:209], v161 offset:19456
	ds_read_b128 v[210:213], v161 offset:20480
	ds_read_b128 v[214:217], v161 offset:21504
	ds_read_b128 v[218:221], v161 offset:22528
	ds_read_b128 v[222:225], v161 offset:23552
	global_load_lds_dwordx4 v[156:157], off
	s_add_i32 m0, s49, 0x2000
	s_add_u32 s82, s36, 0x20000
	v_lshl_add_u64 v[226:227], s[36:37], 0, v[138:139]
	s_addc_u32 s83, s37, 0
	s_add_i32 s49, s51, s56
	global_load_lds_dwordx4 v[226:227], off
	v_lshl_add_u64 v[2:3], s[82:83], 0, v[134:135]
	s_mov_b32 m0, s49
	v_lshl_add_u64 v[228:229], s[40:41], 0, v[132:133]
	global_load_lds_dwordx4 v[2:3], off
	v_lshl_add_u64 v[2:3], s[82:83], 0, v[138:139]
	s_add_i32 m0, s49, 0x2000
	v_lshl_add_u64 v[230:231], s[40:41], 0, v[136:137]
	global_load_lds_dwordx4 v[2:3], off
	s_mov_b32 m0, s57
	s_nop 0
	global_load_lds_dwordx4 v[228:229], off
	s_mov_b32 m0, s58
	s_nop 0
	global_load_lds_dwordx4 v[230:231], off
	s_waitcnt vmcnt(8)
	s_waitcnt lgkmcnt(0)
	s_barrier
; #define PG8_STAGE(bufoff, gbase, voff) do { _Pragma("unroll") for (int _i = 0; _i < 2; ++_i) \
;         __builtin_amdgcn_global_load_lds((const __attribute__((address_space(1))) unsigned*)((const char*)(gbase) + (voff)[_i]), (LAS unsigned*)(lds + (bufoff) + ldsw + _i * 8192), 16, 0, 0); } while (0)
; #define PG8_LDA(dst, b, h) do { _Pragma("unroll") for (int m = 0; m < 4; ++m) _Pragma("unroll") for (int k = 0; k < 2; ++k) dst[m][k] = *(const LAS bf16x8*)(lds + PG8_SA(b, h) + aoff + m * 2048 + k * 1024); } while (0)
; #define PG8_LDB(dst, b, h) do { _Pragma("unroll") for (int n = 0; n < 2; ++n) _Pragma("unroll") for (int k = 0; k < 2; ++k) dst[n][k] = *(const LAS bf16x8*)(lds + PG8_SB(b, h) + boff + n * 2048 + k * 1024); } while (0)
; #define PG8_MMA(ai, bj, At, Bt) do { __builtin_amdgcn_s_setprio(1); _Pragma("unroll") for (int m = 0; m < 4; ++m) _Pragma("unroll") for (int n = 0; n < 2; ++n) _Pragma("unroll") for (int k = 0; k < 2; ++k) \
;         acc[ai][bj][m][n] = __builtin_amdgcn_mfma_f32_16x16x32_bf16(Bt[n][k], At[m][k], acc[ai][bj][m][n], 0, 0, 0); __builtin_amdgcn_s_setprio(0); } while (0)
; #define PG8_WAIT_V(n) asm volatile("s_waitcnt vmcnt(" #n ")" ::: "memory")
; #define PG8_WAIT_L(n) asm volatile("s_waitcnt lgkmcnt(" #n ")" ::: "memory")
; #define PG8_BAR __builtin_amdgcn_s_barrier()
; #define PG8_SCHED __builtin_amdgcn_sched_barrier(0)
; template <class Epi, class SchedT, bool ALIGN_EPI, bool SP2>
; __device__ __forceinline__ void gemm_phase(LAS unsigned char* lds, const int ldk, const int nt, const SchedT& S, const Epi& E) {
;     ...
;             PG8_WAIT_V(8); PG8_WAIT_L(0); PG8_BAR; PG8_MMA(1, 0, At, B0); PG8_MMA(1, 1, At, B1); PG8_BAR; PG8_SCHED;
;             PG8_LDB(B0, 1, 0); PG8_LDB(B1, 1, 1); PG8_SCHED; PG8_LDA(At, 1, 0); PG8_STAGE(PG8_SA(0, 1), a2 + hstep, voffA);
;             PG8_WAIT_V(8); PG8_WAIT_L(0); PG8_BAR; PG8_MMA(0, 0, At, B0); PG8_MMA(0, 1, At, B1); PG8_BAR; PG8_SCHED;
	s_waitcnt lgkmcnt(0)
	v_mfma_f32_16x16x32_bf16 v[64:67], v[144:147], v[194:197], v[64:67]
	v_mfma_f32_16x16x32_bf16 v[60:63], v[152:155], v[194:197], v[60:63]
	v_mfma_f32_16x16x32_bf16 v[56:59], v[144:147], v[202:205], v[56:59]
	v_mfma_f32_16x16x32_bf16 v[52:55], v[152:155], v[202:205], v[52:55]
	v_mfma_f32_16x16x32_bf16 v[48:51], v[144:147], v[210:213], v[48:51]
	v_mfma_f32_16x16x32_bf16 v[44:47], v[152:155], v[210:213], v[44:47]
	v_mfma_f32_16x16x32_bf16 v[40:43], v[144:147], v[218:221], v[40:43]
	v_mfma_f32_16x16x32_bf16 v[36:39], v[152:155], v[218:221], v[36:39]
	v_mfma_f32_16x16x32_bf16 v[64:67], v[148:151], v[198:201], v[64:67]
	v_mfma_f32_16x16x32_bf16 v[60:63], v[174:177], v[198:201], v[60:63]
	v_mfma_f32_16x16x32_bf16 v[56:59], v[148:151], v[206:209], v[56:59]
	v_mfma_f32_16x16x32_bf16 v[52:55], v[174:177], v[206:209], v[52:55]
	v_mfma_f32_16x16x32_bf16 v[48:51], v[148:151], v[214:217], v[48:51]
	v_mfma_f32_16x16x32_bf16 v[44:47], v[174:177], v[214:217], v[44:47]
	v_mfma_f32_16x16x32_bf16 v[40:43], v[148:151], v[222:225], v[40:43]
	v_mfma_f32_16x16x32_bf16 v[36:39], v[174:177], v[222:225], v[36:39]
	v_mfma_f32_16x16x32_bf16 v[32:35], v[178:181], v[194:197], v[32:35]
	v_mfma_f32_16x16x32_bf16 v[28:31], v[186:189], v[194:197], v[28:31]
	v_mfma_f32_16x16x32_bf16 v[24:27], v[178:181], v[202:205], v[24:27]
	v_mfma_f32_16x16x32_bf16 v[20:23], v[186:189], v[202:205], v[20:23]
	v_mfma_f32_16x16x32_bf16 v[16:19], v[178:181], v[210:213], v[16:19]
	v_mfma_f32_16x16x32_bf16 v[12:15], v[186:189], v[210:213], v[12:15]
	v_mfma_f32_16x16x32_bf16 v[8:11], v[178:181], v[218:221], v[8:11]
	v_mfma_f32_16x16x32_bf16 v[2:5], v[186:189], v[218:221], v[4:7]
	v_mfma_f32_16x16x32_bf16 v[32:35], v[182:185], v[198:201], v[32:35]
	v_mfma_f32_16x16x32_bf16 v[28:31], v[190:193], v[198:201], v[28:31]
	v_mfma_f32_16x16x32_bf16 v[24:27], v[182:185], v[206:209], v[24:27]
	v_mfma_f32_16x16x32_bf16 v[20:23], v[190:193], v[206:209], v[20:23]
	v_mfma_f32_16x16x32_bf16 v[16:19], v[182:185], v[214:217], v[16:19]
	v_mfma_f32_16x16x32_bf16 v[12:15], v[190:193], v[214:217], v[12:15]
	v_mfma_f32_16x16x32_bf16 v[8:11], v[182:185], v[222:225], v[8:11]
	v_mfma_f32_16x16x32_bf16 v[2:5], v[190:193], v[222:225], v[2:5]
	s_barrier
	s_add_i32 s49, 0, 0x18000
	v_add_u32_e32 v0, s49, v159
	s_add_i32 s51, 0, 0x1c000
	ds_read_b128 v[144:147], v0
	ds_read_b128 v[148:151], v0 offset:1024
	ds_read_b128 v[152:155], v0 offset:2048
	ds_read_b128 v[174:177], v0 offset:3072
	v_add_u32_e32 v0, s51, v159
	ds_read_b128 v[178:181], v0
	ds_read_b128 v[182:185], v0 offset:1024
	ds_read_b128 v[186:189], v0 offset:2048
	ds_read_b128 v[190:193], v0 offset:3072
	s_add_u32 s40, s40, 0x80000
	s_addc_u32 s41, s41, 0
	s_mov_b32 m0, s59
	v_lshl_add_u64 v[6:7], s[40:41], 0, v[132:133]
	ds_read_b128 v[194:197], v161 offset:32768
	ds_read_b128 v[198:201], v161 offset:33792
	ds_read_b128 v[202:205], v161 offset:34816
	ds_read_b128 v[206:209], v161 offset:35840
	ds_read_b128 v[210:213], v161 offset:36864
	ds_read_b128 v[214:217], v161 offset:37888
	ds_read_b128 v[218:221], v161 offset:38912
	ds_read_b128 v[222:225], v161 offset:39936
	global_load_lds_dwordx4 v[6:7], off
	v_lshl_add_u64 v[6:7], s[40:41], 0, v[136:137]
	s_mov_b32 m0, s60
	s_nop 0
	global_load_lds_dwordx4 v[6:7], off
	s_waitcnt vmcnt(8)
	s_waitcnt lgkmcnt(0)
	s_barrier
	s_waitcnt lgkmcnt(0)
	v_mfma_f32_16x16x32_bf16 v[128:131], v[144:147], v[194:197], v[128:131]
	v_mfma_f32_16x16x32_bf16 v[124:127], v[152:155], v[194:197], v[124:127]
	v_mfma_f32_16x16x32_bf16 v[120:123], v[144:147], v[202:205], v[120:123]
	v_mfma_f32_16x16x32_bf16 v[116:119], v[152:155], v[202:205], v[116:119]
	v_mfma_f32_16x16x32_bf16 v[112:115], v[144:147], v[210:213], v[112:115]
	v_mfma_f32_16x16x32_bf16 v[108:111], v[152:155], v[210:213], v[108:111]
	v_mfma_f32_16x16x32_bf16 v[104:107], v[144:147], v[218:221], v[104:107]
	v_mfma_f32_16x16x32_bf16 v[100:103], v[152:155], v[218:221], v[100:103]
	v_mfma_f32_16x16x32_bf16 v[128:131], v[148:151], v[198:201], v[128:131]
	v_mfma_f32_16x16x32_bf16 v[124:127], v[174:177], v[198:201], v[124:127]
	v_mfma_f32_16x16x32_bf16 v[120:123], v[148:151], v[206:209], v[120:123]
	v_mfma_f32_16x16x32_bf16 v[116:119], v[174:177], v[206:209], v[116:119]
	v_mfma_f32_16x16x32_bf16 v[112:115], v[148:151], v[214:217], v[112:115]
	v_mfma_f32_16x16x32_bf16 v[108:111], v[174:177], v[214:217], v[108:111]
	v_mfma_f32_16x16x32_bf16 v[104:107], v[148:151], v[222:225], v[104:107]
	v_mfma_f32_16x16x32_bf16 v[100:103], v[174:177], v[222:225], v[100:103]
	v_mfma_f32_16x16x32_bf16 v[96:99], v[178:181], v[194:197], v[96:99]
	v_mfma_f32_16x16x32_bf16 v[92:95], v[186:189], v[194:197], v[92:95]
	v_mfma_f32_16x16x32_bf16 v[88:91], v[178:181], v[202:205], v[88:91]
	v_mfma_f32_16x16x32_bf16 v[84:87], v[186:189], v[202:205], v[84:87]
	v_mfma_f32_16x16x32_bf16 v[80:83], v[178:181], v[210:213], v[80:83]
	v_mfma_f32_16x16x32_bf16 v[76:79], v[186:189], v[210:213], v[76:79]
	v_mfma_f32_16x16x32_bf16 v[72:75], v[178:181], v[218:221], v[72:75]
	v_mfma_f32_16x16x32_bf16 v[68:71], v[186:189], v[218:221], v[68:71]
	v_mfma_f32_16x16x32_bf16 v[96:99], v[182:185], v[198:201], v[96:99]
	v_mfma_f32_16x16x32_bf16 v[92:95], v[190:193], v[198:201], v[92:95]
	v_mfma_f32_16x16x32_bf16 v[88:91], v[182:185], v[206:209], v[88:91]
	v_mfma_f32_16x16x32_bf16 v[84:87], v[190:193], v[206:209], v[84:87]
	v_mfma_f32_16x16x32_bf16 v[80:83], v[182:185], v[214:217], v[80:83]
	v_mfma_f32_16x16x32_bf16 v[76:79], v[190:193], v[214:217], v[76:79]
	v_mfma_f32_16x16x32_bf16 v[72:75], v[182:185], v[222:225], v[72:75]
	v_mfma_f32_16x16x32_bf16 v[68:71], v[190:193], v[222:225], v[68:71]
	s_barrier
; #define PG8_STAGE(bufoff, gbase, voff) do { _Pragma("unroll") for (int _i = 0; _i < 2; ++_i) \
;         __builtin_amdgcn_global_load_lds((const __attribute__((address_space(1))) unsigned*)((const char*)(gbase) + (voff)[_i]), (LAS unsigned*)(lds + (bufoff) + ldsw + _i * 8192), 16, 0, 0); } while (0)
; #define PG8_LDA(dst, b, h) do { _Pragma("unroll") for (int m = 0; m < 4; ++m) _Pragma("unroll") for (int k = 0; k < 2; ++k) dst[m][k] = *(const LAS bf16x8*)(lds + PG8_SA(b, h) + aoff + m * 2048 + k * 1024); } while (0)
; #define PG8_MMA(ai, bj, At, Bt) do { __builtin_amdgcn_s_setprio(1); _Pragma("unroll") for (int m = 0; m < 4; ++m) _Pragma("unroll") for (int n = 0; n < 2; ++n) _Pragma("unroll") for (int k = 0; k < 2; ++k) \
;         acc[ai][bj][m][n] = __builtin_amdgcn_mfma_f32_16x16x32_bf16(Bt[n][k], At[m][k], acc[ai][bj][m][n], 0, 0, 0); __builtin_amdgcn_s_setprio(0); } while (0)
; #define PG8_WAIT_V(n) asm volatile("s_waitcnt vmcnt(" #n ")" ::: "memory")
; #define PG8_WAIT_L(n) asm volatile("s_waitcnt lgkmcnt(" #n ")" ::: "memory")
; template <class Epi, class SchedT, bool ALIGN_EPI, bool SP2>
; __device__ __forceinline__ void gemm_phase(LAS unsigned char* lds, const int ldk, const int nt, const SchedT& S, const Epi& E) {
;     ...
;             PG8_LDA(At, 1, 1); PG8_STAGE(PG8_SB(1, 0), b3, voffB); PG8_STAGE(PG8_SB(1, 1), b3 + hstepB, voffB); PG8_STAGE(PG8_SA(1, 0), a3, voffA);
;             PG8_WAIT_V(8); PG8_WAIT_L(0); PG8_BAR; PG8_MMA(1, 0, At, B0); PG8_MMA(1, 1, At, B1); PG8_BAR; PG8_SCHED;
;     __device__ __forceinline__ void operator()(f32x4 (&acc)[2][2][4][2], const Unit& u, int wr, int wc, int fr, int fq) const {
;         const int row0 = u.pm * BM + wr * 64 + fr, col0 = u.pn * BM + wc * 64 + 8 * fq;
; #pragma unroll
;         for (int ai = 0; ai < 2; ++ai)
; #pragma unroll
;             for (int m = 0; m < 4; ++m) {
;                 const int row = row0 + ai * HALF + m * 16;
; #pragma unroll
;                 for (int bj = 0; bj < 2; ++bj) {
;                     const int col = col0 + bj * 32;
;                     const unsigned char* grow = (const unsigned char*)Gt + (size_t)row * 4096 + col;
;                     const u32x2 gw = *(const u32x2*)(grow + 2048);
;                     f32x4 g0 = gate_d4(gw.x), g1 = gate_d4(gw.y);
;                     if (u.kind == 0) {
;                         const u32x2 aw = *(const u32x2*)grow;
	s_add_i32 s40, s49, s56
	v_lshl_add_u64 v[6:7], v[156:157], 0, s[24:25]
	s_mov_b32 m0, s40
	ds_read_b128 v[194:197], v161 offset:49152
	ds_read_b128 v[198:201], v161 offset:50176
	ds_read_b128 v[202:205], v161 offset:51200
	ds_read_b128 v[206:209], v161 offset:52224
	ds_read_b128 v[210:213], v161 offset:53248
	ds_read_b128 v[214:217], v161 offset:54272
	ds_read_b128 v[218:221], v161 offset:55296
	ds_read_b128 v[222:225], v161 offset:56320
	global_load_lds_dwordx4 v[6:7], off
	s_add_i32 m0, s40, 0x2000
	s_add_u32 s36, s36, 0x20080
	v_lshl_add_u64 v[6:7], v[226:227], 0, s[24:25]
	s_addc_u32 s37, s37, 0
	s_add_i32 s40, s51, s56
	global_load_lds_dwordx4 v[6:7], off
	v_lshl_add_u64 v[6:7], s[36:37], 0, v[134:135]
	s_mov_b32 m0, s40
	s_nop 0
	global_load_lds_dwordx4 v[6:7], off
	v_lshl_add_u64 v[6:7], s[36:37], 0, v[138:139]
	s_add_i32 m0, s40, 0x2000
	s_nop 0
	global_load_lds_dwordx4 v[6:7], off
	v_lshl_add_u64 v[6:7], v[228:229], 0, s[24:25]
	s_mov_b32 m0, s61
	s_nop 0
	global_load_lds_dwordx4 v[6:7], off
	v_lshl_add_u64 v[6:7], v[230:231], 0, s[24:25]
	s_mov_b32 m0, s62
	s_nop 0
	global_load_lds_dwordx4 v[6:7], off
	s_waitcnt vmcnt(8)
	s_waitcnt lgkmcnt(0)
	s_barrier
	s_waitcnt lgkmcnt(0)
	v_mfma_f32_16x16x32_bf16 v[64:67], v[144:147], v[194:197], v[64:67]
	v_mfma_f32_16x16x32_bf16 v[60:63], v[152:155], v[194:197], v[60:63]
	v_mfma_f32_16x16x32_bf16 v[56:59], v[144:147], v[202:205], v[56:59]
	v_mfma_f32_16x16x32_bf16 v[52:55], v[152:155], v[202:205], v[52:55]
	v_mfma_f32_16x16x32_bf16 v[48:51], v[144:147], v[210:213], v[48:51]
	v_mfma_f32_16x16x32_bf16 v[44:47], v[152:155], v[210:213], v[44:47]
	v_mfma_f32_16x16x32_bf16 v[40:43], v[144:147], v[218:221], v[40:43]
	v_mfma_f32_16x16x32_bf16 v[36:39], v[152:155], v[218:221], v[36:39]
	v_mfma_f32_16x16x32_bf16 v[64:67], v[148:151], v[198:201], v[64:67]
	v_mfma_f32_16x16x32_bf16 v[60:63], v[174:177], v[198:201], v[60:63]
	v_mfma_f32_16x16x32_bf16 v[56:59], v[148:151], v[206:209], v[56:59]
	v_mfma_f32_16x16x32_bf16 v[52:55], v[174:177], v[206:209], v[52:55]
	v_mfma_f32_16x16x32_bf16 v[48:51], v[148:151], v[214:217], v[48:51]
	v_mfma_f32_16x16x32_bf16 v[44:47], v[174:177], v[214:217], v[44:47]
	v_mfma_f32_16x16x32_bf16 v[40:43], v[148:151], v[222:225], v[40:43]
	v_mfma_f32_16x16x32_bf16 v[36:39], v[174:177], v[222:225], v[36:39]
	v_mfma_f32_16x16x32_bf16 v[32:35], v[178:181], v[194:197], v[32:35]
	v_mfma_f32_16x16x32_bf16 v[28:31], v[186:189], v[194:197], v[28:31]
	v_mfma_f32_16x16x32_bf16 v[24:27], v[178:181], v[202:205], v[24:27]
	v_mfma_f32_16x16x32_bf16 v[20:23], v[186:189], v[202:205], v[20:23]
	v_mfma_f32_16x16x32_bf16 v[16:19], v[178:181], v[210:213], v[16:19]
	v_mfma_f32_16x16x32_bf16 v[12:15], v[186:189], v[210:213], v[12:15]
	v_mfma_f32_16x16x32_bf16 v[6:9], v[178:181], v[218:221], v[8:11]
	v_mfma_f32_16x16x32_bf16 v[2:5], v[186:189], v[218:221], v[2:5]
	v_mfma_f32_16x16x32_bf16 v[32:35], v[182:185], v[198:201], v[32:35]
	v_mfma_f32_16x16x32_bf16 v[28:31], v[190:193], v[198:201], v[28:31]
	v_mfma_f32_16x16x32_bf16 v[24:27], v[182:185], v[206:209], v[24:27]
	v_mfma_f32_16x16x32_bf16 v[20:23], v[190:193], v[206:209], v[20:23]
	v_mfma_f32_16x16x32_bf16 v[16:19], v[182:185], v[214:217], v[16:19]
	v_mfma_f32_16x16x32_bf16 v[12:15], v[190:193], v[214:217], v[12:15]
	v_mfma_f32_16x16x32_bf16 v[8:11], v[182:185], v[222:225], v[6:9]
	v_mfma_f32_16x16x32_bf16 v[4:7], v[190:193], v[222:225], v[2:5]
	s_barrier
	s_add_i32 s47, s47, 2
	s_add_u32 s34, s34, 0x100
	s_addc_u32 s35, s35, 0
	s_add_u32 s17, s17, 0x100
	s_addc_u32 s20, s20, 0
	s_cmp_gt_u32 s47, 13
	s_cbranch_scc0 .LBB0_534
	v_lshl_add_u32 v144, s16, 8, v158
	v_lshl_or_b32 v145, s12, 8, v160
	v_lshl_add_u32 v146, v144, 12, v145
	v_add_u32_e32 v147, 0x10000, v146
	v_add_u32_e32 v148, 0x20000, v146
	v_add_u32_e32 v149, 0x30000, v146
	v_add_u32_e32 v150, 0x80000, v146
	v_add_u32_e32 v151, 0x90000, v146
	v_add_u32_e32 v152, 0xa0000, v146
	v_add_u32_e32 v153, 0xb0000, v146
	s_cmp_lg_u32 s13, 0
	s_cbranch_scc1 .Lp3e_k1_loads
	global_load_dwordx2 v[174:175], v146, s[30:31] offset:2048
	global_load_dwordx2 v[176:177], v146, s[30:31] offset:0
	global_load_dwordx2 v[178:179], v146, s[30:31] offset:2080
	global_load_dwordx2 v[180:181], v146, s[30:31] offset:32
	global_load_dwordx2 v[182:183], v147, s[30:31] offset:2048
	global_load_dwordx2 v[184:185], v147, s[30:31] offset:0
	global_load_dwordx2 v[186:187], v147, s[30:31] offset:2080
	global_load_dwordx2 v[188:189], v147, s[30:31] offset:32
	global_load_dwordx2 v[190:191], v148, s[30:31] offset:2048
	global_load_dwordx2 v[192:193], v148, s[30:31] offset:0
	global_load_dwordx2 v[194:195], v148, s[30:31] offset:2080
	global_load_dwordx2 v[196:197], v148, s[30:31] offset:32
	global_load_dwordx2 v[198:199], v149, s[30:31] offset:2048
	global_load_dwordx2 v[200:201], v149, s[30:31] offset:0
	global_load_dwordx2 v[202:203], v149, s[30:31] offset:2080
	global_load_dwordx2 v[204:205], v149, s[30:31] offset:32
	global_load_dwordx2 v[206:207], v150, s[30:31] offset:2048
	global_load_dwordx2 v[208:209], v150, s[30:31] offset:0
	global_load_dwordx2 v[210:211], v150, s[30:31] offset:2080
	global_load_dwordx2 v[212:213], v150, s[30:31] offset:32
	global_load_dwordx2 v[214:215], v151, s[30:31] offset:2048
	global_load_dwordx2 v[216:217], v151, s[30:31] offset:0
	global_load_dwordx2 v[218:219], v151, s[30:31] offset:2080
	global_load_dwordx2 v[220:221], v151, s[30:31] offset:32
	global_load_dwordx2 v[222:223], v152, s[30:31] offset:2048
	global_load_dwordx2 v[224:225], v152, s[30:31] offset:0
	global_load_dwordx2 v[226:227], v152, s[30:31] offset:2080
	global_load_dwordx2 v[228:229], v152, s[30:31] offset:32
	global_load_dwordx2 v[230:231], v153, s[30:31] offset:2048
	global_load_dwordx2 v[232:233], v153, s[30:31] offset:0
	global_load_dwordx2 v[234:235], v153, s[30:31] offset:2080
	global_load_dwordx2 v[236:237], v153, s[30:31] offset:32
	s_branch .Lp3e_align

; #define PG8_STAGE(bufoff, gbase, voff) do { _Pragma("unroll") for (int _i = 0; _i < 2; ++_i) \
;         __builtin_amdgcn_global_load_lds((const __attribute__((address_space(1))) unsigned*)((const char*)(gbase) + (voff)[_i]), (LAS unsigned*)(lds + (bufoff) + ldsw + _i * 8192), 16, 0, 0); } while (0)
; #define PG8_BAR __builtin_amdgcn_s_barrier()
; template <class Epi, class SchedT, bool ALIGN_EPI, bool SP2>
; __device__ __forceinline__ void gemm_phase(LAS unsigned char* lds, const int ldk, const int nt, const SchedT& S, const Epi& E) {
;     ...
;     for (int i = 0; i < 2; ++i) { int R, C; stage_rc(tid * 16 + i * 8192, R, C); const int Rb = 2 * (R & ~31) + perm32(R & 31);
;         voffA[i] = (unsigned)(R * K + C) * 2u; voffB[i] = (unsigned)(Rb * K + C) * 2u; }
;     ...
;         PG8_STAGE(PG8_SB(0, 0), cB, voffB); PG8_STAGE(PG8_SB(0, 1), cB + hstepB, voffB); PG8_STAGE(PG8_SA(0, 0), cA, voffA); PG8_STAGE(PG8_SA(0, 1), cA + hstep, voffA);
;         if (wr == 1) PG8_BAR;
.LBB0_657:
	v_readlane_b32 s18, v163, 37
	v_readlane_b32 s19, v163, 38
	s_or_b32 s30, s18, 0x40000
	v_readlane_b32 s18, v163, 43
	v_readlane_b32 s19, v163, 44
	s_and_b64 vcc, exec, s[18:19]
	s_mov_b32 s31, s23
	s_cbranch_vccnz .LBB0_691
	v_ashrrev_i32_e32 v0, 31, v16
	v_lshrrev_b32_e32 v0, 26, v0
	v_add_u32_e32 v0, v16, v0
	v_ashrrev_i32_e32 v10, 6, v0
	v_bfe_i32 v0, v16, 27, 1
	v_lshlrev_b32_e32 v2, 4, v16
	v_lshrrev_b32_e32 v0, 22, v0
	v_add_u32_e32 v0, v2, v0
	v_and_b32_e32 v0, 0xfffffc00, v0
	v_sub_u32_e32 v0, v2, v0
	v_lshrrev_b32_e32 v3, 4, v0
	v_bitop3_b32 v0, v3, v0, 32 bitop3:0x6c
	v_ashrrev_i32_e32 v4, 31, v0
	v_lshrrev_b32_e32 v4, 26, v4
	v_add_u32_e32 v4, v0, v4
	v_lshlrev_b32_e32 v3, 3, v10
	v_ashrrev_i32_e32 v11, 6, v4
	v_and_b32_e32 v4, 0xc0, v4
	v_and_b32_e32 v3, -16, v3
	v_sub_u32_e32 v0, v0, v4
	v_add_u32_e32 v3, v11, v3
	v_ashrrev_i16_sdwa v0, v244, sext(v0) dst_sel:DWORD dst_unused:UNUSED_PAD src0_sel:DWORD src1_sel:BYTE_0
	v_lshlrev_b32_e32 v5, 5, v10
	v_bfe_i32 v12, v0, 0, 16
	v_lshlrev_b32_e32 v0, 1, v3
	v_lshrrev_b32_e32 v4, 2, v3
	v_and_b32_e32 v5, 32, v5
	v_and_b32_e32 v4, 4, v4
	v_and_b32_e32 v6, 3, v11
	v_and_b32_e32 v0, 0xfffd8, v0
	v_or3_b32 v0, v6, v4, v0
	v_add_lshl_u32 v4, v5, v12, 1
	v_add_u32_e32 v2, 0x2000, v2
	v_lshl_add_u32 v130, v3, 12, v4
	v_ashrrev_i32_e32 v3, 31, v2
	v_lshrrev_b32_e32 v3, 22, v3
	v_add_u32_e32 v3, v2, v3
	v_ashrrev_i32_e32 v13, 10, v3
	v_readlane_b32 s18, v163, 39
	v_mul_i32_i24_e32 v3, 0x400, v13
	s_mul_i32 s13, s18, 0x7500000
	v_sub_u32_e32 v2, v2, v3
	s_add_u32 s13, s0, s13
	v_lshrrev_b32_e32 v3, 4, v2
	s_addc_u32 s17, s1, 0
	v_bitop3_b32 v2, v3, v2, 32 bitop3:0x6c
	s_add_u32 s21, s0, 0x25c00000
	v_lshl_add_u32 v0, v0, 12, v4
	v_ashrrev_i32_e32 v4, 31, v2
	s_addc_u32 s58, s1, 0
	v_lshrrev_b32_e32 v4, 26, v4
	s_add_u32 s59, s13, 0x2e00000
	v_add_u32_e32 v4, v2, v4
	v_readlane_b32 s19, v163, 40
	s_addc_u32 s60, s17, 0
	s_ashr_i32 s22, s20, 6
	v_lshlrev_b32_e32 v3, 3, v13
	v_ashrrev_i32_e32 v14, 6, v4
	v_and_b32_e32 v4, 0xc0, v4
	s_ashr_i32 s17, s16, 31
	s_ashr_i32 s13, s12, 31
	v_and_b32_e32 v3, -16, v3
	v_sub_u32_e32 v2, v2, v4
	s_ashr_i32 s38, s20, 8
	s_lshl_b32 s61, s22, 10
	s_lshl_b64 s[18:19], s[16:17], 20
	s_lshl_b64 s[34:35], s[12:13], 20
	v_add_u32_e32 v3, v14, v3
	v_ashrrev_i16_sdwa v2, v244, sext(v2) dst_sel:DWORD dst_unused:UNUSED_PAD src0_sel:DWORD src1_sel:BYTE_0
	s_add_u32 s36, s59, s34
	v_lshlrev_b32_e32 v5, 5, v13
	v_bfe_i32 v15, v2, 0, 16
	v_lshlrev_b32_e32 v2, 1, v3
	v_lshrrev_b32_e32 v4, 2, v3
	s_addc_u32 s37, s60, s35
	s_add_i32 s17, s61, 0
	v_and_b32_e32 v5, 32, v5
	v_and_b32_e32 v4, 4, v4
	v_and_b32_e32 v6, 3, v14
	v_and_b32_e32 v2, 0xfffd8, v2
	s_add_i32 m0, s17, 0x10000
	v_or3_b32 v2, v6, v4, v2
	v_add_lshl_u32 v4, v5, v15, 1
	global_load_lds_dwordx4 v0, s[36:37]
	s_add_i32 m0, s17, 0x12000
	v_lshl_add_u32 v134, v2, 12, v4
	s_add_u32 s34, s36, 0x20000
	global_load_lds_dwordx4 v134, s[36:37]
	s_addc_u32 s35, s37, 0
	s_add_i32 m0, s17, 0x14000
	v_lshl_add_u32 v132, v3, 12, v4
	global_load_lds_dwordx4 v0, s[34:35]
	s_add_i32 m0, s17, 0x16000
	v_mov_b32_e32 v135, v1
	global_load_lds_dwordx4 v134, s[34:35]
	s_add_u32 s34, s21, s18
	s_addc_u32 s35, s58, s19
	s_add_i32 s62, s17, 0x2000
	s_mov_b32 m0, s17
	s_add_u32 s18, s34, 0x80000
	global_load_lds_dwordx4 v130, s[34:35]
	s_mov_b32 m0, s62
	s_addc_u32 s19, s35, 0
	s_add_i32 s63, s17, 0x4000
	global_load_lds_dwordx4 v132, s[34:35]
	s_mov_b32 m0, s63
	s_add_i32 s81, s17, 0x6000
	global_load_lds_dwordx4 v130, s[18:19]
	s_mov_b32 m0, s81
	v_mov_b32_e32 v131, v1
	global_load_lds_dwordx4 v132, s[18:19]
	v_mov_b32_e32 v133, v1
	s_cmp_eq_u32 s38, 1
	v_lshl_add_u64 v[8:9], s[36:37], 0, v[0:1]
	v_lshl_add_u64 v[6:7], s[36:37], 0, v[134:135]
	v_lshl_add_u64 v[2:3], s[34:35], 0, v[130:131]
	s_cselect_b64 s[18:19], -1, 0
	s_cmp_lg_u32 s38, 1
	v_lshl_add_u64 v[4:5], s[34:35], 0, v[132:133]
	s_cbranch_scc1 .LBB0_660
	s_barrier
	s_setprio 1

; #define PG8_STAGE(bufoff, gbase, voff) do { _Pragma("unroll") for (int _i = 0; _i < 2; ++_i) \
;         __builtin_amdgcn_global_load_lds((const __attribute__((address_space(1))) unsigned*)((const char*)(gbase) + (voff)[_i]), (LAS unsigned*)(lds + (bufoff) + ldsw + _i * 8192), 16, 0, 0); } while (0)
; #define PG8_LDA(dst, b, h) do { _Pragma("unroll") for (int m = 0; m < 4; ++m) _Pragma("unroll") for (int k = 0; k < 2; ++k) dst[m][k] = *(const LAS bf16x8*)(lds + PG8_SA(b, h) + aoff + m * 2048 + k * 1024); } while (0)
; #define PG8_LDB(dst, b, h) do { _Pragma("unroll") for (int n = 0; n < 2; ++n) _Pragma("unroll") for (int k = 0; k < 2; ++k) dst[n][k] = *(const LAS bf16x8*)(lds + PG8_SB(b, h) + boff + n * 2048 + k * 1024); } while (0)
; #define PG8_MMA(ai, bj, At, Bt) do { __builtin_amdgcn_s_setprio(1); _Pragma("unroll") for (int m = 0; m < 4; ++m) _Pragma("unroll") for (int n = 0; n < 2; ++n) _Pragma("unroll") for (int k = 0; k < 2; ++k) \
;         acc[ai][bj][m][n] = __builtin_amdgcn_mfma_f32_16x16x32_bf16(Bt[n][k], At[m][k], acc[ai][bj][m][n], 0, 0, 0); __builtin_amdgcn_s_setprio(0); } while (0)
; #define PG8_WAIT_V(n) asm volatile("s_waitcnt vmcnt(" #n ")" ::: "memory")
; #define PG8_WAIT_L(n) asm volatile("s_waitcnt lgkmcnt(" #n ")" ::: "memory")
; #define PG8_BAR __builtin_amdgcn_s_barrier()
; #define PG8_SCHED __builtin_amdgcn_sched_barrier(0)
; template <class Epi, class SchedT, bool ALIGN_EPI, bool SP2>
; __device__ __forceinline__ void gemm_phase(LAS unsigned char* lds, const int ldk, const int nt, const SchedT& S, const Epi& E) {
;     ...
;             PG8_LDB(B0, 0, 0); PG8_LDB(B1, 0, 1); PG8_SCHED; PG8_LDA(At, 0, 0); PG8_STAGE(PG8_SA(1, 1), a1 + hstep, voffA);
;             PG8_WAIT_V(8); PG8_WAIT_L(0); PG8_BAR; PG8_MMA(0, 0, At, B0); PG8_MMA(0, 1, At, B1); PG8_BAR; PG8_SCHED;
;             PG8_LDA(At, 0, 1); PG8_STAGE(PG8_SB(0, 0), b2, voffB); PG8_STAGE(PG8_SB(0, 1), b2 + hstepB, voffB); PG8_STAGE(PG8_SA(0, 0), a2, voffA);
.LBB0_668:
	s_add_u32 s36, s34, 0xfff80080
	s_addc_u32 s37, s35, -1
	s_add_i32 s51, 0, 0x10000
	s_cmp_eq_u32 s22, 28
	s_cselect_b32 s57, s1, s37
	s_cselect_b32 s56, s0, s36
	v_add_u32_e32 v144, s51, v147
	s_cselect_b32 s37, s55, s20
	s_cselect_b32 s36, s54, s13
	s_add_i32 s53, 0, 0x14000
	ds_read_b128 v[140:143], v144
	ds_read_b128 v[150:153], v144 offset:1024
	ds_read_b128 v[154:157], v144 offset:2048
	ds_read_b128 v[158:161], v144 offset:3072
	v_add_u32_e32 v144, s53, v147
	ds_read_b128 v[174:177], v144
	ds_read_b128 v[178:181], v144 offset:1024
	ds_read_b128 v[182:185], v144 offset:2048
	ds_read_b128 v[186:189], v144 offset:3072
	v_lshl_add_u64 v[144:145], s[34:35], 0, v[136:137]
	s_add_i32 m0, s17, 0xc000
	ds_read_b128 v[190:193], v149
	ds_read_b128 v[194:197], v149 offset:1024
	ds_read_b128 v[198:201], v149 offset:2048
	ds_read_b128 v[202:205], v149 offset:3072
	ds_read_b128 v[206:209], v149 offset:4096
	ds_read_b128 v[210:213], v149 offset:5120
	ds_read_b128 v[214:217], v149 offset:6144
	ds_read_b128 v[218:221], v149 offset:7168
	global_load_lds_dwordx4 v[144:145], off
	v_lshl_add_u64 v[144:145], s[34:35], 0, v[138:139]
	s_add_i32 m0, s17, 0xe000
	s_nop 0
	global_load_lds_dwordx4 v[144:145], off
	s_waitcnt vmcnt(8)
	s_waitcnt lgkmcnt(0)
	s_barrier
	s_waitcnt lgkmcnt(0)
	v_mfma_f32_16x16x32_bf16 v[126:129], v[140:143], v[190:193], v[126:129]
	v_mfma_f32_16x16x32_bf16 v[122:125], v[154:157], v[190:193], v[122:125]
	v_mfma_f32_16x16x32_bf16 v[110:113], v[140:143], v[198:201], v[110:113]
	v_mfma_f32_16x16x32_bf16 v[106:109], v[154:157], v[198:201], v[106:109]
	v_mfma_f32_16x16x32_bf16 v[94:97], v[140:143], v[206:209], v[94:97]
	v_mfma_f32_16x16x32_bf16 v[90:93], v[154:157], v[206:209], v[90:93]
	v_mfma_f32_16x16x32_bf16 v[78:81], v[140:143], v[214:217], v[78:81]
	v_mfma_f32_16x16x32_bf16 v[74:77], v[154:157], v[214:217], v[74:77]
	v_mfma_f32_16x16x32_bf16 v[126:129], v[150:153], v[194:197], v[126:129]
	v_mfma_f32_16x16x32_bf16 v[122:125], v[158:161], v[194:197], v[122:125]
	v_mfma_f32_16x16x32_bf16 v[110:113], v[150:153], v[202:205], v[110:113]
	v_mfma_f32_16x16x32_bf16 v[106:109], v[158:161], v[202:205], v[106:109]
	v_mfma_f32_16x16x32_bf16 v[94:97], v[150:153], v[210:213], v[94:97]
	v_mfma_f32_16x16x32_bf16 v[90:93], v[158:161], v[210:213], v[90:93]
	v_mfma_f32_16x16x32_bf16 v[78:81], v[150:153], v[218:221], v[78:81]
	v_mfma_f32_16x16x32_bf16 v[74:77], v[158:161], v[218:221], v[74:77]
	v_mfma_f32_16x16x32_bf16 v[118:121], v[174:177], v[190:193], v[118:121]
	v_mfma_f32_16x16x32_bf16 v[114:117], v[182:185], v[190:193], v[114:117]
	v_mfma_f32_16x16x32_bf16 v[102:105], v[174:177], v[198:201], v[102:105]
	v_mfma_f32_16x16x32_bf16 v[98:101], v[182:185], v[198:201], v[98:101]
	v_mfma_f32_16x16x32_bf16 v[86:89], v[174:177], v[206:209], v[86:89]
	v_mfma_f32_16x16x32_bf16 v[82:85], v[182:185], v[206:209], v[82:85]
	v_mfma_f32_16x16x32_bf16 v[70:73], v[174:177], v[214:217], v[70:73]
	v_mfma_f32_16x16x32_bf16 v[66:69], v[182:185], v[214:217], v[66:69]
	v_mfma_f32_16x16x32_bf16 v[118:121], v[178:181], v[194:197], v[118:121]
	v_mfma_f32_16x16x32_bf16 v[114:117], v[186:189], v[194:197], v[114:117]
	v_mfma_f32_16x16x32_bf16 v[102:105], v[178:181], v[202:205], v[102:105]
	v_mfma_f32_16x16x32_bf16 v[98:101], v[186:189], v[202:205], v[98:101]
	v_mfma_f32_16x16x32_bf16 v[86:89], v[178:181], v[210:213], v[86:89]
	v_mfma_f32_16x16x32_bf16 v[82:85], v[186:189], v[210:213], v[82:85]
	v_mfma_f32_16x16x32_bf16 v[70:73], v[178:181], v[218:221], v[70:73]
	v_mfma_f32_16x16x32_bf16 v[66:69], v[186:189], v[218:221], v[66:69]
	s_barrier
	s_add_i32 s51, s51, s61
	v_lshl_add_u64 v[144:145], s[36:37], 0, v[0:1]
	s_mov_b32 m0, s51
	ds_read_b128 v[190:193], v149 offset:16384
	ds_read_b128 v[194:197], v149 offset:17408
	ds_read_b128 v[198:201], v149 offset:18432
	ds_read_b128 v[202:205], v149 offset:19456
	ds_read_b128 v[206:209], v149 offset:20480
	ds_read_b128 v[210:213], v149 offset:21504
	ds_read_b128 v[214:217], v149 offset:22528
	ds_read_b128 v[218:221], v149 offset:23552
	global_load_lds_dwordx4 v[144:145], off
	s_add_i32 m0, s51, 0x2000
	s_add_u32 s86, s36, 0x20000
	v_lshl_add_u64 v[222:223], s[36:37], 0, v[134:135]
	s_addc_u32 s87, s37, 0
	s_add_i32 s51, s53, s61
	global_load_lds_dwordx4 v[222:223], off
	v_lshl_add_u64 v[224:225], s[86:87], 0, v[0:1]
	s_mov_b32 m0, s51
	v_lshl_add_u64 v[226:227], s[56:57], 0, v[132:133]
	global_load_lds_dwordx4 v[224:225], off
	v_lshl_add_u64 v[224:225], s[86:87], 0, v[134:135]
	s_add_i32 m0, s51, 0x2000
	s_nop 0
	global_load_lds_dwordx4 v[224:225], off
	v_lshl_add_u64 v[224:225], s[56:57], 0, v[130:131]
	s_mov_b32 m0, s17
	s_nop 0
	global_load_lds_dwordx4 v[224:225], off
	s_mov_b32 m0, s62
	s_nop 0
	global_load_lds_dwordx4 v[226:227], off
	s_waitcnt vmcnt(8)
	s_waitcnt lgkmcnt(0)
	s_barrier
; #define PG8_STAGE(bufoff, gbase, voff) do { _Pragma("unroll") for (int _i = 0; _i < 2; ++_i) \
;         __builtin_amdgcn_global_load_lds((const __attribute__((address_space(1))) unsigned*)((const char*)(gbase) + (voff)[_i]), (LAS unsigned*)(lds + (bufoff) + ldsw + _i * 8192), 16, 0, 0); } while (0)
; #define PG8_LDA(dst, b, h) do { _Pragma("unroll") for (int m = 0; m < 4; ++m) _Pragma("unroll") for (int k = 0; k < 2; ++k) dst[m][k] = *(const LAS bf16x8*)(lds + PG8_SA(b, h) + aoff + m * 2048 + k * 1024); } while (0)
; #define PG8_LDB(dst, b, h) do { _Pragma("unroll") for (int n = 0; n < 2; ++n) _Pragma("unroll") for (int k = 0; k < 2; ++k) dst[n][k] = *(const LAS bf16x8*)(lds + PG8_SB(b, h) + boff + n * 2048 + k * 1024); } while (0)
; #define PG8_MMA(ai, bj, At, Bt) do { __builtin_amdgcn_s_setprio(1); _Pragma("unroll") for (int m = 0; m < 4; ++m) _Pragma("unroll") for (int n = 0; n < 2; ++n) _Pragma("unroll") for (int k = 0; k < 2; ++k) \
;         acc[ai][bj][m][n] = __builtin_amdgcn_mfma_f32_16x16x32_bf16(Bt[n][k], At[m][k], acc[ai][bj][m][n], 0, 0, 0); __builtin_amdgcn_s_setprio(0); } while (0)
; #define PG8_WAIT_V(n) asm volatile("s_waitcnt vmcnt(" #n ")" ::: "memory")
; #define PG8_WAIT_L(n) asm volatile("s_waitcnt lgkmcnt(" #n ")" ::: "memory")
; #define PG8_BAR __builtin_amdgcn_s_barrier()
; #define PG8_SCHED __builtin_amdgcn_sched_barrier(0)
; template <class Epi, class SchedT, bool ALIGN_EPI, bool SP2>
; __device__ __forceinline__ void gemm_phase(LAS unsigned char* lds, const int ldk, const int nt, const SchedT& S, const Epi& E) {
;     ...
;             PG8_WAIT_V(8); PG8_WAIT_L(0); PG8_BAR; PG8_MMA(1, 0, At, B0); PG8_MMA(1, 1, At, B1); PG8_BAR; PG8_SCHED;
;             PG8_LDB(B0, 1, 0); PG8_LDB(B1, 1, 1); PG8_SCHED; PG8_LDA(At, 1, 0); PG8_STAGE(PG8_SA(0, 1), a2 + hstep, voffA);
;             PG8_WAIT_V(8); PG8_WAIT_L(0); PG8_BAR; PG8_MMA(0, 0, At, B0); PG8_MMA(0, 1, At, B1); PG8_BAR; PG8_SCHED;
	s_waitcnt lgkmcnt(0)
	v_mfma_f32_16x16x32_bf16 v[62:65], v[140:143], v[190:193], v[62:65]
	v_mfma_f32_16x16x32_bf16 v[58:61], v[154:157], v[190:193], v[58:61]
	v_mfma_f32_16x16x32_bf16 v[46:49], v[140:143], v[198:201], v[46:49]
	v_mfma_f32_16x16x32_bf16 v[42:45], v[154:157], v[198:201], v[42:45]
	v_mfma_f32_16x16x32_bf16 v[30:33], v[140:143], v[206:209], v[30:33]
	v_mfma_f32_16x16x32_bf16 v[26:29], v[154:157], v[206:209], v[26:29]
	v_mfma_f32_16x16x32_bf16 v[14:17], v[140:143], v[214:217], v[14:17]
	v_mfma_f32_16x16x32_bf16 v[10:13], v[154:157], v[214:217], v[10:13]
	v_mfma_f32_16x16x32_bf16 v[62:65], v[150:153], v[194:197], v[62:65]
	v_mfma_f32_16x16x32_bf16 v[58:61], v[158:161], v[194:197], v[58:61]
	v_mfma_f32_16x16x32_bf16 v[46:49], v[150:153], v[202:205], v[46:49]
	v_mfma_f32_16x16x32_bf16 v[42:45], v[158:161], v[202:205], v[42:45]
	v_mfma_f32_16x16x32_bf16 v[30:33], v[150:153], v[210:213], v[30:33]
	v_mfma_f32_16x16x32_bf16 v[26:29], v[158:161], v[210:213], v[26:29]
	v_mfma_f32_16x16x32_bf16 v[14:17], v[150:153], v[218:221], v[14:17]
	v_mfma_f32_16x16x32_bf16 v[10:13], v[158:161], v[218:221], v[10:13]
	v_mfma_f32_16x16x32_bf16 v[54:57], v[174:177], v[190:193], v[54:57]
	v_mfma_f32_16x16x32_bf16 v[50:53], v[182:185], v[190:193], v[50:53]
	v_mfma_f32_16x16x32_bf16 v[38:41], v[174:177], v[198:201], v[38:41]
	v_mfma_f32_16x16x32_bf16 v[34:37], v[182:185], v[198:201], v[34:37]
	v_mfma_f32_16x16x32_bf16 v[22:25], v[174:177], v[206:209], v[22:25]
	v_mfma_f32_16x16x32_bf16 v[18:21], v[182:185], v[206:209], v[18:21]
	v_mfma_f32_16x16x32_bf16 v[6:9], v[174:177], v[214:217], v[6:9]
	v_mfma_f32_16x16x32_bf16 v[2:5], v[182:185], v[214:217], v[2:5]
	v_mfma_f32_16x16x32_bf16 v[54:57], v[178:181], v[194:197], v[54:57]
	v_mfma_f32_16x16x32_bf16 v[50:53], v[186:189], v[194:197], v[50:53]
	v_mfma_f32_16x16x32_bf16 v[38:41], v[178:181], v[202:205], v[38:41]
	v_mfma_f32_16x16x32_bf16 v[34:37], v[186:189], v[202:205], v[34:37]
	v_mfma_f32_16x16x32_bf16 v[22:25], v[178:181], v[210:213], v[22:25]
	v_mfma_f32_16x16x32_bf16 v[18:21], v[186:189], v[210:213], v[18:21]
	v_mfma_f32_16x16x32_bf16 v[6:9], v[178:181], v[218:221], v[6:9]
	v_mfma_f32_16x16x32_bf16 v[2:5], v[186:189], v[218:221], v[2:5]
	s_barrier
	s_add_i32 s51, 0, 0x18000
	s_add_i32 s53, 0, 0x1c000
	v_add_u32_e32 v158, s51, v147
	v_add_u32_e32 v186, s53, v147
	ds_read_b128 v[140:143], v158
	ds_read_b128 v[150:153], v158 offset:1024
	ds_read_b128 v[154:157], v158 offset:2048
	ds_read_b128 v[158:161], v158 offset:3072
	ds_read_b128 v[174:177], v186
	ds_read_b128 v[178:181], v186 offset:1024
	ds_read_b128 v[182:185], v186 offset:2048
	ds_read_b128 v[186:189], v186 offset:3072
	s_add_u32 s56, s56, 0x80000
	s_addc_u32 s57, s57, 0
	s_mov_b32 m0, s63
	v_lshl_add_u64 v[228:229], s[56:57], 0, v[130:131]
	ds_read_b128 v[190:193], v149 offset:32768
	ds_read_b128 v[194:197], v149 offset:33792
	ds_read_b128 v[198:201], v149 offset:34816
	ds_read_b128 v[202:205], v149 offset:35840
	ds_read_b128 v[206:209], v149 offset:36864
	ds_read_b128 v[210:213], v149 offset:37888
	ds_read_b128 v[214:217], v149 offset:38912
	ds_read_b128 v[218:221], v149 offset:39936
	global_load_lds_dwordx4 v[228:229], off
	v_lshl_add_u64 v[228:229], s[56:57], 0, v[132:133]
	s_mov_b32 m0, s81
	s_nop 0
	global_load_lds_dwordx4 v[228:229], off
	s_waitcnt vmcnt(8)
	s_waitcnt lgkmcnt(0)
	s_barrier
	s_waitcnt lgkmcnt(0)
	v_mfma_f32_16x16x32_bf16 v[126:129], v[140:143], v[190:193], v[126:129]
	v_mfma_f32_16x16x32_bf16 v[122:125], v[154:157], v[190:193], v[122:125]
	v_mfma_f32_16x16x32_bf16 v[110:113], v[140:143], v[198:201], v[110:113]
	v_mfma_f32_16x16x32_bf16 v[106:109], v[154:157], v[198:201], v[106:109]
	v_mfma_f32_16x16x32_bf16 v[94:97], v[140:143], v[206:209], v[94:97]
	v_mfma_f32_16x16x32_bf16 v[90:93], v[154:157], v[206:209], v[90:93]
	v_mfma_f32_16x16x32_bf16 v[78:81], v[140:143], v[214:217], v[78:81]
	v_mfma_f32_16x16x32_bf16 v[74:77], v[154:157], v[214:217], v[74:77]
	v_mfma_f32_16x16x32_bf16 v[126:129], v[150:153], v[194:197], v[126:129]
	v_mfma_f32_16x16x32_bf16 v[122:125], v[158:161], v[194:197], v[122:125]
	v_mfma_f32_16x16x32_bf16 v[110:113], v[150:153], v[202:205], v[110:113]
	v_mfma_f32_16x16x32_bf16 v[106:109], v[158:161], v[202:205], v[106:109]
	v_mfma_f32_16x16x32_bf16 v[94:97], v[150:153], v[210:213], v[94:97]
	v_mfma_f32_16x16x32_bf16 v[90:93], v[158:161], v[210:213], v[90:93]
	v_mfma_f32_16x16x32_bf16 v[78:81], v[150:153], v[218:221], v[78:81]
	v_mfma_f32_16x16x32_bf16 v[74:77], v[158:161], v[218:221], v[74:77]
	v_mfma_f32_16x16x32_bf16 v[118:121], v[174:177], v[190:193], v[118:121]
	v_mfma_f32_16x16x32_bf16 v[114:117], v[182:185], v[190:193], v[114:117]
	v_mfma_f32_16x16x32_bf16 v[102:105], v[174:177], v[198:201], v[102:105]
	v_mfma_f32_16x16x32_bf16 v[98:101], v[182:185], v[198:201], v[98:101]
	v_mfma_f32_16x16x32_bf16 v[86:89], v[174:177], v[206:209], v[86:89]
	v_mfma_f32_16x16x32_bf16 v[82:85], v[182:185], v[206:209], v[82:85]
	v_mfma_f32_16x16x32_bf16 v[70:73], v[174:177], v[214:217], v[70:73]
	v_mfma_f32_16x16x32_bf16 v[66:69], v[182:185], v[214:217], v[66:69]
	v_mfma_f32_16x16x32_bf16 v[118:121], v[178:181], v[194:197], v[118:121]
	v_mfma_f32_16x16x32_bf16 v[114:117], v[186:189], v[194:197], v[114:117]
	v_mfma_f32_16x16x32_bf16 v[102:105], v[178:181], v[202:205], v[102:105]
	v_mfma_f32_16x16x32_bf16 v[98:101], v[186:189], v[202:205], v[98:101]
	v_mfma_f32_16x16x32_bf16 v[86:89], v[178:181], v[210:213], v[86:89]
	v_mfma_f32_16x16x32_bf16 v[82:85], v[186:189], v[210:213], v[82:85]
	v_mfma_f32_16x16x32_bf16 v[70:73], v[178:181], v[218:221], v[70:73]
	v_mfma_f32_16x16x32_bf16 v[66:69], v[186:189], v[218:221], v[66:69]
	s_barrier
; __device__ __forceinline__ float bf_lo(unsigned w) { return __uint_as_float(w << 16); }
; __device__ __forceinline__ float bf_hi(unsigned w) { return __uint_as_float(w & 0xffff0000u); }
; __device__ __forceinline__ u32x4 pack8(f32x4 a, f32x4 b) { u32x4 w; w.x = cvt_pk_bf16(a[0], a[1]); w.y = cvt_pk_bf16(a[2], a[3]); w.z = cvt_pk_bf16(b[0], b[1]); w.w = cvt_pk_bf16(b[2], b[3]); return w; }
; #define PG8_STAGE(bufoff, gbase, voff) do { _Pragma("unroll") for (int _i = 0; _i < 2; ++_i) \
;         __builtin_amdgcn_global_load_lds((const __attribute__((address_space(1))) unsigned*)((const char*)(gbase) + (voff)[_i]), (LAS unsigned*)(lds + (bufoff) + ldsw + _i * 8192), 16, 0, 0); } while (0)
; #define PG8_WAIT_V(n) asm volatile("s_waitcnt vmcnt(" #n ")" ::: "memory")
; template <class Epi, class SchedT, bool ALIGN_EPI, bool SP2>
; __device__ __forceinline__ void gemm_phase(LAS unsigned char* lds, const int ldk, const int nt, const SchedT& S, const Epi& E) {
;     ...
;             PG8_LDA(At, 1, 1); PG8_STAGE(PG8_SB(1, 0), b3, voffB); PG8_STAGE(PG8_SB(1, 1), b3 + hstepB, voffB); PG8_STAGE(PG8_SA(1, 0), a3, voffA);
;             PG8_WAIT_V(8); PG8_WAIT_L(0); PG8_BAR; PG8_MMA(1, 0, At, B0); PG8_MMA(1, 1, At, B1); PG8_BAR; PG8_SCHED;
;     __device__ __forceinline__ void operator()(f32x4 (&acc)[2][2][4][2], const Unit& u, int wr, int wc, int fr, int fq) const {
;         const int row0 = u.pm * BM + wr * 64 + fr, col0 = u.pn * BM + wc * 64 + 8 * fq;
; #pragma unroll
;         for (int ai = 0; ai < 2; ++ai)
; #pragma unroll
;             for (int m = 0; m < 4; ++m) {
;                 const int row = row0 + ai * HALF + m * 16; float sq = 0.f;
; #pragma unroll
;                 for (int bj = 0; bj < 2; ++bj) {
;                     const size_t off = (size_t)row * D + col0 + bj * 32;
;                     const u32x4 xw = *(const u32x4*)(xin + off);
;                     const f32x4 v0 = acc[ai][bj][m][0] + (f32x4){bf_lo(xw.x), bf_hi(xw.x), bf_lo(xw.y), bf_hi(xw.y)}, v1 = acc[ai][bj][m][1] + (f32x4){bf_lo(xw.z), bf_hi(xw.z), bf_lo(xw.w), bf_hi(xw.w)};
;                     *(u32x4*)(xb + off) = pack8(v0, v1);
;                     sq += (v0[0] * v0[0] + v0[1] * v0[1]) + (v0[2] * v0[2] + v0[3] * v0[3]) + (v1[0] * v1[0] + v1[1] * v1[1]) + (v1[2] * v1[2] + v1[3] * v1[3]);
;                 }
;                 sq += __shfl_xor(sq, 16); sq += __shfl_xor(sq, 32);
	s_add_i32 s51, s51, s61
	v_lshl_add_u64 v[144:145], v[144:145], 0, s[24:25]
	s_mov_b32 m0, s51
	ds_read_b128 v[190:193], v149 offset:49152
	ds_read_b128 v[194:197], v149 offset:50176
	ds_read_b128 v[198:201], v149 offset:51200
	ds_read_b128 v[202:205], v149 offset:52224
	ds_read_b128 v[206:209], v149 offset:53248
	ds_read_b128 v[210:213], v149 offset:54272
	ds_read_b128 v[214:217], v149 offset:55296
	ds_read_b128 v[218:221], v149 offset:56320
	global_load_lds_dwordx4 v[144:145], off
	s_add_i32 m0, s51, 0x2000
	s_add_u32 s36, s36, 0x20080
	v_lshl_add_u64 v[144:145], v[222:223], 0, s[24:25]
	s_addc_u32 s37, s37, 0
	s_add_i32 s51, s53, s61
	global_load_lds_dwordx4 v[144:145], off
	v_lshl_add_u64 v[144:145], s[36:37], 0, v[0:1]
	s_mov_b32 m0, s51
	s_nop 0
	global_load_lds_dwordx4 v[144:145], off
	v_lshl_add_u64 v[144:145], s[36:37], 0, v[134:135]
	s_add_i32 m0, s51, 0x2000
	s_nop 0
	global_load_lds_dwordx4 v[144:145], off
	v_lshl_add_u64 v[144:145], v[224:225], 0, s[24:25]
	s_mov_b32 m0, s83
	s_nop 0
	global_load_lds_dwordx4 v[144:145], off
	v_lshl_add_u64 v[144:145], v[226:227], 0, s[24:25]
	s_mov_b32 m0, s84
	s_nop 0
	global_load_lds_dwordx4 v[144:145], off
	s_waitcnt vmcnt(8)
	s_waitcnt lgkmcnt(0)
	s_barrier
	s_waitcnt lgkmcnt(0)
	v_mfma_f32_16x16x32_bf16 v[62:65], v[140:143], v[190:193], v[62:65]
	v_mfma_f32_16x16x32_bf16 v[58:61], v[154:157], v[190:193], v[58:61]
	v_mfma_f32_16x16x32_bf16 v[46:49], v[140:143], v[198:201], v[46:49]
	v_mfma_f32_16x16x32_bf16 v[42:45], v[154:157], v[198:201], v[42:45]
	v_mfma_f32_16x16x32_bf16 v[30:33], v[140:143], v[206:209], v[30:33]
	v_mfma_f32_16x16x32_bf16 v[26:29], v[154:157], v[206:209], v[26:29]
	v_mfma_f32_16x16x32_bf16 v[14:17], v[140:143], v[214:217], v[14:17]
	v_mfma_f32_16x16x32_bf16 v[10:13], v[154:157], v[214:217], v[10:13]
	v_mfma_f32_16x16x32_bf16 v[62:65], v[150:153], v[194:197], v[62:65]
	v_mfma_f32_16x16x32_bf16 v[58:61], v[158:161], v[194:197], v[58:61]
	v_mfma_f32_16x16x32_bf16 v[46:49], v[150:153], v[202:205], v[46:49]
	v_mfma_f32_16x16x32_bf16 v[42:45], v[158:161], v[202:205], v[42:45]
	v_mfma_f32_16x16x32_bf16 v[30:33], v[150:153], v[210:213], v[30:33]
	v_mfma_f32_16x16x32_bf16 v[26:29], v[158:161], v[210:213], v[26:29]
	v_mfma_f32_16x16x32_bf16 v[14:17], v[150:153], v[218:221], v[14:17]
	v_mfma_f32_16x16x32_bf16 v[10:13], v[158:161], v[218:221], v[10:13]
	v_mfma_f32_16x16x32_bf16 v[54:57], v[174:177], v[190:193], v[54:57]
	v_mfma_f32_16x16x32_bf16 v[50:53], v[182:185], v[190:193], v[50:53]
	v_mfma_f32_16x16x32_bf16 v[38:41], v[174:177], v[198:201], v[38:41]
	v_mfma_f32_16x16x32_bf16 v[34:37], v[182:185], v[198:201], v[34:37]
	v_mfma_f32_16x16x32_bf16 v[22:25], v[174:177], v[206:209], v[22:25]
	v_mfma_f32_16x16x32_bf16 v[18:21], v[182:185], v[206:209], v[18:21]
	v_mfma_f32_16x16x32_bf16 v[6:9], v[174:177], v[214:217], v[6:9]
	v_mfma_f32_16x16x32_bf16 v[2:5], v[182:185], v[214:217], v[2:5]
	v_mfma_f32_16x16x32_bf16 v[54:57], v[178:181], v[194:197], v[54:57]
	v_mfma_f32_16x16x32_bf16 v[50:53], v[186:189], v[194:197], v[50:53]
	v_mfma_f32_16x16x32_bf16 v[38:41], v[178:181], v[202:205], v[38:41]
	v_mfma_f32_16x16x32_bf16 v[34:37], v[186:189], v[202:205], v[34:37]
	v_mfma_f32_16x16x32_bf16 v[22:25], v[178:181], v[210:213], v[22:25]
	v_mfma_f32_16x16x32_bf16 v[18:21], v[186:189], v[210:213], v[18:21]
	v_mfma_f32_16x16x32_bf16 v[6:9], v[178:181], v[218:221], v[6:9]
	v_mfma_f32_16x16x32_bf16 v[2:5], v[186:189], v[218:221], v[2:5]
	s_barrier
	s_add_i32 s22, s22, 2
	s_add_u32 s34, s34, 0x100
	s_addc_u32 s35, s35, 0
	s_add_u32 s13, s13, 0x100
	s_addc_u32 s20, s20, 0
	s_cmp_gt_u32 s22, 29
	s_cbranch_scc0 .LBB0_668
	v_lshl_add_u32 v142, s16, 8, v146
	v_lshl_or_b32 v140, s12, 8, v148
	v_lshlrev_b32_e32 v141, 12, v142
	v_lshl_add_u32 v150, v140, 1, v141
	v_add_u32_e32 v151, 0x10000, v150
	v_add_u32_e32 v152, 0x20000, v150
	v_add_u32_e32 v153, 0x30000, v150
	v_add_u32_e32 v154, 0x80000, v150
	v_add_u32_e32 v155, 0x90000, v150
	v_add_u32_e32 v156, 0xa0000, v150
	v_add_u32_e32 v157, 0xb0000, v150
	global_load_dwordx4 v[174:177], v150, s[42:43]
	global_load_dwordx4 v[178:181], v150, s[42:43] offset:64
	global_load_dwordx4 v[182:185], v151, s[42:43]
	global_load_dwordx4 v[186:189], v151, s[42:43] offset:64
	global_load_dwordx4 v[190:193], v152, s[42:43]
	global_load_dwordx4 v[194:197], v152, s[42:43] offset:64
	global_load_dwordx4 v[198:201], v153, s[42:43]
	global_load_dwordx4 v[202:205], v153, s[42:43] offset:64
	global_load_dwordx4 v[206:209], v154, s[42:43]
	global_load_dwordx4 v[210:213], v154, s[42:43] offset:64
	global_load_dwordx4 v[214:217], v155, s[42:43]
	global_load_dwordx4 v[218:221], v155, s[42:43] offset:64
	global_load_dwordx4 v[222:225], v156, s[42:43]
	global_load_dwordx4 v[226:229], v156, s[42:43] offset:64
	global_load_dwordx4 v[230:233], v157, s[42:43]
	global_load_dwordx4 v[234:237], v157, s[42:43] offset:64
	s_lshl_b32 s56, s12, 4
	s_lshl_b32 s22, s82, 2
	s_add_i32 s56, s56, s22
	v_lshl_add_u32 v158, v142, 7, s56
	v_add_u32_e32 v159, 0x1000, v158
	v_add_u32_e32 v160, 0x4000, v158
	v_add_u32_e32 v161, 0x5000, v158
	v_xor_b32_e32 v239, 16, v241
	v_xor_b32_e32 v252, 32, v241
	v_lshlrev_b32_e32 v239, 2, v239
	v_lshlrev_b32_e32 v252, 2, v252
	s_and_b64 vcc, exec, s[48:49]
	s_cbranch_vccz .LBB0_671
	s_barrier

; #define PG8_STAGE(bufoff, gbase, voff) do { _Pragma("unroll") for (int _i = 0; _i < 2; ++_i) \
;         __builtin_amdgcn_global_load_lds((const __attribute__((address_space(1))) unsigned*)((const char*)(gbase) + (voff)[_i]), (LAS unsigned*)(lds + (bufoff) + ldsw + _i * 8192), 16, 0, 0); } while (0)
; #define PG8_BAR __builtin_amdgcn_s_barrier()
; template <class Epi, class SchedT, bool ALIGN_EPI, bool SP2>
; __device__ __forceinline__ void gemm_phase(LAS unsigned char* lds, const int ldk, const int nt, const SchedT& S, const Epi& E) {
;     ...
;     for (int i = 0; i < 2; ++i) { int R, C; stage_rc(tid * 16 + i * 8192, R, C); const int Rb = 2 * (R & ~31) + perm32(R & 31);
;         voffA[i] = (unsigned)(R * K + C) * 2u; voffB[i] = (unsigned)(Rb * K + C) * 2u; }
;     ...
;         PG8_STAGE(PG8_SB(0, 0), cB, voffB); PG8_STAGE(PG8_SB(0, 1), cB + hstepB, voffB); PG8_STAGE(PG8_SA(0, 0), cA, voffA); PG8_STAGE(PG8_SA(0, 1), cA + hstep, voffA);
;         if (wr == 1) PG8_BAR;
.LBB0_741:
	v_readlane_b32 s18, v163, 39
	v_readlane_b32 s44, v254, 1
	s_mul_i32 s13, s18, 0x20400
	v_readlane_b32 s52, v254, 9
	v_readlane_b32 s19, v163, 40
	s_mov_b32 s20, s18
	v_readlane_b32 s53, v254, 10
	s_add_u32 s18, s52, s13
	v_readlane_b32 s54, v254, 11
	s_addc_u32 s19, s53, 0
	s_mul_i32 s13, s20, 0xac00
	v_readlane_b32 s55, v254, 12
	s_add_u32 s20, s54, s13
	s_addc_u32 s21, s55, 0
	s_and_b64 vcc, exec, s[0:1]
	v_readlane_b32 s45, v254, 2
	v_readlane_b32 s46, v254, 3
	v_readlane_b32 s47, v254, 4
	v_readlane_b32 s48, v254, 5
	v_readlane_b32 s49, v254, 6
	v_readlane_b32 s50, v254, 7
	v_readlane_b32 s51, v254, 8
	v_readlane_b32 s56, v254, 13
	v_readlane_b32 s57, v254, 14
	v_readlane_b32 s58, v254, 15
	v_readlane_b32 s59, v254, 16
	s_cbranch_vccnz .LBB0_791
	v_ashrrev_i32_e32 v0, 31, v16
	v_lshrrev_b32_e32 v0, 26, v0
	v_add_u32_e32 v0, v16, v0
	v_ashrrev_i32_e32 v10, 6, v0
	v_bfe_i32 v0, v16, 27, 1
	v_lshlrev_b32_e32 v2, 4, v16
	v_lshrrev_b32_e32 v0, 22, v0
	v_add_u32_e32 v0, v2, v0
	v_and_b32_e32 v0, 0xfffffc00, v0
	v_sub_u32_e32 v0, v2, v0
	v_lshrrev_b32_e32 v3, 4, v0
	v_bitop3_b32 v0, v3, v0, 32 bitop3:0x6c
	v_ashrrev_i32_e32 v4, 31, v0
	v_lshrrev_b32_e32 v4, 26, v4
	v_add_u32_e32 v4, v0, v4
	v_lshlrev_b32_e32 v3, 3, v10
	v_ashrrev_i32_e32 v11, 6, v4
	v_and_b32_e32 v4, 0xc0, v4
	v_and_b32_e32 v3, -16, v3
	v_sub_u32_e32 v0, v0, v4
	v_add_u32_e32 v3, v11, v3
	v_ashrrev_i16_sdwa v0, v244, sext(v0) dst_sel:DWORD dst_unused:UNUSED_PAD src0_sel:DWORD src1_sel:BYTE_0
	v_lshlrev_b32_e32 v5, 5, v10
	v_bfe_i32 v12, v0, 0, 16
	v_lshlrev_b32_e32 v0, 1, v3
	v_lshrrev_b32_e32 v4, 2, v3
	v_and_b32_e32 v5, 32, v5
	v_and_b32_e32 v4, 4, v4
	v_and_b32_e32 v6, 3, v11
	v_and_b32_e32 v0, 0xfffd8, v0
	v_or3_b32 v0, v6, v4, v0
	v_add_lshl_u32 v4, v5, v12, 1
	v_add_u32_e32 v2, 0x2000, v2
	v_lshl_add_u32 v146, v3, 12, v4
	v_ashrrev_i32_e32 v3, 31, v2
	v_lshrrev_b32_e32 v3, 22, v3
	v_add_u32_e32 v3, v2, v3
	v_ashrrev_i32_e32 v13, 10, v3
	v_mul_i32_i24_e32 v3, 0x400, v13
	v_readlane_b32 s0, v163, 36
	v_sub_u32_e32 v2, v2, v3
	s_add_u32 s0, s38, s0
	v_lshrrev_b32_e32 v3, 4, v2
	s_addc_u32 s1, s39, 0
	v_bitop3_b32 v2, v3, v2, 32 bitop3:0x6c
	s_add_u32 s22, s38, 0x10c00000
	v_lshl_add_u32 v0, v0, 12, v4
	v_ashrrev_i32_e32 v4, 31, v2
	s_addc_u32 s81, s39, 0
	v_lshrrev_b32_e32 v4, 26, v4
	s_add_u32 s82, s0, 0x3600000
	v_add_u32_e32 v4, v2, v4
	s_addc_u32 s83, s1, 0
	v_lshlrev_b32_e32 v3, 3, v13
	v_ashrrev_i32_e32 v14, 6, v4
	v_and_b32_e32 v4, 0xc0, v4
	s_ashr_i32 s41, s40, 6
	s_ashr_i32 s13, s12, 31
	s_ashr_i32 s17, s16, 31
	s_ashr_i32 s50, s40, 8
	v_and_b32_e32 v3, -16, v3
	v_sub_u32_e32 v2, v2, v4
	s_lshl_b32 s84, s41, 10
	s_lshl_b64 s[0:1], s[12:13], 20
	s_lshl_b64 s[34:35], s[16:17], 20
	v_add_u32_e32 v3, v14, v3
	v_ashrrev_i16_sdwa v2, v244, sext(v2) dst_sel:DWORD dst_unused:UNUSED_PAD src0_sel:DWORD src1_sel:BYTE_0
	s_add_u32 s36, s82, s34
	v_lshlrev_b32_e32 v5, 5, v13
	v_bfe_i32 v15, v2, 0, 16
	v_lshlrev_b32_e32 v2, 1, v3
	v_lshrrev_b32_e32 v4, 2, v3
	s_addc_u32 s37, s83, s35
	s_add_i32 s85, s84, 0
	v_and_b32_e32 v5, 32, v5
	v_and_b32_e32 v4, 4, v4
	v_and_b32_e32 v6, 3, v14
	v_and_b32_e32 v2, 0xfffd8, v2
	s_add_i32 m0, s85, 0x10000
	v_or3_b32 v2, v6, v4, v2
	v_add_lshl_u32 v4, v5, v15, 1
	global_load_lds_dwordx4 v0, s[36:37]
	s_add_i32 m0, s85, 0x12000
	v_lshl_add_u32 v150, v2, 12, v4
	s_add_u32 s34, s36, 0x20000
	global_load_lds_dwordx4 v150, s[36:37]
	s_addc_u32 s35, s37, 0
	s_add_i32 m0, s85, 0x14000
	v_lshl_add_u32 v148, v3, 12, v4
	global_load_lds_dwordx4 v0, s[34:35]
	s_add_i32 m0, s85, 0x16000
	v_mov_b32_e32 v151, v1
	global_load_lds_dwordx4 v150, s[34:35]
	s_add_u32 s34, s22, s0
	s_addc_u32 s35, s81, s1
	s_add_i32 s86, s85, 0x2000
	s_mov_b32 m0, s85
	s_add_u32 s0, s34, 0x80000
	global_load_lds_dwordx4 v146, s[34:35]
	s_mov_b32 m0, s86
	s_addc_u32 s1, s35, 0
	s_add_i32 s87, s85, 0x4000
	global_load_lds_dwordx4 v148, s[34:35]
	s_mov_b32 m0, s87
	s_add_i32 s88, s85, 0x6000
	global_load_lds_dwordx4 v146, s[0:1]
	s_mov_b32 m0, s88
	v_mov_b32_e32 v147, v1
	global_load_lds_dwordx4 v148, s[0:1]
	v_mov_b32_e32 v149, v1
	s_cmp_eq_u32 s50, 1
	v_mov_b32_e32 v162, v242
	v_lshl_add_u64 v[8:9], s[36:37], 0, v[0:1]
	v_lshl_add_u64 v[6:7], s[36:37], 0, v[150:151]
	v_lshl_add_u64 v[2:3], s[34:35], 0, v[146:147]
	s_cselect_b64 s[52:53], -1, 0
	s_cmp_lg_u32 s50, 1
	v_lshl_add_u64 v[4:5], s[34:35], 0, v[148:149]
	s_cbranch_scc1 .LBB0_744
	s_barrier
	s_setprio 1

; #define PG8_STAGE(bufoff, gbase, voff) do { _Pragma("unroll") for (int _i = 0; _i < 2; ++_i) \
;         __builtin_amdgcn_global_load_lds((const __attribute__((address_space(1))) unsigned*)((const char*)(gbase) + (voff)[_i]), (LAS unsigned*)(lds + (bufoff) + ldsw + _i * 8192), 16, 0, 0); } while (0)
; #define PG8_LDA(dst, b, h) do { _Pragma("unroll") for (int m = 0; m < 4; ++m) _Pragma("unroll") for (int k = 0; k < 2; ++k) dst[m][k] = *(const LAS bf16x8*)(lds + PG8_SA(b, h) + aoff + m * 2048 + k * 1024); } while (0)
; #define PG8_LDB(dst, b, h) do { _Pragma("unroll") for (int n = 0; n < 2; ++n) _Pragma("unroll") for (int k = 0; k < 2; ++k) dst[n][k] = *(const LAS bf16x8*)(lds + PG8_SB(b, h) + boff + n * 2048 + k * 1024); } while (0)
; #define PG8_MMA(ai, bj, At, Bt) do { __builtin_amdgcn_s_setprio(1); _Pragma("unroll") for (int m = 0; m < 4; ++m) _Pragma("unroll") for (int n = 0; n < 2; ++n) _Pragma("unroll") for (int k = 0; k < 2; ++k) \
;         acc[ai][bj][m][n] = __builtin_amdgcn_mfma_f32_16x16x32_bf16(Bt[n][k], At[m][k], acc[ai][bj][m][n], 0, 0, 0); __builtin_amdgcn_s_setprio(0); } while (0)
; #define PG8_WAIT_V(n) asm volatile("s_waitcnt vmcnt(" #n ")" ::: "memory")
; #define PG8_WAIT_L(n) asm volatile("s_waitcnt lgkmcnt(" #n ")" ::: "memory")
; #define PG8_BAR __builtin_amdgcn_s_barrier()
; #define PG8_SCHED __builtin_amdgcn_sched_barrier(0)
; template <class Epi, class SchedT, bool ALIGN_EPI, bool SP2>
; __device__ __forceinline__ void gemm_phase(LAS unsigned char* lds, const int ldk, const int nt, const SchedT& S, const Epi& E) {
;     ...
;             PG8_LDB(B0, 0, 0); PG8_LDB(B1, 0, 1); PG8_SCHED; PG8_LDA(At, 0, 0); PG8_STAGE(PG8_SA(1, 1), a1 + hstep, voffA);
;             PG8_WAIT_V(8); PG8_WAIT_L(0); PG8_BAR; PG8_MMA(0, 0, At, B0); PG8_MMA(0, 1, At, B1); PG8_BAR; PG8_SCHED;
;             PG8_LDA(At, 0, 1); PG8_STAGE(PG8_SB(0, 0), b2, voffB); PG8_STAGE(PG8_SB(0, 1), b2 + hstepB, voffB); PG8_STAGE(PG8_SA(0, 0), a2, voffA);
.LBB0_752:
	s_add_u32 s36, s34, 0xfff80080
	s_addc_u32 s37, s35, -1
	s_add_i32 s61, 0, 0x10000
	s_cmp_eq_u32 s59, 28
	s_cselect_b32 vcc_hi, s1, s37
	s_cselect_b32 vcc_lo, s0, s36
	s_cselect_b32 s37, s63, s17
	s_cselect_b32 s36, s62, s13
	s_add_i32 s64, 0, 0x14000
	v_add_u32_e32 v142, s61, v248
	v_add_u32_e32 v182, s64, v248
	ds_read_b128 v[130:133], v142
	ds_read_b128 v[134:137], v142 offset:1024
	ds_read_b128 v[138:141], v142 offset:2048
	ds_read_b128 v[142:145], v142 offset:3072
	ds_read_b128 v[158:161], v182
	ds_read_b128 v[174:177], v182 offset:1024
	ds_read_b128 v[178:181], v182 offset:2048
	ds_read_b128 v[182:185], v182 offset:3072
	v_lshl_add_u64 v[218:219], s[34:35], 0, v[154:155]
	s_add_i32 m0, s85, 0xc000
	ds_read_b128 v[186:189], v251
	ds_read_b128 v[190:193], v251 offset:1024
	ds_read_b128 v[194:197], v251 offset:2048
	ds_read_b128 v[198:201], v251 offset:3072
	ds_read_b128 v[202:205], v251 offset:4096
	ds_read_b128 v[206:209], v251 offset:5120
	ds_read_b128 v[210:213], v251 offset:6144
	ds_read_b128 v[214:217], v251 offset:7168
	global_load_lds_dwordx4 v[218:219], off
	v_lshl_add_u64 v[218:219], s[34:35], 0, v[156:157]
	s_add_i32 m0, s85, 0xe000
	s_nop 0
	global_load_lds_dwordx4 v[218:219], off
	s_waitcnt vmcnt(8)
	s_waitcnt lgkmcnt(0)
	s_barrier
	s_waitcnt lgkmcnt(0)
	v_mfma_f32_16x16x32_bf16 v[126:129], v[130:133], v[186:189], v[126:129]
	v_mfma_f32_16x16x32_bf16 v[62:65], v[138:141], v[186:189], v[62:65]
	v_mfma_f32_16x16x32_bf16 v[118:121], v[130:133], v[194:197], v[118:121]
	v_mfma_f32_16x16x32_bf16 v[58:61], v[138:141], v[194:197], v[58:61]
	v_mfma_f32_16x16x32_bf16 v[110:113], v[130:133], v[202:205], v[110:113]
	v_mfma_f32_16x16x32_bf16 v[46:49], v[138:141], v[202:205], v[46:49]
	v_mfma_f32_16x16x32_bf16 v[106:109], v[130:133], v[210:213], v[106:109]
	v_mfma_f32_16x16x32_bf16 v[42:45], v[138:141], v[210:213], v[42:45]
	v_mfma_f32_16x16x32_bf16 v[126:129], v[134:137], v[190:193], v[126:129]
	v_mfma_f32_16x16x32_bf16 v[62:65], v[142:145], v[190:193], v[62:65]
	v_mfma_f32_16x16x32_bf16 v[118:121], v[134:137], v[198:201], v[118:121]
	v_mfma_f32_16x16x32_bf16 v[58:61], v[142:145], v[198:201], v[58:61]
	v_mfma_f32_16x16x32_bf16 v[110:113], v[134:137], v[206:209], v[110:113]
	v_mfma_f32_16x16x32_bf16 v[46:49], v[142:145], v[206:209], v[46:49]
	v_mfma_f32_16x16x32_bf16 v[106:109], v[134:137], v[214:217], v[106:109]
	v_mfma_f32_16x16x32_bf16 v[42:45], v[142:145], v[214:217], v[42:45]
	v_mfma_f32_16x16x32_bf16 v[122:125], v[158:161], v[186:189], v[122:125]
	v_mfma_f32_16x16x32_bf16 v[54:57], v[178:181], v[186:189], v[54:57]
	v_mfma_f32_16x16x32_bf16 v[114:117], v[158:161], v[194:197], v[114:117]
	v_mfma_f32_16x16x32_bf16 v[50:53], v[178:181], v[194:197], v[50:53]
	v_mfma_f32_16x16x32_bf16 v[102:105], v[158:161], v[202:205], v[102:105]
	v_mfma_f32_16x16x32_bf16 v[38:41], v[178:181], v[202:205], v[38:41]
	v_mfma_f32_16x16x32_bf16 v[98:101], v[158:161], v[210:213], v[98:101]
	v_mfma_f32_16x16x32_bf16 v[34:37], v[178:181], v[210:213], v[34:37]
	v_mfma_f32_16x16x32_bf16 v[122:125], v[174:177], v[190:193], v[122:125]
	v_mfma_f32_16x16x32_bf16 v[54:57], v[182:185], v[190:193], v[54:57]
	v_mfma_f32_16x16x32_bf16 v[114:117], v[174:177], v[198:201], v[114:117]
	v_mfma_f32_16x16x32_bf16 v[50:53], v[182:185], v[198:201], v[50:53]
	v_mfma_f32_16x16x32_bf16 v[102:105], v[174:177], v[206:209], v[102:105]
	v_mfma_f32_16x16x32_bf16 v[38:41], v[182:185], v[206:209], v[38:41]
	v_mfma_f32_16x16x32_bf16 v[98:101], v[174:177], v[214:217], v[98:101]
	v_mfma_f32_16x16x32_bf16 v[34:37], v[182:185], v[214:217], v[34:37]
	s_barrier
	s_add_i32 s61, s61, s84
	v_lshl_add_u64 v[218:219], s[36:37], 0, v[0:1]
	s_mov_b32 m0, s61
	ds_read_b128 v[186:189], v251 offset:16384
	ds_read_b128 v[190:193], v251 offset:17408
	ds_read_b128 v[194:197], v251 offset:18432
	ds_read_b128 v[198:201], v251 offset:19456
	ds_read_b128 v[202:205], v251 offset:20480
	ds_read_b128 v[206:209], v251 offset:21504
	ds_read_b128 v[210:213], v251 offset:22528
	ds_read_b128 v[214:217], v251 offset:23552
	global_load_lds_dwordx4 v[218:219], off
	s_add_i32 m0, s61, 0x2000
	s_add_u32 s94, s36, 0x20000
	v_lshl_add_u64 v[220:221], s[36:37], 0, v[150:151]
	s_addc_u32 s95, s37, 0
	s_add_i32 s61, s64, s84
	global_load_lds_dwordx4 v[220:221], off
	v_lshl_add_u64 v[222:223], s[94:95], 0, v[0:1]
	s_mov_b32 m0, s61
	v_lshl_add_u64 v[224:225], vcc, 0, v[148:149]
	global_load_lds_dwordx4 v[222:223], off
	v_lshl_add_u64 v[222:223], s[94:95], 0, v[150:151]
	s_add_i32 m0, s61, 0x2000
	s_nop 0
	global_load_lds_dwordx4 v[222:223], off
	v_lshl_add_u64 v[222:223], vcc, 0, v[146:147]
	s_mov_b32 m0, s85
	s_nop 0
	global_load_lds_dwordx4 v[222:223], off
	s_mov_b32 m0, s86
	s_nop 0
	global_load_lds_dwordx4 v[224:225], off
	s_waitcnt vmcnt(8)
	s_waitcnt lgkmcnt(0)
	s_barrier
; #define PG8_STAGE(bufoff, gbase, voff) do { _Pragma("unroll") for (int _i = 0; _i < 2; ++_i) \
;         __builtin_amdgcn_global_load_lds((const __attribute__((address_space(1))) unsigned*)((const char*)(gbase) + (voff)[_i]), (LAS unsigned*)(lds + (bufoff) + ldsw + _i * 8192), 16, 0, 0); } while (0)
; #define PG8_LDA(dst, b, h) do { _Pragma("unroll") for (int m = 0; m < 4; ++m) _Pragma("unroll") for (int k = 0; k < 2; ++k) dst[m][k] = *(const LAS bf16x8*)(lds + PG8_SA(b, h) + aoff + m * 2048 + k * 1024); } while (0)
; #define PG8_LDB(dst, b, h) do { _Pragma("unroll") for (int n = 0; n < 2; ++n) _Pragma("unroll") for (int k = 0; k < 2; ++k) dst[n][k] = *(const LAS bf16x8*)(lds + PG8_SB(b, h) + boff + n * 2048 + k * 1024); } while (0)
; #define PG8_MMA(ai, bj, At, Bt) do { __builtin_amdgcn_s_setprio(1); _Pragma("unroll") for (int m = 0; m < 4; ++m) _Pragma("unroll") for (int n = 0; n < 2; ++n) _Pragma("unroll") for (int k = 0; k < 2; ++k) \
;         acc[ai][bj][m][n] = __builtin_amdgcn_mfma_f32_16x16x32_bf16(Bt[n][k], At[m][k], acc[ai][bj][m][n], 0, 0, 0); __builtin_amdgcn_s_setprio(0); } while (0)
; #define PG8_WAIT_V(n) asm volatile("s_waitcnt vmcnt(" #n ")" ::: "memory")
; #define PG8_WAIT_L(n) asm volatile("s_waitcnt lgkmcnt(" #n ")" ::: "memory")
; #define PG8_BAR __builtin_amdgcn_s_barrier()
; #define PG8_SCHED __builtin_amdgcn_sched_barrier(0)
; template <class Epi, class SchedT, bool ALIGN_EPI, bool SP2>
; __device__ __forceinline__ void gemm_phase(LAS unsigned char* lds, const int ldk, const int nt, const SchedT& S, const Epi& E) {
;     ...
;             PG8_WAIT_V(8); PG8_WAIT_L(0); PG8_BAR; PG8_MMA(1, 0, At, B0); PG8_MMA(1, 1, At, B1); PG8_BAR; PG8_SCHED;
;             PG8_LDB(B0, 1, 0); PG8_LDB(B1, 1, 1); PG8_SCHED; PG8_LDA(At, 1, 0); PG8_STAGE(PG8_SA(0, 1), a2 + hstep, voffA);
;             PG8_WAIT_V(8); PG8_WAIT_L(0); PG8_BAR; PG8_MMA(0, 0, At, B0); PG8_MMA(0, 1, At, B1); PG8_BAR; PG8_SCHED;
	s_waitcnt lgkmcnt(0)
	v_mfma_f32_16x16x32_bf16 v[94:97], v[130:133], v[186:189], v[94:97]
	v_mfma_f32_16x16x32_bf16 v[30:33], v[138:141], v[186:189], v[30:33]
	v_mfma_f32_16x16x32_bf16 v[90:93], v[130:133], v[194:197], v[90:93]
	v_mfma_f32_16x16x32_bf16 v[26:29], v[138:141], v[194:197], v[26:29]
	v_mfma_f32_16x16x32_bf16 v[78:81], v[130:133], v[202:205], v[78:81]
	v_mfma_f32_16x16x32_bf16 v[14:17], v[138:141], v[202:205], v[14:17]
	v_mfma_f32_16x16x32_bf16 v[74:77], v[130:133], v[210:213], v[74:77]
	v_mfma_f32_16x16x32_bf16 v[10:13], v[138:141], v[210:213], v[10:13]
	v_mfma_f32_16x16x32_bf16 v[94:97], v[134:137], v[190:193], v[94:97]
	v_mfma_f32_16x16x32_bf16 v[30:33], v[142:145], v[190:193], v[30:33]
	v_mfma_f32_16x16x32_bf16 v[90:93], v[134:137], v[198:201], v[90:93]
	v_mfma_f32_16x16x32_bf16 v[26:29], v[142:145], v[198:201], v[26:29]
	v_mfma_f32_16x16x32_bf16 v[78:81], v[134:137], v[206:209], v[78:81]
	v_mfma_f32_16x16x32_bf16 v[14:17], v[142:145], v[206:209], v[14:17]
	v_mfma_f32_16x16x32_bf16 v[74:77], v[134:137], v[214:217], v[74:77]
	v_mfma_f32_16x16x32_bf16 v[10:13], v[142:145], v[214:217], v[10:13]
	v_mfma_f32_16x16x32_bf16 v[86:89], v[158:161], v[186:189], v[86:89]
	v_mfma_f32_16x16x32_bf16 v[22:25], v[178:181], v[186:189], v[22:25]
	v_mfma_f32_16x16x32_bf16 v[82:85], v[158:161], v[194:197], v[82:85]
	v_mfma_f32_16x16x32_bf16 v[18:21], v[178:181], v[194:197], v[18:21]
	v_mfma_f32_16x16x32_bf16 v[70:73], v[158:161], v[202:205], v[70:73]
	v_mfma_f32_16x16x32_bf16 v[6:9], v[178:181], v[202:205], v[6:9]
	v_mfma_f32_16x16x32_bf16 v[66:69], v[158:161], v[210:213], v[66:69]
	v_mfma_f32_16x16x32_bf16 v[2:5], v[178:181], v[210:213], v[2:5]
	v_mfma_f32_16x16x32_bf16 v[86:89], v[174:177], v[190:193], v[86:89]
	v_mfma_f32_16x16x32_bf16 v[22:25], v[182:185], v[190:193], v[22:25]
	v_mfma_f32_16x16x32_bf16 v[82:85], v[174:177], v[198:201], v[82:85]
	v_mfma_f32_16x16x32_bf16 v[18:21], v[182:185], v[198:201], v[18:21]
	v_mfma_f32_16x16x32_bf16 v[70:73], v[174:177], v[206:209], v[70:73]
	v_mfma_f32_16x16x32_bf16 v[6:9], v[182:185], v[206:209], v[6:9]
	v_mfma_f32_16x16x32_bf16 v[66:69], v[174:177], v[214:217], v[66:69]
	v_mfma_f32_16x16x32_bf16 v[2:5], v[182:185], v[214:217], v[2:5]
	s_barrier
	s_add_i32 s61, 0, 0x18000
	s_add_i32 s64, 0, 0x1c000
	v_add_u32_e32 v142, s61, v248
	v_add_u32_e32 v182, s64, v248
	ds_read_b128 v[130:133], v142
	ds_read_b128 v[134:137], v142 offset:1024
	ds_read_b128 v[138:141], v142 offset:2048
	ds_read_b128 v[142:145], v142 offset:3072
	ds_read_b128 v[158:161], v182
	ds_read_b128 v[174:177], v182 offset:1024
	ds_read_b128 v[178:181], v182 offset:2048
	ds_read_b128 v[182:185], v182 offset:3072
	s_add_u32 s94, vcc_lo, 0x80000
	s_addc_u32 s95, vcc_hi, 0
	s_mov_b32 m0, s87
	v_lshl_add_u64 v[226:227], s[94:95], 0, v[146:147]
	ds_read_b128 v[186:189], v251 offset:32768
	ds_read_b128 v[190:193], v251 offset:33792
	ds_read_b128 v[194:197], v251 offset:34816
	ds_read_b128 v[198:201], v251 offset:35840
	ds_read_b128 v[202:205], v251 offset:36864
	ds_read_b128 v[206:209], v251 offset:37888
	ds_read_b128 v[210:213], v251 offset:38912
	ds_read_b128 v[214:217], v251 offset:39936
	global_load_lds_dwordx4 v[226:227], off
	v_lshl_add_u64 v[226:227], s[94:95], 0, v[148:149]
	s_mov_b32 m0, s88
	s_nop 0
	global_load_lds_dwordx4 v[226:227], off
	s_waitcnt vmcnt(8)
	s_waitcnt lgkmcnt(0)
	s_barrier
	s_waitcnt lgkmcnt(0)
	v_mfma_f32_16x16x32_bf16 v[126:129], v[130:133], v[186:189], v[126:129]
	v_mfma_f32_16x16x32_bf16 v[62:65], v[138:141], v[186:189], v[62:65]
	v_mfma_f32_16x16x32_bf16 v[118:121], v[130:133], v[194:197], v[118:121]
	v_mfma_f32_16x16x32_bf16 v[58:61], v[138:141], v[194:197], v[58:61]
	v_mfma_f32_16x16x32_bf16 v[110:113], v[130:133], v[202:205], v[110:113]
	v_mfma_f32_16x16x32_bf16 v[46:49], v[138:141], v[202:205], v[46:49]
	v_mfma_f32_16x16x32_bf16 v[106:109], v[130:133], v[210:213], v[106:109]
	v_mfma_f32_16x16x32_bf16 v[42:45], v[138:141], v[210:213], v[42:45]
	v_mfma_f32_16x16x32_bf16 v[126:129], v[134:137], v[190:193], v[126:129]
	v_mfma_f32_16x16x32_bf16 v[62:65], v[142:145], v[190:193], v[62:65]
	v_mfma_f32_16x16x32_bf16 v[118:121], v[134:137], v[198:201], v[118:121]
	v_mfma_f32_16x16x32_bf16 v[58:61], v[142:145], v[198:201], v[58:61]
	v_mfma_f32_16x16x32_bf16 v[110:113], v[134:137], v[206:209], v[110:113]
	v_mfma_f32_16x16x32_bf16 v[46:49], v[142:145], v[206:209], v[46:49]
	v_mfma_f32_16x16x32_bf16 v[106:109], v[134:137], v[214:217], v[106:109]
	v_mfma_f32_16x16x32_bf16 v[42:45], v[142:145], v[214:217], v[42:45]
	v_mfma_f32_16x16x32_bf16 v[122:125], v[158:161], v[186:189], v[122:125]
	v_mfma_f32_16x16x32_bf16 v[54:57], v[178:181], v[186:189], v[54:57]
	v_mfma_f32_16x16x32_bf16 v[114:117], v[158:161], v[194:197], v[114:117]
	v_mfma_f32_16x16x32_bf16 v[50:53], v[178:181], v[194:197], v[50:53]
	v_mfma_f32_16x16x32_bf16 v[102:105], v[158:161], v[202:205], v[102:105]
	v_mfma_f32_16x16x32_bf16 v[38:41], v[178:181], v[202:205], v[38:41]
	v_mfma_f32_16x16x32_bf16 v[98:101], v[158:161], v[210:213], v[98:101]
	v_mfma_f32_16x16x32_bf16 v[34:37], v[178:181], v[210:213], v[34:37]
	v_mfma_f32_16x16x32_bf16 v[122:125], v[174:177], v[190:193], v[122:125]
	v_mfma_f32_16x16x32_bf16 v[54:57], v[182:185], v[190:193], v[54:57]
	v_mfma_f32_16x16x32_bf16 v[114:117], v[174:177], v[198:201], v[114:117]
	v_mfma_f32_16x16x32_bf16 v[50:53], v[182:185], v[198:201], v[50:53]
	v_mfma_f32_16x16x32_bf16 v[102:105], v[174:177], v[206:209], v[102:105]
	v_mfma_f32_16x16x32_bf16 v[38:41], v[182:185], v[206:209], v[38:41]
	v_mfma_f32_16x16x32_bf16 v[98:101], v[174:177], v[214:217], v[98:101]
	v_mfma_f32_16x16x32_bf16 v[34:37], v[182:185], v[214:217], v[34:37]
	s_barrier
; #define PG8_STAGE(bufoff, gbase, voff) do { _Pragma("unroll") for (int _i = 0; _i < 2; ++_i) \
;         __builtin_amdgcn_global_load_lds((const __attribute__((address_space(1))) unsigned*)((const char*)(gbase) + (voff)[_i]), (LAS unsigned*)(lds + (bufoff) + ldsw + _i * 8192), 16, 0, 0); } while (0)
; #define PG8_LDA(dst, b, h) do { _Pragma("unroll") for (int m = 0; m < 4; ++m) _Pragma("unroll") for (int k = 0; k < 2; ++k) dst[m][k] = *(const LAS bf16x8*)(lds + PG8_SA(b, h) + aoff + m * 2048 + k * 1024); } while (0)
; #define PG8_MMA(ai, bj, At, Bt) do { __builtin_amdgcn_s_setprio(1); _Pragma("unroll") for (int m = 0; m < 4; ++m) _Pragma("unroll") for (int n = 0; n < 2; ++n) _Pragma("unroll") for (int k = 0; k < 2; ++k) \
;         acc[ai][bj][m][n] = __builtin_amdgcn_mfma_f32_16x16x32_bf16(Bt[n][k], At[m][k], acc[ai][bj][m][n], 0, 0, 0); __builtin_amdgcn_s_setprio(0); } while (0)
; #define PG8_WAIT_V(n) asm volatile("s_waitcnt vmcnt(" #n ")" ::: "memory")
; #define PG8_WAIT_L(n) asm volatile("s_waitcnt lgkmcnt(" #n ")" ::: "memory")
; #define PG8_BAR __builtin_amdgcn_s_barrier()
; #define PG8_SCHED __builtin_amdgcn_sched_barrier(0)
; __device__ __forceinline__ float row_rstd(const float* ssp, int row, int fq) {
;     const f32x4 a = *(const f32x4*)(ssp + (size_t)row * 32 + 8 * fq), b = *(const f32x4*)(ssp + (size_t)row * 32 + 8 * fq + 4);
;     float s = ((a[0] + a[1]) + (a[2] + a[3])) + ((b[0] + b[1]) + (b[2] + b[3]));
;     s += __shfl_xor(s, 16); s += __shfl_xor(s, 32);
;     return __builtin_amdgcn_rsqf(s * (1.0f / 2048.0f) + 1e-6f);
; }
; template <class Epi, class SchedT, bool ALIGN_EPI, bool SP2>
; __device__ __forceinline__ void gemm_phase(LAS unsigned char* lds, const int ldk, const int nt, const SchedT& S, const Epi& E) {
;     ...
;             PG8_LDA(At, 1, 1); PG8_STAGE(PG8_SB(1, 0), b3, voffB); PG8_STAGE(PG8_SB(1, 1), b3 + hstepB, voffB); PG8_STAGE(PG8_SA(1, 0), a3, voffA);
;             PG8_WAIT_V(8); PG8_WAIT_L(0); PG8_BAR; PG8_MMA(1, 0, At, B0); PG8_MMA(1, 1, At, B1); PG8_BAR; PG8_SCHED;
	s_add_i32 s61, s61, s84
	v_lshl_add_u64 v[218:219], v[218:219], 0, s[24:25]
	s_mov_b32 m0, s61
	ds_read_b128 v[186:189], v251 offset:49152
	ds_read_b128 v[190:193], v251 offset:50176
	ds_read_b128 v[194:197], v251 offset:51200
	ds_read_b128 v[198:201], v251 offset:52224
	ds_read_b128 v[202:205], v251 offset:53248
	ds_read_b128 v[206:209], v251 offset:54272
	ds_read_b128 v[210:213], v251 offset:55296
	ds_read_b128 v[214:217], v251 offset:56320
	global_load_lds_dwordx4 v[218:219], off
	s_add_i32 m0, s61, 0x2000
	s_add_u32 s36, s36, 0x20080
	v_lshl_add_u64 v[218:219], v[220:221], 0, s[24:25]
	s_addc_u32 s37, s37, 0
	s_add_i32 s61, s64, s84
	global_load_lds_dwordx4 v[218:219], off
	v_lshl_add_u64 v[218:219], s[36:37], 0, v[0:1]
	s_mov_b32 m0, s61
	s_nop 0
	global_load_lds_dwordx4 v[218:219], off
	v_lshl_add_u64 v[218:219], s[36:37], 0, v[150:151]
	s_add_i32 m0, s61, 0x2000
	s_nop 0
	global_load_lds_dwordx4 v[218:219], off
	v_lshl_add_u64 v[218:219], v[222:223], 0, s[24:25]
	s_mov_b32 m0, s89
	s_nop 0
	global_load_lds_dwordx4 v[218:219], off
	v_lshl_add_u64 v[218:219], v[224:225], 0, s[24:25]
	s_mov_b32 m0, s90
	s_nop 0
	global_load_lds_dwordx4 v[218:219], off
	s_waitcnt vmcnt(8)
	s_waitcnt lgkmcnt(0)
	s_barrier
	s_waitcnt lgkmcnt(0)
	v_mfma_f32_16x16x32_bf16 v[94:97], v[130:133], v[186:189], v[94:97]
	v_mfma_f32_16x16x32_bf16 v[30:33], v[138:141], v[186:189], v[30:33]
	v_mfma_f32_16x16x32_bf16 v[90:93], v[130:133], v[194:197], v[90:93]
	v_mfma_f32_16x16x32_bf16 v[26:29], v[138:141], v[194:197], v[26:29]
	v_mfma_f32_16x16x32_bf16 v[78:81], v[130:133], v[202:205], v[78:81]
	v_mfma_f32_16x16x32_bf16 v[14:17], v[138:141], v[202:205], v[14:17]
	v_mfma_f32_16x16x32_bf16 v[74:77], v[130:133], v[210:213], v[74:77]
	v_mfma_f32_16x16x32_bf16 v[10:13], v[138:141], v[210:213], v[10:13]
	v_mfma_f32_16x16x32_bf16 v[94:97], v[134:137], v[190:193], v[94:97]
	v_mfma_f32_16x16x32_bf16 v[30:33], v[142:145], v[190:193], v[30:33]
	v_mfma_f32_16x16x32_bf16 v[90:93], v[134:137], v[198:201], v[90:93]
	v_mfma_f32_16x16x32_bf16 v[26:29], v[142:145], v[198:201], v[26:29]
	v_mfma_f32_16x16x32_bf16 v[78:81], v[134:137], v[206:209], v[78:81]
	v_mfma_f32_16x16x32_bf16 v[14:17], v[142:145], v[206:209], v[14:17]
	v_mfma_f32_16x16x32_bf16 v[74:77], v[134:137], v[214:217], v[74:77]
	v_mfma_f32_16x16x32_bf16 v[10:13], v[142:145], v[214:217], v[10:13]
	v_mfma_f32_16x16x32_bf16 v[86:89], v[158:161], v[186:189], v[86:89]
	v_mfma_f32_16x16x32_bf16 v[22:25], v[178:181], v[186:189], v[22:25]
	v_mfma_f32_16x16x32_bf16 v[82:85], v[158:161], v[194:197], v[82:85]
	v_mfma_f32_16x16x32_bf16 v[18:21], v[178:181], v[194:197], v[18:21]
	v_mfma_f32_16x16x32_bf16 v[70:73], v[158:161], v[202:205], v[70:73]
	v_mfma_f32_16x16x32_bf16 v[6:9], v[178:181], v[202:205], v[6:9]
	v_mfma_f32_16x16x32_bf16 v[66:69], v[158:161], v[210:213], v[66:69]
	v_mfma_f32_16x16x32_bf16 v[2:5], v[178:181], v[210:213], v[2:5]
	v_mfma_f32_16x16x32_bf16 v[86:89], v[174:177], v[190:193], v[86:89]
	v_mfma_f32_16x16x32_bf16 v[22:25], v[182:185], v[190:193], v[22:25]
	v_mfma_f32_16x16x32_bf16 v[82:85], v[174:177], v[198:201], v[82:85]
	v_mfma_f32_16x16x32_bf16 v[18:21], v[182:185], v[198:201], v[18:21]
	v_mfma_f32_16x16x32_bf16 v[70:73], v[174:177], v[206:209], v[70:73]
	v_mfma_f32_16x16x32_bf16 v[6:9], v[182:185], v[206:209], v[6:9]
	v_mfma_f32_16x16x32_bf16 v[66:69], v[174:177], v[214:217], v[66:69]
	v_mfma_f32_16x16x32_bf16 v[2:5], v[182:185], v[214:217], v[2:5]
	s_barrier
	s_add_i32 s59, s59, 2
	s_add_u32 s34, s34, 0x100
	s_addc_u32 s35, s35, 0
	s_add_u32 s13, s13, 0x100
	s_addc_u32 s17, s17, 0
	s_cmp_gt_u32 s59, 29
	s_cbranch_scc0 .LBB0_752
	v_lshl_add_u32 v130, s12, 8, v247
	v_lshlrev_b32_e32 v140, 7, v130
	v_mov_b32_e32 v141, 0
	v_lshl_add_u64 v[132:133], v[152:153], 0, v[140:141]
	v_add_u32_e32 v140, 0x1000, v140
	v_lshl_add_u64 v[134:135], v[152:153], 0, v[140:141]
	v_add_u32_e32 v140, 0x3000, v140
	v_lshl_add_u64 v[136:137], v[152:153], 0, v[140:141]
	v_add_u32_e32 v140, 0x1000, v140
	v_lshl_add_u64 v[138:139], v[152:153], 0, v[140:141]
	global_load_dwordx4 v[174:177], v[132:133], off
	global_load_dwordx4 v[178:181], v[132:133], off offset:16
	global_load_dwordx4 v[182:185], v[132:133], off offset:2048
	global_load_dwordx4 v[186:189], v[132:133], off offset:2064
	global_load_dwordx4 v[190:193], v[134:135], off
	global_load_dwordx4 v[194:197], v[134:135], off offset:16
	global_load_dwordx4 v[198:201], v[134:135], off offset:2048
	global_load_dwordx4 v[202:205], v[134:135], off offset:2064
	global_load_dwordx4 v[206:209], v[136:137], off
	global_load_dwordx4 v[210:213], v[136:137], off offset:16
	global_load_dwordx4 v[214:217], v[136:137], off offset:2048
	global_load_dwordx4 v[218:221], v[136:137], off offset:2064
	global_load_dwordx4 v[222:225], v[138:139], off
	global_load_dwordx4 v[226:229], v[138:139], off offset:16
	global_load_dwordx4 v[230:233], v[138:139], off offset:2048
	global_load_dwordx4 v[234:237], v[138:139], off offset:2064
	v_xor_b32_e32 v238, 16, v241
	v_xor_b32_e32 v239, 32, v241
	v_lshlrev_b32_e32 v238, 2, v238
	v_lshlrev_b32_e32 v239, 2, v239
	s_and_b64 vcc, exec, s[56:57]
	s_cbranch_vccz .LBB0_755
	s_barrier

; #define PG8_STAGE(bufoff, gbase, voff) do { _Pragma("unroll") for (int _i = 0; _i < 2; ++_i) \
;         __builtin_amdgcn_global_load_lds((const __attribute__((address_space(1))) unsigned*)((const char*)(gbase) + (voff)[_i]), (LAS unsigned*)(lds + (bufoff) + ldsw + _i * 8192), 16, 0, 0); } while (0)
; #define PG8_BAR __builtin_amdgcn_s_barrier()
; template <class Epi, class SchedT, bool ALIGN_EPI, bool SP2>
; __device__ __forceinline__ void gemm_phase(LAS unsigned char* lds, const int ldk, const int nt, const SchedT& S, const Epi& E) {
;     ...
;     for (int i = 0; i < 2; ++i) { int R, C; stage_rc(tid * 16 + i * 8192, R, C); const int Rb = 2 * (R & ~31) + perm32(R & 31);
;         voffA[i] = (unsigned)(R * K + C) * 2u; voffB[i] = (unsigned)(Rb * K + C) * 2u; }
;     ...
;         PG8_STAGE(PG8_SB(0, 0), cB, voffB); PG8_STAGE(PG8_SB(0, 1), cB + hstepB, voffB); PG8_STAGE(PG8_SA(0, 0), cA, voffA); PG8_STAGE(PG8_SA(0, 1), cA + hstep, voffA);
;         if (wr == 1) PG8_BAR;
.LBB0_937:
	v_readlane_b32 s12, v163, 43
	v_readlane_b32 s13, v163, 44
	s_and_b64 vcc, exec, s[12:13]
	s_cbranch_vccnz .LBB0_971
	v_ashrrev_i32_e32 v0, 31, v18
	v_lshrrev_b32_e32 v0, 26, v0
	v_add_u32_e32 v0, v18, v0
	v_ashrrev_i32_e32 v10, 6, v0
	v_bfe_i32 v0, v18, 27, 1
	v_lshlrev_b32_e32 v2, 4, v18
	v_lshrrev_b32_e32 v0, 22, v0
	v_add_u32_e32 v0, v2, v0
	v_and_b32_e32 v0, 0xfffffc00, v0
	v_sub_u32_e32 v0, v2, v0
	v_lshrrev_b32_e32 v3, 4, v0
	v_bitop3_b32 v0, v3, v0, 32 bitop3:0x6c
	v_ashrrev_i32_e32 v4, 31, v0
	v_readlane_b32 s12, v163, 36
	v_lshrrev_b32_e32 v4, 26, v4
	s_add_u32 s12, s0, s12
	v_lshlrev_b32_e32 v3, 3, v10
	v_add_u32_e32 v4, v0, v4
	s_addc_u32 s13, s1, 0
	v_and_b32_e32 v3, -16, v3
	v_ashrrev_i32_e32 v12, 6, v4
	v_and_b32_e32 v4, 0xc0, v4
	s_add_u32 s48, s0, 0x21800000
	v_add_u32_e32 v3, v12, v3
	v_lshlrev_b32_e32 v5, 5, v10
	v_sub_u32_e32 v0, v0, v4
	s_addc_u32 s49, s1, 0
	v_and_b32_e32 v11, 32, v5
	v_ashrrev_i16_sdwa v0, v244, sext(v0) dst_sel:DWORD dst_unused:UNUSED_PAD src0_sel:DWORD src1_sel:BYTE_0
	v_lshlrev_b32_e32 v4, 1, v3
	v_lshrrev_b32_e32 v5, 2, v3
	s_add_u32 s50, s12, 0x6100000
	v_bfe_i32 v13, v0, 0, 16
	v_and_b32_e32 v5, 4, v5
	v_and_b32_e32 v6, 3, v12
	v_and_b32_e32 v4, 0x1ffffd8, v4
	s_movk_i32 s12, 0x1580
	v_add_u32_e32 v0, v11, v13
	v_or3_b32 v4, v6, v5, v4
	v_mul_lo_u32 v3, v3, s12
	v_add_lshl_u32 v130, v0, v3, 1
	v_mul_lo_u32 v3, v4, s12
	v_add_u32_e32 v2, 0x2000, v2
	v_add_lshl_u32 v0, v3, v0, 1
	v_ashrrev_i32_e32 v3, 31, v2
	v_lshrrev_b32_e32 v3, 22, v3
	v_add_u32_e32 v3, v2, v3
	v_ashrrev_i32_e32 v14, 10, v3
	v_mul_i32_i24_e32 v3, 0x400, v14
	v_sub_u32_e32 v2, v2, v3
	v_lshrrev_b32_e32 v3, 4, v2
	v_bitop3_b32 v2, v3, v2, 32 bitop3:0x6c
	v_ashrrev_i32_e32 v4, 31, v2
	v_lshrrev_b32_e32 v4, 26, v4
	v_lshlrev_b32_e32 v3, 3, v14
	v_add_u32_e32 v4, v2, v4
	v_and_b32_e32 v3, -16, v3
	v_ashrrev_i32_e32 v16, 6, v4
	v_and_b32_e32 v4, 0xc0, v4
	v_add_u32_e32 v3, v16, v3
	v_lshlrev_b32_e32 v5, 5, v14
	v_sub_u32_e32 v2, v2, v4
	v_and_b32_e32 v15, 32, v5
	v_ashrrev_i16_sdwa v2, v244, sext(v2) dst_sel:DWORD dst_unused:UNUSED_PAD src0_sel:DWORD src1_sel:BYTE_0
	v_lshlrev_b32_e32 v4, 1, v3
	v_lshrrev_b32_e32 v5, 2, v3
	s_addc_u32 s51, s13, 0
	s_ashr_i32 s37, s36, 6
	v_bfe_i32 v17, v2, 0, 16
	v_and_b32_e32 v5, 4, v5
	v_and_b32_e32 v6, 3, v16
	v_and_b32_e32 v4, 0x1ffffd8, v4
	v_add_u32_e32 v2, v15, v17
	v_or3_b32 v4, v6, v5, v4
	v_mul_lo_u32 v3, v3, s12
	s_ashr_i32 s38, s36, 8
	s_lshl_b32 s52, s37, 10
	s_mul_i32 s13, s22, 0x2b0000
	v_add_lshl_u32 v132, v2, v3, 1
	v_mul_lo_u32 v3, v4, s12
	s_mul_hi_i32 s12, s22, 0x2b0000
	s_add_u32 s16, s50, s13
	s_addc_u32 s17, s51, s12
	s_add_i32 s53, s52, 0
	s_add_i32 m0, s53, 0x10000
	v_add_lshl_u32 v134, v3, v2, 1
	global_load_lds_dwordx4 v0, s[16:17]
	s_add_i32 m0, s53, 0x12000
	s_add_u32 s12, s16, 0x56000
	global_load_lds_dwordx4 v134, s[16:17]
	s_addc_u32 s13, s17, 0
	s_add_i32 m0, s53, 0x14000
	s_mul_i32 s19, s63, 0x2b0000
	global_load_lds_dwordx4 v0, s[12:13]
	s_add_i32 m0, s53, 0x16000
	s_mul_hi_i32 s18, s63, 0x2b0000
	global_load_lds_dwordx4 v134, s[12:13]
	s_add_u32 s12, s48, s19
	s_addc_u32 s13, s49, s18
	s_add_i32 s54, s53, 0x2000
	s_mov_b32 m0, s53
	s_add_u32 s18, s12, 0x158000
	global_load_lds_dwordx4 v130, s[12:13]
	s_mov_b32 m0, s54
	s_addc_u32 s19, s13, 0
	s_add_i32 s55, s53, 0x4000
	global_load_lds_dwordx4 v132, s[12:13]
	s_mov_b32 m0, s55
	s_add_i32 s56, s53, 0x6000
	global_load_lds_dwordx4 v130, s[18:19]
	s_mov_b32 m0, s56
	v_mov_b32_e32 v135, v1
	global_load_lds_dwordx4 v132, s[18:19]
	v_mov_b32_e32 v131, v1
	v_mov_b32_e32 v133, v1
	s_cmp_eq_u32 s38, 1
	v_lshl_add_u64 v[8:9], s[16:17], 0, v[0:1]
	v_lshl_add_u64 v[6:7], s[16:17], 0, v[134:135]
	v_lshl_add_u64 v[2:3], s[12:13], 0, v[130:131]
	s_cselect_b64 s[18:19], -1, 0
	s_cmp_lg_u32 s38, 1
	v_lshl_add_u64 v[4:5], s[12:13], 0, v[132:133]
	s_cbranch_scc1 .LBB0_940
	s_barrier
	s_setprio 1

; #define PG8_STAGE(bufoff, gbase, voff) do { _Pragma("unroll") for (int _i = 0; _i < 2; ++_i) \
;         __builtin_amdgcn_global_load_lds((const __attribute__((address_space(1))) unsigned*)((const char*)(gbase) + (voff)[_i]), (LAS unsigned*)(lds + (bufoff) + ldsw + _i * 8192), 16, 0, 0); } while (0)
; #define PG8_LDA(dst, b, h) do { _Pragma("unroll") for (int m = 0; m < 4; ++m) _Pragma("unroll") for (int k = 0; k < 2; ++k) dst[m][k] = *(const LAS bf16x8*)(lds + PG8_SA(b, h) + aoff + m * 2048 + k * 1024); } while (0)
; #define PG8_LDB(dst, b, h) do { _Pragma("unroll") for (int n = 0; n < 2; ++n) _Pragma("unroll") for (int k = 0; k < 2; ++k) dst[n][k] = *(const LAS bf16x8*)(lds + PG8_SB(b, h) + boff + n * 2048 + k * 1024); } while (0)
; #define PG8_MMA(ai, bj, At, Bt) do { __builtin_amdgcn_s_setprio(1); _Pragma("unroll") for (int m = 0; m < 4; ++m) _Pragma("unroll") for (int n = 0; n < 2; ++n) _Pragma("unroll") for (int k = 0; k < 2; ++k) \
;         acc[ai][bj][m][n] = __builtin_amdgcn_mfma_f32_16x16x32_bf16(Bt[n][k], At[m][k], acc[ai][bj][m][n], 0, 0, 0); __builtin_amdgcn_s_setprio(0); } while (0)
; #define PG8_WAIT_V(n) asm volatile("s_waitcnt vmcnt(" #n ")" ::: "memory")
; #define PG8_WAIT_L(n) asm volatile("s_waitcnt lgkmcnt(" #n ")" ::: "memory")
; #define PG8_BAR __builtin_amdgcn_s_barrier()
; #define PG8_SCHED __builtin_amdgcn_sched_barrier(0)
; template <class Epi, class SchedT, bool ALIGN_EPI, bool SP2>
; __device__ __forceinline__ void gemm_phase(LAS unsigned char* lds, const int ldk, const int nt, const SchedT& S, const Epi& E) {
;     ...
;             PG8_LDB(B0, 0, 0); PG8_LDB(B1, 0, 1); PG8_SCHED; PG8_LDA(At, 0, 0); PG8_STAGE(PG8_SA(1, 1), a1 + hstep, voffA);
;             PG8_WAIT_V(8); PG8_WAIT_L(0); PG8_BAR; PG8_MMA(0, 0, At, B0); PG8_MMA(0, 1, At, B1); PG8_BAR; PG8_SCHED;
;             PG8_LDA(At, 0, 1); PG8_STAGE(PG8_SB(0, 0), b2, voffB); PG8_STAGE(PG8_SB(0, 1), b2 + hstepB, voffB); PG8_STAGE(PG8_SA(0, 0), a2, voffA);
.LBB0_948:
	s_add_u32 s16, s12, 0x100
	s_addc_u32 s17, s13, 0
	s_add_i32 s64, 0, 0x10000
	s_cmpk_eq_i32 s83, 0x52
	s_cselect_b32 s47, s1, s17
	s_cselect_b32 s46, s0, s16
	v_add_u32_e32 v144, s64, v147
	s_cselect_b32 s45, s43, s82
	s_cselect_b32 s44, s42, s81
	s_add_i32 s65, 0, 0x14000
	ds_read_b128 v[140:143], v144
	ds_read_b128 v[150:153], v144 offset:1024
	ds_read_b128 v[154:157], v144 offset:2048
	ds_read_b128 v[158:161], v144 offset:3072
	v_add_u32_e32 v144, s65, v147
	ds_read_b128 v[174:177], v144
	ds_read_b128 v[178:181], v144 offset:1024
	ds_read_b128 v[182:185], v144 offset:2048
	ds_read_b128 v[186:189], v144 offset:3072
	v_lshl_add_u64 v[144:145], s[12:13], 0, v[136:137]
	s_add_i32 m0, s53, 0xc000
	ds_read_b128 v[190:193], v149
	ds_read_b128 v[194:197], v149 offset:1024
	ds_read_b128 v[198:201], v149 offset:2048
	ds_read_b128 v[202:205], v149 offset:3072
	ds_read_b128 v[206:209], v149 offset:4096
	ds_read_b128 v[210:213], v149 offset:5120
	ds_read_b128 v[214:217], v149 offset:6144
	ds_read_b128 v[218:221], v149 offset:7168
	global_load_lds_dwordx4 v[144:145], off
	v_lshl_add_u64 v[144:145], s[12:13], 0, v[138:139]
	s_add_i32 m0, s53, 0xe000
	s_nop 0
	global_load_lds_dwordx4 v[144:145], off
	s_waitcnt vmcnt(8)
	s_waitcnt lgkmcnt(0)
	s_barrier
	s_waitcnt lgkmcnt(0)
	v_mfma_f32_16x16x32_bf16 v[126:129], v[140:143], v[190:193], v[126:129]
	v_mfma_f32_16x16x32_bf16 v[122:125], v[154:157], v[190:193], v[122:125]
	v_mfma_f32_16x16x32_bf16 v[110:113], v[140:143], v[198:201], v[110:113]
	v_mfma_f32_16x16x32_bf16 v[106:109], v[154:157], v[198:201], v[106:109]
	v_mfma_f32_16x16x32_bf16 v[94:97], v[140:143], v[206:209], v[94:97]
	v_mfma_f32_16x16x32_bf16 v[90:93], v[154:157], v[206:209], v[90:93]
	v_mfma_f32_16x16x32_bf16 v[78:81], v[140:143], v[214:217], v[78:81]
	v_mfma_f32_16x16x32_bf16 v[74:77], v[154:157], v[214:217], v[74:77]
	v_mfma_f32_16x16x32_bf16 v[126:129], v[150:153], v[194:197], v[126:129]
	v_mfma_f32_16x16x32_bf16 v[122:125], v[158:161], v[194:197], v[122:125]
	v_mfma_f32_16x16x32_bf16 v[110:113], v[150:153], v[202:205], v[110:113]
	v_mfma_f32_16x16x32_bf16 v[106:109], v[158:161], v[202:205], v[106:109]
	v_mfma_f32_16x16x32_bf16 v[94:97], v[150:153], v[210:213], v[94:97]
	v_mfma_f32_16x16x32_bf16 v[90:93], v[158:161], v[210:213], v[90:93]
	v_mfma_f32_16x16x32_bf16 v[78:81], v[150:153], v[218:221], v[78:81]
	v_mfma_f32_16x16x32_bf16 v[74:77], v[158:161], v[218:221], v[74:77]
	v_mfma_f32_16x16x32_bf16 v[118:121], v[174:177], v[190:193], v[118:121]
	v_mfma_f32_16x16x32_bf16 v[114:117], v[182:185], v[190:193], v[114:117]
	v_mfma_f32_16x16x32_bf16 v[102:105], v[174:177], v[198:201], v[102:105]
	v_mfma_f32_16x16x32_bf16 v[98:101], v[182:185], v[198:201], v[98:101]
	v_mfma_f32_16x16x32_bf16 v[86:89], v[174:177], v[206:209], v[86:89]
	v_mfma_f32_16x16x32_bf16 v[82:85], v[182:185], v[206:209], v[82:85]
	v_mfma_f32_16x16x32_bf16 v[70:73], v[174:177], v[214:217], v[70:73]
	v_mfma_f32_16x16x32_bf16 v[66:69], v[182:185], v[214:217], v[66:69]
	v_mfma_f32_16x16x32_bf16 v[118:121], v[178:181], v[194:197], v[118:121]
	v_mfma_f32_16x16x32_bf16 v[114:117], v[186:189], v[194:197], v[114:117]
	v_mfma_f32_16x16x32_bf16 v[102:105], v[178:181], v[202:205], v[102:105]
	v_mfma_f32_16x16x32_bf16 v[98:101], v[186:189], v[202:205], v[98:101]
	v_mfma_f32_16x16x32_bf16 v[86:89], v[178:181], v[210:213], v[86:89]
	v_mfma_f32_16x16x32_bf16 v[82:85], v[186:189], v[210:213], v[82:85]
	v_mfma_f32_16x16x32_bf16 v[70:73], v[178:181], v[218:221], v[70:73]
	v_mfma_f32_16x16x32_bf16 v[66:69], v[186:189], v[218:221], v[66:69]
	s_barrier
	s_add_i32 s12, s64, s52
	v_lshl_add_u64 v[144:145], s[44:45], 0, v[0:1]
	s_mov_b32 m0, s12
	ds_read_b128 v[190:193], v149 offset:16384
	ds_read_b128 v[194:197], v149 offset:17408
	ds_read_b128 v[198:201], v149 offset:18432
	ds_read_b128 v[202:205], v149 offset:19456
	ds_read_b128 v[206:209], v149 offset:20480
	ds_read_b128 v[210:213], v149 offset:21504
	ds_read_b128 v[214:217], v149 offset:22528
	ds_read_b128 v[218:221], v149 offset:23552
	global_load_lds_dwordx4 v[144:145], off
	s_add_i32 m0, s12, 0x2000
	s_add_u32 s12, s44, 0x56000
	v_lshl_add_u64 v[222:223], s[44:45], 0, v[134:135]
	s_addc_u32 s13, s45, 0
	s_add_i32 s64, s65, s52
	global_load_lds_dwordx4 v[222:223], off
	v_lshl_add_u64 v[224:225], s[12:13], 0, v[0:1]
	s_mov_b32 m0, s64
	v_lshl_add_u64 v[226:227], s[46:47], 0, v[132:133]
	global_load_lds_dwordx4 v[224:225], off
	v_lshl_add_u64 v[224:225], s[12:13], 0, v[134:135]
	s_add_i32 m0, s64, 0x2000
	s_nop 0
	global_load_lds_dwordx4 v[224:225], off
	v_lshl_add_u64 v[224:225], s[46:47], 0, v[130:131]
	s_mov_b32 m0, s53
	s_nop 0
	global_load_lds_dwordx4 v[224:225], off
	s_mov_b32 m0, s54
	s_nop 0
	global_load_lds_dwordx4 v[226:227], off
	s_waitcnt vmcnt(8)
	s_waitcnt lgkmcnt(0)
	s_barrier
; #define PG8_STAGE(bufoff, gbase, voff) do { _Pragma("unroll") for (int _i = 0; _i < 2; ++_i) \
;         __builtin_amdgcn_global_load_lds((const __attribute__((address_space(1))) unsigned*)((const char*)(gbase) + (voff)[_i]), (LAS unsigned*)(lds + (bufoff) + ldsw + _i * 8192), 16, 0, 0); } while (0)
; #define PG8_LDA(dst, b, h) do { _Pragma("unroll") for (int m = 0; m < 4; ++m) _Pragma("unroll") for (int k = 0; k < 2; ++k) dst[m][k] = *(const LAS bf16x8*)(lds + PG8_SA(b, h) + aoff + m * 2048 + k * 1024); } while (0)
; #define PG8_LDB(dst, b, h) do { _Pragma("unroll") for (int n = 0; n < 2; ++n) _Pragma("unroll") for (int k = 0; k < 2; ++k) dst[n][k] = *(const LAS bf16x8*)(lds + PG8_SB(b, h) + boff + n * 2048 + k * 1024); } while (0)
; #define PG8_MMA(ai, bj, At, Bt) do { __builtin_amdgcn_s_setprio(1); _Pragma("unroll") for (int m = 0; m < 4; ++m) _Pragma("unroll") for (int n = 0; n < 2; ++n) _Pragma("unroll") for (int k = 0; k < 2; ++k) \
;         acc[ai][bj][m][n] = __builtin_amdgcn_mfma_f32_16x16x32_bf16(Bt[n][k], At[m][k], acc[ai][bj][m][n], 0, 0, 0); __builtin_amdgcn_s_setprio(0); } while (0)
; #define PG8_WAIT_V(n) asm volatile("s_waitcnt vmcnt(" #n ")" ::: "memory")
; #define PG8_WAIT_L(n) asm volatile("s_waitcnt lgkmcnt(" #n ")" ::: "memory")
; #define PG8_BAR __builtin_amdgcn_s_barrier()
; #define PG8_SCHED __builtin_amdgcn_sched_barrier(0)
; template <class Epi, class SchedT, bool ALIGN_EPI, bool SP2>
; __device__ __forceinline__ void gemm_phase(LAS unsigned char* lds, const int ldk, const int nt, const SchedT& S, const Epi& E) {
;     ...
;             PG8_WAIT_V(8); PG8_WAIT_L(0); PG8_BAR; PG8_MMA(1, 0, At, B0); PG8_MMA(1, 1, At, B1); PG8_BAR; PG8_SCHED;
;             PG8_LDB(B0, 1, 0); PG8_LDB(B1, 1, 1); PG8_SCHED; PG8_LDA(At, 1, 0); PG8_STAGE(PG8_SA(0, 1), a2 + hstep, voffA);
;             PG8_WAIT_V(8); PG8_WAIT_L(0); PG8_BAR; PG8_MMA(0, 0, At, B0); PG8_MMA(0, 1, At, B1); PG8_BAR; PG8_SCHED;
	s_waitcnt lgkmcnt(0)
	v_mfma_f32_16x16x32_bf16 v[62:65], v[140:143], v[190:193], v[62:65]
	v_mfma_f32_16x16x32_bf16 v[58:61], v[154:157], v[190:193], v[58:61]
	v_mfma_f32_16x16x32_bf16 v[46:49], v[140:143], v[198:201], v[46:49]
	v_mfma_f32_16x16x32_bf16 v[42:45], v[154:157], v[198:201], v[42:45]
	v_mfma_f32_16x16x32_bf16 v[30:33], v[140:143], v[206:209], v[30:33]
	v_mfma_f32_16x16x32_bf16 v[26:29], v[154:157], v[206:209], v[26:29]
	v_mfma_f32_16x16x32_bf16 v[14:17], v[140:143], v[214:217], v[14:17]
	v_mfma_f32_16x16x32_bf16 v[10:13], v[154:157], v[214:217], v[10:13]
	v_mfma_f32_16x16x32_bf16 v[62:65], v[150:153], v[194:197], v[62:65]
	v_mfma_f32_16x16x32_bf16 v[58:61], v[158:161], v[194:197], v[58:61]
	v_mfma_f32_16x16x32_bf16 v[46:49], v[150:153], v[202:205], v[46:49]
	v_mfma_f32_16x16x32_bf16 v[42:45], v[158:161], v[202:205], v[42:45]
	v_mfma_f32_16x16x32_bf16 v[30:33], v[150:153], v[210:213], v[30:33]
	v_mfma_f32_16x16x32_bf16 v[26:29], v[158:161], v[210:213], v[26:29]
	v_mfma_f32_16x16x32_bf16 v[14:17], v[150:153], v[218:221], v[14:17]
	v_mfma_f32_16x16x32_bf16 v[10:13], v[158:161], v[218:221], v[10:13]
	v_mfma_f32_16x16x32_bf16 v[54:57], v[174:177], v[190:193], v[54:57]
	v_mfma_f32_16x16x32_bf16 v[50:53], v[182:185], v[190:193], v[50:53]
	v_mfma_f32_16x16x32_bf16 v[38:41], v[174:177], v[198:201], v[38:41]
	v_mfma_f32_16x16x32_bf16 v[34:37], v[182:185], v[198:201], v[34:37]
	v_mfma_f32_16x16x32_bf16 v[22:25], v[174:177], v[206:209], v[22:25]
	v_mfma_f32_16x16x32_bf16 v[18:21], v[182:185], v[206:209], v[18:21]
	v_mfma_f32_16x16x32_bf16 v[6:9], v[174:177], v[214:217], v[6:9]
	v_mfma_f32_16x16x32_bf16 v[2:5], v[182:185], v[214:217], v[2:5]
	v_mfma_f32_16x16x32_bf16 v[54:57], v[178:181], v[194:197], v[54:57]
	v_mfma_f32_16x16x32_bf16 v[50:53], v[186:189], v[194:197], v[50:53]
	v_mfma_f32_16x16x32_bf16 v[38:41], v[178:181], v[202:205], v[38:41]
	v_mfma_f32_16x16x32_bf16 v[34:37], v[186:189], v[202:205], v[34:37]
	v_mfma_f32_16x16x32_bf16 v[22:25], v[178:181], v[210:213], v[22:25]
	v_mfma_f32_16x16x32_bf16 v[18:21], v[186:189], v[210:213], v[18:21]
	v_mfma_f32_16x16x32_bf16 v[6:9], v[178:181], v[218:221], v[6:9]
	v_mfma_f32_16x16x32_bf16 v[2:5], v[186:189], v[218:221], v[2:5]
	s_barrier
	s_add_i32 s64, 0, 0x18000
	s_add_i32 s65, 0, 0x1c000
	v_add_u32_e32 v158, s64, v147
	v_add_u32_e32 v186, s65, v147
	ds_read_b128 v[140:143], v158
	ds_read_b128 v[150:153], v158 offset:1024
	ds_read_b128 v[154:157], v158 offset:2048
	ds_read_b128 v[158:161], v158 offset:3072
	ds_read_b128 v[174:177], v186
	ds_read_b128 v[178:181], v186 offset:1024
	ds_read_b128 v[182:185], v186 offset:2048
	ds_read_b128 v[186:189], v186 offset:3072
	s_add_u32 s12, s46, 0x158000
	s_addc_u32 s13, s47, 0
	s_mov_b32 m0, s55
	v_lshl_add_u64 v[228:229], s[12:13], 0, v[130:131]
	ds_read_b128 v[190:193], v149 offset:32768
	ds_read_b128 v[194:197], v149 offset:33792
	ds_read_b128 v[198:201], v149 offset:34816
	ds_read_b128 v[202:205], v149 offset:35840
	ds_read_b128 v[206:209], v149 offset:36864
	ds_read_b128 v[210:213], v149 offset:37888
	ds_read_b128 v[214:217], v149 offset:38912
	ds_read_b128 v[218:221], v149 offset:39936
	global_load_lds_dwordx4 v[228:229], off
	v_lshl_add_u64 v[228:229], s[12:13], 0, v[132:133]
	s_mov_b32 m0, s56
	s_nop 0
	global_load_lds_dwordx4 v[228:229], off
	s_waitcnt vmcnt(8)
	s_waitcnt lgkmcnt(0)
	s_barrier
	s_waitcnt lgkmcnt(0)
	v_mfma_f32_16x16x32_bf16 v[126:129], v[140:143], v[190:193], v[126:129]
	v_mfma_f32_16x16x32_bf16 v[122:125], v[154:157], v[190:193], v[122:125]
	v_mfma_f32_16x16x32_bf16 v[110:113], v[140:143], v[198:201], v[110:113]
	v_mfma_f32_16x16x32_bf16 v[106:109], v[154:157], v[198:201], v[106:109]
	v_mfma_f32_16x16x32_bf16 v[94:97], v[140:143], v[206:209], v[94:97]
	v_mfma_f32_16x16x32_bf16 v[90:93], v[154:157], v[206:209], v[90:93]
	v_mfma_f32_16x16x32_bf16 v[78:81], v[140:143], v[214:217], v[78:81]
	v_mfma_f32_16x16x32_bf16 v[74:77], v[154:157], v[214:217], v[74:77]
	v_mfma_f32_16x16x32_bf16 v[126:129], v[150:153], v[194:197], v[126:129]
	v_mfma_f32_16x16x32_bf16 v[122:125], v[158:161], v[194:197], v[122:125]
	v_mfma_f32_16x16x32_bf16 v[110:113], v[150:153], v[202:205], v[110:113]
	v_mfma_f32_16x16x32_bf16 v[106:109], v[158:161], v[202:205], v[106:109]
	v_mfma_f32_16x16x32_bf16 v[94:97], v[150:153], v[210:213], v[94:97]
	v_mfma_f32_16x16x32_bf16 v[90:93], v[158:161], v[210:213], v[90:93]
	v_mfma_f32_16x16x32_bf16 v[78:81], v[150:153], v[218:221], v[78:81]
	v_mfma_f32_16x16x32_bf16 v[74:77], v[158:161], v[218:221], v[74:77]
	v_mfma_f32_16x16x32_bf16 v[118:121], v[174:177], v[190:193], v[118:121]
	v_mfma_f32_16x16x32_bf16 v[114:117], v[182:185], v[190:193], v[114:117]
	v_mfma_f32_16x16x32_bf16 v[102:105], v[174:177], v[198:201], v[102:105]
	v_mfma_f32_16x16x32_bf16 v[98:101], v[182:185], v[198:201], v[98:101]
	v_mfma_f32_16x16x32_bf16 v[86:89], v[174:177], v[206:209], v[86:89]
	v_mfma_f32_16x16x32_bf16 v[82:85], v[182:185], v[206:209], v[82:85]
	v_mfma_f32_16x16x32_bf16 v[70:73], v[174:177], v[214:217], v[70:73]
	v_mfma_f32_16x16x32_bf16 v[66:69], v[182:185], v[214:217], v[66:69]
	v_mfma_f32_16x16x32_bf16 v[118:121], v[178:181], v[194:197], v[118:121]
	v_mfma_f32_16x16x32_bf16 v[114:117], v[186:189], v[194:197], v[114:117]
	v_mfma_f32_16x16x32_bf16 v[102:105], v[178:181], v[202:205], v[102:105]
	v_mfma_f32_16x16x32_bf16 v[98:101], v[186:189], v[202:205], v[98:101]
	v_mfma_f32_16x16x32_bf16 v[86:89], v[178:181], v[210:213], v[86:89]
	v_mfma_f32_16x16x32_bf16 v[82:85], v[186:189], v[210:213], v[82:85]
	v_mfma_f32_16x16x32_bf16 v[70:73], v[178:181], v[218:221], v[70:73]
	v_mfma_f32_16x16x32_bf16 v[66:69], v[186:189], v[218:221], v[66:69]
	s_barrier
; __device__ __forceinline__ float bf_lo(unsigned w) { return __uint_as_float(w << 16); }
; __device__ __forceinline__ float bf_hi(unsigned w) { return __uint_as_float(w & 0xffff0000u); }
; __device__ __forceinline__ u32x4 pack8(f32x4 a, f32x4 b) { u32x4 w; w.x = cvt_pk_bf16(a[0], a[1]); w.y = cvt_pk_bf16(a[2], a[3]); w.z = cvt_pk_bf16(b[0], b[1]); w.w = cvt_pk_bf16(b[2], b[3]); return w; }
; #define PG8_STAGE(bufoff, gbase, voff) do { _Pragma("unroll") for (int _i = 0; _i < 2; ++_i) \
;         __builtin_amdgcn_global_load_lds((const __attribute__((address_space(1))) unsigned*)((const char*)(gbase) + (voff)[_i]), (LAS unsigned*)(lds + (bufoff) + ldsw + _i * 8192), 16, 0, 0); } while (0)
; #define PG8_WAIT_V(n) asm volatile("s_waitcnt vmcnt(" #n ")" ::: "memory")
; template <class Epi, class SchedT, bool ALIGN_EPI, bool SP2>
; __device__ __forceinline__ void gemm_phase(LAS unsigned char* lds, const int ldk, const int nt, const SchedT& S, const Epi& E) {
;     ...
;             PG8_LDA(At, 1, 1); PG8_STAGE(PG8_SB(1, 0), b3, voffB); PG8_STAGE(PG8_SB(1, 1), b3 + hstepB, voffB); PG8_STAGE(PG8_SA(1, 0), a3, voffA);
;             PG8_WAIT_V(8); PG8_WAIT_L(0); PG8_BAR; PG8_MMA(1, 0, At, B0); PG8_MMA(1, 1, At, B1); PG8_BAR; PG8_SCHED;
;     __device__ __forceinline__ void operator()(f32x4 (&acc)[2][2][4][2], const Unit& u, int wr, int wc, int fr, int fq) const {
;         const int row0 = u.pm * BM + wr * 64 + fr, col0 = u.pn * BM + wc * 64 + 8 * fq;
; #pragma unroll
;         for (int ai = 0; ai < 2; ++ai)
; #pragma unroll
;             for (int m = 0; m < 4; ++m) {
;                 const int row = row0 + ai * HALF + m * 16; float sq = 0.f;
; #pragma unroll
;                 for (int bj = 0; bj < 2; ++bj) {
;                     const size_t off = (size_t)row * D + col0 + bj * 32;
;                     const u32x4 xw = *(const u32x4*)(xin + off);
;                     const f32x4 v0 = acc[ai][bj][m][0] + (f32x4){bf_lo(xw.x), bf_hi(xw.x), bf_lo(xw.y), bf_hi(xw.y)}, v1 = acc[ai][bj][m][1] + (f32x4){bf_lo(xw.z), bf_hi(xw.z), bf_lo(xw.w), bf_hi(xw.w)};
;                     *(u32x4*)(xb + off) = pack8(v0, v1);
;                     sq += (v0[0] * v0[0] + v0[1] * v0[1]) + (v0[2] * v0[2] + v0[3] * v0[3]) + (v1[0] * v1[0] + v1[1] * v1[1]) + (v1[2] * v1[2] + v1[3] * v1[3]);
;                 }
;                 sq += __shfl_xor(sq, 16); sq += __shfl_xor(sq, 32);
	s_add_i32 s12, s64, s52
	v_lshl_add_u64 v[144:145], v[144:145], 0, s[24:25]
	s_mov_b32 m0, s12
	ds_read_b128 v[190:193], v149 offset:49152
	ds_read_b128 v[194:197], v149 offset:50176
	ds_read_b128 v[198:201], v149 offset:51200
	ds_read_b128 v[202:205], v149 offset:52224
	ds_read_b128 v[206:209], v149 offset:53248
	ds_read_b128 v[210:213], v149 offset:54272
	ds_read_b128 v[214:217], v149 offset:55296
	ds_read_b128 v[218:221], v149 offset:56320
	global_load_lds_dwordx4 v[144:145], off
	s_add_i32 m0, s12, 0x2000
	s_add_u32 s12, s44, 0x56080
	v_lshl_add_u64 v[144:145], v[222:223], 0, s[24:25]
	s_addc_u32 s13, s45, 0
	s_add_i32 s44, s65, s52
	global_load_lds_dwordx4 v[144:145], off
	v_lshl_add_u64 v[144:145], s[12:13], 0, v[0:1]
	s_mov_b32 m0, s44
	s_nop 0
	global_load_lds_dwordx4 v[144:145], off
	v_lshl_add_u64 v[144:145], s[12:13], 0, v[134:135]
	s_add_i32 m0, s44, 0x2000
	s_nop 0
	global_load_lds_dwordx4 v[144:145], off
	v_lshl_add_u64 v[144:145], v[224:225], 0, s[24:25]
	s_mov_b32 m0, s58
	s_nop 0
	global_load_lds_dwordx4 v[144:145], off
	v_lshl_add_u64 v[144:145], v[226:227], 0, s[24:25]
	s_mov_b32 m0, s59
	s_nop 0
	global_load_lds_dwordx4 v[144:145], off
	s_waitcnt vmcnt(8)
	s_waitcnt lgkmcnt(0)
	s_barrier
	s_waitcnt lgkmcnt(0)
	v_mfma_f32_16x16x32_bf16 v[62:65], v[140:143], v[190:193], v[62:65]
	v_mfma_f32_16x16x32_bf16 v[58:61], v[154:157], v[190:193], v[58:61]
	v_mfma_f32_16x16x32_bf16 v[46:49], v[140:143], v[198:201], v[46:49]
	v_mfma_f32_16x16x32_bf16 v[42:45], v[154:157], v[198:201], v[42:45]
	v_mfma_f32_16x16x32_bf16 v[30:33], v[140:143], v[206:209], v[30:33]
	v_mfma_f32_16x16x32_bf16 v[26:29], v[154:157], v[206:209], v[26:29]
	v_mfma_f32_16x16x32_bf16 v[14:17], v[140:143], v[214:217], v[14:17]
	v_mfma_f32_16x16x32_bf16 v[10:13], v[154:157], v[214:217], v[10:13]
	v_mfma_f32_16x16x32_bf16 v[62:65], v[150:153], v[194:197], v[62:65]
	v_mfma_f32_16x16x32_bf16 v[58:61], v[158:161], v[194:197], v[58:61]
	v_mfma_f32_16x16x32_bf16 v[46:49], v[150:153], v[202:205], v[46:49]
	v_mfma_f32_16x16x32_bf16 v[42:45], v[158:161], v[202:205], v[42:45]
	v_mfma_f32_16x16x32_bf16 v[30:33], v[150:153], v[210:213], v[30:33]
	v_mfma_f32_16x16x32_bf16 v[26:29], v[158:161], v[210:213], v[26:29]
	v_mfma_f32_16x16x32_bf16 v[14:17], v[150:153], v[218:221], v[14:17]
	v_mfma_f32_16x16x32_bf16 v[10:13], v[158:161], v[218:221], v[10:13]
	v_mfma_f32_16x16x32_bf16 v[54:57], v[174:177], v[190:193], v[54:57]
	v_mfma_f32_16x16x32_bf16 v[50:53], v[182:185], v[190:193], v[50:53]
	v_mfma_f32_16x16x32_bf16 v[38:41], v[174:177], v[198:201], v[38:41]
	v_mfma_f32_16x16x32_bf16 v[34:37], v[182:185], v[198:201], v[34:37]
	v_mfma_f32_16x16x32_bf16 v[22:25], v[174:177], v[206:209], v[22:25]
	v_mfma_f32_16x16x32_bf16 v[18:21], v[182:185], v[206:209], v[18:21]
	v_mfma_f32_16x16x32_bf16 v[6:9], v[174:177], v[214:217], v[6:9]
	v_mfma_f32_16x16x32_bf16 v[2:5], v[182:185], v[214:217], v[2:5]
	v_mfma_f32_16x16x32_bf16 v[54:57], v[178:181], v[194:197], v[54:57]
	v_mfma_f32_16x16x32_bf16 v[50:53], v[186:189], v[194:197], v[50:53]
	v_mfma_f32_16x16x32_bf16 v[38:41], v[178:181], v[202:205], v[38:41]
	v_mfma_f32_16x16x32_bf16 v[34:37], v[186:189], v[202:205], v[34:37]
	v_mfma_f32_16x16x32_bf16 v[22:25], v[178:181], v[210:213], v[22:25]
	v_mfma_f32_16x16x32_bf16 v[18:21], v[186:189], v[210:213], v[18:21]
	v_mfma_f32_16x16x32_bf16 v[6:9], v[178:181], v[218:221], v[6:9]
	v_mfma_f32_16x16x32_bf16 v[2:5], v[186:189], v[218:221], v[2:5]
	s_barrier
	s_add_i32 s83, s83, 2
	s_add_u32 s81, s81, 0x100
	s_addc_u32 s82, s82, 0
	s_cmpk_gt_u32 s83, 0x53
	s_mov_b64 s[12:13], s[16:17]
	s_cbranch_scc0 .LBB0_948
	v_lshl_add_u32 v142, s63, 8, v146
	v_lshl_or_b32 v140, s22, 8, v148
	v_lshlrev_b32_e32 v141, 12, v142
	v_lshl_add_u32 v150, v140, 1, v141
	v_add_u32_e32 v151, 0x10000, v150
	v_add_u32_e32 v152, 0x20000, v150
	v_add_u32_e32 v153, 0x30000, v150
	v_add_u32_e32 v154, 0x80000, v150
	v_add_u32_e32 v155, 0x90000, v150
	v_add_u32_e32 v156, 0xa0000, v150
	v_add_u32_e32 v157, 0xb0000, v150
	global_load_dwordx4 v[174:177], v150, s[20:21]
	global_load_dwordx4 v[178:181], v150, s[20:21] offset:64
	global_load_dwordx4 v[182:185], v151, s[20:21]
	global_load_dwordx4 v[186:189], v151, s[20:21] offset:64
	global_load_dwordx4 v[190:193], v152, s[20:21]
	global_load_dwordx4 v[194:197], v152, s[20:21] offset:64
	global_load_dwordx4 v[198:201], v153, s[20:21]
	global_load_dwordx4 v[202:205], v153, s[20:21] offset:64
	global_load_dwordx4 v[206:209], v154, s[20:21]
	global_load_dwordx4 v[210:213], v154, s[20:21] offset:64
	global_load_dwordx4 v[214:217], v155, s[20:21]
	global_load_dwordx4 v[218:221], v155, s[20:21] offset:64
	global_load_dwordx4 v[222:225], v156, s[20:21]
	global_load_dwordx4 v[226:229], v156, s[20:21] offset:64
	global_load_dwordx4 v[230:233], v157, s[20:21]
	global_load_dwordx4 v[234:237], v157, s[20:21] offset:64
	s_lshl_b32 s44, s22, 4
	s_lshl_b32 s45, s57, 2
	s_add_i32 s44, s44, s45
	v_lshl_add_u32 v158, v142, 7, s44
	v_add_u32_e32 v159, 0x1000, v158
	v_add_u32_e32 v160, 0x4000, v158
	v_add_u32_e32 v161, 0x5000, v158
	v_xor_b32_e32 v239, 16, v241
	v_xor_b32_e32 v252, 32, v241
	v_lshlrev_b32_e32 v239, 2, v239
	v_lshlrev_b32_e32 v252, 2, v252
	s_and_b64 vcc, exec, s[40:41]
	s_cbranch_vccz .LBB0_951
	s_barrier
